# static s_setprio 1 for waves 4-7 for the whole kernel, all per-segment priority flips in the GEMM K-loops deleted (docs 7.4)
# speedup vs baseline: 1.0219x; 1.0219x over previous
_Z10fwd_kernel4Args:
	s_load_dword s97, s[0:1], 0xa0
	s_mov_b32 s8, s2
	s_add_u32 s2, s0, 0xa0
	s_addc_u32 s3, s1, 0
	v_lshl_add_u32 v1, v0, 2, 0
	v_writelane_b32 v254, s2, 0
	v_add_u32_e32 v1, 0x20000, v1
	v_mov_b32_e32 v2, 0
	v_readfirstlane_b32 s9, v0
	v_writelane_b32 v254, s3, 1
	ds_write2st64_b32 v1, v2, v2 offset1:8
	ds_write2st64_b32 v1, v2, v2 offset0:16 offset1:24
	v_or_b32_e32 v1, 0x800, v0
	s_mov_b64 s[2:3], -1
	s_and_saveexec_b64 s[4:5], s[2:3]
	v_lshl_add_u32 v3, v1, 2, 0
	v_add_u32_e32 v3, 0x20000, v3
	ds_write_b32 v3, v2
	s_or_b64 exec, exec, s[4:5]
	s_and_saveexec_b64 s[4:5], s[2:3]
	s_add_i32 s2, 0, 0x20000
	v_lshl_add_u32 v1, v1, 2, s2
	v_mov_b32_e32 v2, 0
	ds_write_b32 v1, v2 offset:2048
	s_or_b64 exec, exec, s[4:5]
	v_or_b32_e32 v1, 0xc00, v0
	v_cmp_gt_u32_e64 s[2:3], 7, 6
	v_cmp_gt_u32_e64 s[6:7], 7, 5
	s_and_saveexec_b64 s[4:5], s[6:7]
	v_lshl_add_u32 v2, v1, 2, 0
	v_add_u32_e32 v2, 0x20000, v2
	v_mov_b32_e32 v3, 0
	ds_write_b32 v2, v3
	s_or_b64 exec, exec, s[4:5]
	s_load_dwordx8 s[88:95], s[0:1], 0x80
	s_and_saveexec_b64 s[4:5], s[2:3]
	s_add_i32 s2, 0, 0x20000
	v_lshl_add_u32 v1, v1, 2, s2
	v_mov_b32_e32 v2, 0
	ds_write_b32 v1, v2 offset:2048
	s_or_b64 exec, exec, s[4:5]
	s_load_dwordx16 s[12:27], s[0:1], 0x0
	s_waitcnt lgkmcnt(0)
	s_barrier
	s_cmp_ge_u32 s9, 0x100
	s_cbranch_scc0 .Lmy_prio_done
	s_setprio 1
.Lmy_prio_done:
	s_mov_b32 s4, 0
	v_writelane_b32 v254, s12, 2
	v_cmp_eq_u32_e64 s[2:3], 0, v0
	s_nop 0
	v_writelane_b32 v254, s13, 3
	v_writelane_b32 v254, s14, 4
	v_writelane_b32 v254, s15, 5
	v_writelane_b32 v254, s16, 6
	v_writelane_b32 v254, s17, 7
	v_writelane_b32 v254, s18, 8
	v_writelane_b32 v254, s19, 9
	v_writelane_b32 v254, s20, 10
	v_writelane_b32 v254, s21, 11
	v_writelane_b32 v254, s22, 12
	v_writelane_b32 v254, s23, 13
	v_writelane_b32 v254, s24, 14
	v_writelane_b32 v254, s25, 15
	v_writelane_b32 v254, s26, 16
	v_writelane_b32 v254, s27, 17
	s_load_dwordx16 s[12:27], s[0:1], 0x40
	s_add_u32 s0, s94, 0x4000
	s_addc_u32 s1, s95, 0
	s_waitcnt lgkmcnt(0)
	v_writelane_b32 v254, s12, 18
	s_nop 1
	v_writelane_b32 v254, s13, 19
	v_writelane_b32 v254, s14, 20
	v_writelane_b32 v254, s15, 21
	v_writelane_b32 v254, s16, 22
	v_writelane_b32 v254, s17, 23
	v_writelane_b32 v254, s18, 24
	v_writelane_b32 v254, s19, 25
	v_writelane_b32 v254, s20, 26
	v_writelane_b32 v254, s21, 27
	v_writelane_b32 v254, s22, 28
	v_writelane_b32 v254, s23, 29
	v_writelane_b32 v254, s24, 30
	v_writelane_b32 v254, s25, 31
	v_writelane_b32 v254, s26, 32
	v_writelane_b32 v254, s27, 33
	v_writelane_b32 v254, s0, 34
	s_nop 1
	v_writelane_b32 v254, s1, 35
	s_getreg_b32 s0, hwreg(HW_REG_XCC_ID, 0, 4)
	s_and_b32 s0, s0, 15
	v_writelane_b32 v254, s0, 36
	s_mov_b64 s[0:1], exec
	v_writelane_b32 v254, s2, 37
	s_nop 1
	v_writelane_b32 v254, s3, 38
	s_and_b64 s[2:3], s[0:1], s[2:3]
	s_mov_b64 exec, s[2:3]
	s_cbranch_execz .LBB0_11
	s_mov_b64 s[2:3], exec
	v_mbcnt_lo_u32_b32 v1, s2, 0
	v_mbcnt_hi_u32_b32 v1, s3, v1
	v_cmp_eq_u32_e32 vcc, 0, v1
	s_and_b64 s[6:7], exec, vcc
	s_mov_b64 exec, s[6:7]
	s_cbranch_execz .LBB0_11
	v_readlane_b32 s5, v254, 36
	s_bcnt1_i32_b64 s2, s[2:3]
	s_lshl_b32 s5, s5, 8
	v_mov_b32_e32 v2, s2
	v_readlane_b32 s2, v254, 34
	v_mov_b32_e32 v1, s5
	v_readlane_b32 s3, v254, 35
	s_nop 4
	global_atomic_add v1, v2, s[2:3] offset:1024

.LBB0_308:
	ds_read_b128 v[142:145], v191
	ds_read_b128 v[138:141], v191 offset:1024
	ds_read_b128 v[134:137], v191 offset:2048
	ds_read_b128 v[130:133], v191 offset:3072
	s_add_u32 s46, s44, 0xfff80080
	s_addc_u32 s47, s45, -1
	s_cmp_eq_u32 s37, 28
	s_cselect_b32 s49, s0, s47
	s_cselect_b32 s48, s1, s46
	s_cselect_b32 s47, s7, s31
	s_cselect_b32 s46, s14, s15
	v_lshl_add_u64 v[166:167], s[44:45], 0, v[162:163]
	s_add_i32 m0, s9, 0xc000
	ds_read_b128 v[170:173], v192
	ds_read_b128 v[174:177], v192 offset:1024
	s_waitcnt lgkmcnt(0)
	ds_read_b128 v[178:181], v192 offset:2048
	ds_read_b128 v[182:185], v192 offset:3072
	ds_read_b128 v[204:207], v192 offset:4096
	ds_read_b128 v[208:211], v192 offset:5120
	ds_read_b128 v[212:215], v192 offset:6144
	ds_read_b128 v[216:219], v192 offset:7168
	global_load_lds_dwordx4 v[166:167], off
	v_lshl_add_u64 v[166:167], s[44:45], 0, v[164:165]
	s_add_i32 m0, s9, 0xe000
	s_nop 0
	global_load_lds_dwordx4 v[166:167], off
	s_waitcnt lgkmcnt(8)
	s_barrier
	s_waitcnt lgkmcnt(0)
	s_waitcnt lgkmcnt(0)
	v_mfma_i32_16x16x64_i8 v[126:129], v[142:145], v[170:173], v[126:129]
	s_nop 0
	v_mfma_i32_16x16x64_i8 v[126:129], v[138:141], v[174:177], v[126:129]
	v_mfma_i32_16x16x64_i8 v[122:125], v[134:137], v[170:173], v[122:125]
	s_nop 0
	v_mfma_i32_16x16x64_i8 v[122:125], v[130:133], v[174:177], v[122:125]
	v_mfma_i32_16x16x64_i8 v[110:113], v[142:145], v[178:181], v[110:113]
	s_nop 0
	v_mfma_i32_16x16x64_i8 v[110:113], v[138:141], v[182:185], v[110:113]
	v_mfma_i32_16x16x64_i8 v[106:109], v[134:137], v[178:181], v[106:109]
	s_nop 0
	v_mfma_i32_16x16x64_i8 v[106:109], v[130:133], v[182:185], v[106:109]
	v_mfma_i32_16x16x64_i8 v[94:97], v[142:145], v[204:207], v[94:97]
	s_nop 0
	v_mfma_i32_16x16x64_i8 v[94:97], v[138:141], v[208:211], v[94:97]
	v_mfma_i32_16x16x64_i8 v[90:93], v[134:137], v[204:207], v[90:93]
	s_nop 0
	v_mfma_i32_16x16x64_i8 v[90:93], v[130:133], v[208:211], v[90:93]
	v_mfma_i32_16x16x64_i8 v[78:81], v[142:145], v[212:215], v[78:81]
	s_nop 0
	v_mfma_i32_16x16x64_i8 v[78:81], v[138:141], v[216:219], v[78:81]
	v_mfma_i32_16x16x64_i8 v[74:77], v[134:137], v[212:215], v[74:77]
	s_nop 0
	v_mfma_i32_16x16x64_i8 v[74:77], v[130:133], v[216:219], v[74:77]
	s_barrier
	s_add_i32 s50, s55, s8
	v_lshl_add_u64 v[166:167], s[46:47], 0, v[148:149]
	s_mov_b32 m0, s50
	ds_read_b128 v[220:223], v193
	ds_read_b128 v[224:227], v193 offset:1024
	ds_read_b128 v[234:237], v193 offset:2048
	ds_read_b128 v[238:241], v193 offset:3072
	global_load_lds_dwordx4 v[166:167], off
	v_lshl_add_u64 v[168:169], s[46:47], 0, v[152:153]
	s_add_i32 m0, s50, 0x2000
	s_nop 0
	global_load_lds_dwordx4 v[168:169], off
	s_barrier
	s_waitcnt lgkmcnt(0)
	s_waitcnt lgkmcnt(0)
	v_mfma_i32_16x16x64_i8 v[118:121], v[220:223], v[170:173], v[118:121]
	s_nop 0
	v_mfma_i32_16x16x64_i8 v[118:121], v[224:227], v[174:177], v[118:121]
	v_mfma_i32_16x16x64_i8 v[114:117], v[234:237], v[170:173], v[114:117]
	s_nop 0
	v_mfma_i32_16x16x64_i8 v[114:117], v[238:241], v[174:177], v[114:117]
	v_mfma_i32_16x16x64_i8 v[102:105], v[220:223], v[178:181], v[102:105]
	s_nop 0
	v_mfma_i32_16x16x64_i8 v[102:105], v[224:227], v[182:185], v[102:105]
	v_mfma_i32_16x16x64_i8 v[98:101], v[234:237], v[178:181], v[98:101]
	s_nop 0
	v_mfma_i32_16x16x64_i8 v[98:101], v[238:241], v[182:185], v[98:101]
	v_mfma_i32_16x16x64_i8 v[86:89], v[220:223], v[204:207], v[86:89]
	s_nop 0
	v_mfma_i32_16x16x64_i8 v[86:89], v[224:227], v[208:211], v[86:89]
	v_mfma_i32_16x16x64_i8 v[82:85], v[234:237], v[204:207], v[82:85]
	s_nop 0
	v_mfma_i32_16x16x64_i8 v[82:85], v[238:241], v[208:211], v[82:85]
	v_mfma_i32_16x16x64_i8 v[70:73], v[220:223], v[212:215], v[70:73]
	s_nop 0
	v_mfma_i32_16x16x64_i8 v[70:73], v[224:227], v[216:219], v[70:73]
	v_mfma_i32_16x16x64_i8 v[66:69], v[234:237], v[212:215], v[66:69]
	s_nop 0
	v_mfma_i32_16x16x64_i8 v[66:69], v[238:241], v[216:219], v[66:69]
	s_mov_b32 m0, s9
	v_lshl_add_u64 v[170:171], s[48:49], 0, v[146:147]
	s_barrier
	ds_read_b128 v[174:177], v192 offset:16384
	ds_read_b128 v[178:181], v192 offset:17408
	ds_read_b128 v[182:185], v192 offset:18432
	ds_read_b128 v[204:207], v192 offset:19456
	ds_read_b128 v[208:211], v192 offset:20480
	ds_read_b128 v[212:215], v192 offset:21504
	ds_read_b128 v[216:219], v192 offset:22528
	ds_read_b128 v[242:245], v192 offset:23552
	global_load_lds_dwordx4 v[170:171], off
	v_lshl_add_u64 v[172:173], s[48:49], 0, v[150:151]
	s_mov_b32 m0, s13
	s_nop 0
	global_load_lds_dwordx4 v[172:173], off
	s_barrier
	s_waitcnt lgkmcnt(0)
	s_waitcnt lgkmcnt(0)
	v_mfma_i32_16x16x64_i8 v[62:65], v[142:145], v[174:177], v[62:65]
	s_nop 0
	v_mfma_i32_16x16x64_i8 v[62:65], v[138:141], v[178:181], v[62:65]
	v_mfma_i32_16x16x64_i8 v[58:61], v[134:137], v[174:177], v[58:61]
	s_nop 0
	v_mfma_i32_16x16x64_i8 v[58:61], v[130:133], v[178:181], v[58:61]
	v_mfma_i32_16x16x64_i8 v[46:49], v[142:145], v[182:185], v[46:49]
	s_nop 0
	v_mfma_i32_16x16x64_i8 v[46:49], v[138:141], v[204:207], v[46:49]
	v_mfma_i32_16x16x64_i8 v[42:45], v[134:137], v[182:185], v[42:45]
	s_nop 0
	v_mfma_i32_16x16x64_i8 v[42:45], v[130:133], v[204:207], v[42:45]
	v_mfma_i32_16x16x64_i8 v[30:33], v[142:145], v[208:211], v[30:33]
	s_nop 0
	v_mfma_i32_16x16x64_i8 v[30:33], v[138:141], v[212:215], v[30:33]
	v_mfma_i32_16x16x64_i8 v[26:29], v[134:137], v[208:211], v[26:29]
	s_nop 0
	v_mfma_i32_16x16x64_i8 v[26:29], v[130:133], v[212:215], v[26:29]
	v_mfma_i32_16x16x64_i8 v[14:17], v[142:145], v[216:219], v[14:17]
	s_nop 0
	v_mfma_i32_16x16x64_i8 v[14:17], v[138:141], v[242:245], v[14:17]
	v_mfma_i32_16x16x64_i8 v[10:13], v[134:137], v[216:219], v[10:13]
	s_nop 0
	v_mfma_i32_16x16x64_i8 v[10:13], v[130:133], v[242:245], v[10:13]
	s_barrier
	s_add_u32 s50, s46, 0x80000
	s_addc_u32 s51, s47, 0
	s_add_i32 s59, s56, s8
	v_lshl_add_u64 v[130:131], s[50:51], 0, v[148:149]
	s_mov_b32 m0, s59
	s_nop 0
	global_load_lds_dwordx4 v[130:131], off
	v_lshl_add_u64 v[130:131], s[50:51], 0, v[152:153]
	s_add_i32 m0, s59, 0x2000
	s_nop 0
	global_load_lds_dwordx4 v[130:131], off
	s_waitcnt vmcnt(6)
	s_barrier
	v_mfma_i32_16x16x64_i8 v[54:57], v[220:223], v[174:177], v[54:57]
	s_nop 0
	v_mfma_i32_16x16x64_i8 v[54:57], v[224:227], v[178:181], v[54:57]
	v_mfma_i32_16x16x64_i8 v[50:53], v[234:237], v[174:177], v[50:53]
	s_nop 0
	v_mfma_i32_16x16x64_i8 v[50:53], v[238:241], v[178:181], v[50:53]
	v_mfma_i32_16x16x64_i8 v[38:41], v[220:223], v[182:185], v[38:41]
	s_nop 0
	v_mfma_i32_16x16x64_i8 v[38:41], v[224:227], v[204:207], v[38:41]
	v_mfma_i32_16x16x64_i8 v[34:37], v[234:237], v[182:185], v[34:37]
	s_nop 0
	v_mfma_i32_16x16x64_i8 v[34:37], v[238:241], v[204:207], v[34:37]
	v_mfma_i32_16x16x64_i8 v[22:25], v[220:223], v[208:211], v[22:25]
	s_nop 0
	v_mfma_i32_16x16x64_i8 v[22:25], v[224:227], v[212:215], v[22:25]
	v_mfma_i32_16x16x64_i8 v[18:21], v[234:237], v[208:211], v[18:21]
	s_nop 0
	v_mfma_i32_16x16x64_i8 v[18:21], v[238:241], v[212:215], v[18:21]
	v_mfma_i32_16x16x64_i8 v[6:9], v[220:223], v[216:219], v[6:9]
	s_nop 0
	v_mfma_i32_16x16x64_i8 v[6:9], v[224:227], v[242:245], v[6:9]
	v_mfma_i32_16x16x64_i8 v[2:5], v[234:237], v[216:219], v[2:5]
	s_nop 0
	v_mfma_i32_16x16x64_i8 v[2:5], v[238:241], v[242:245], v[2:5]
	s_add_i32 s50, 0, 0x18000
	v_add_u32_e32 v142, s50, v188
	s_barrier
	ds_read_b128 v[130:133], v142
	ds_read_b128 v[134:137], v142 offset:1024
	ds_read_b128 v[138:141], v142 offset:2048
	ds_read_b128 v[142:145], v142 offset:3072
	s_add_u32 s48, s48, 0x80000
	s_addc_u32 s49, s49, 0
	s_mov_b32 m0, s29
	v_lshl_add_u64 v[186:187], s[48:49], 0, v[146:147]
	ds_read_b128 v[174:177], v192 offset:32768
	ds_read_b128 v[178:181], v192 offset:33792
	ds_read_b128 v[182:185], v192 offset:34816
	ds_read_b128 v[204:207], v192 offset:35840
	ds_read_b128 v[208:211], v192 offset:36864
	ds_read_b128 v[212:215], v192 offset:37888
	ds_read_b128 v[216:219], v192 offset:38912
	ds_read_b128 v[220:223], v192 offset:39936
	global_load_lds_dwordx4 v[186:187], off
	v_lshl_add_u64 v[186:187], s[48:49], 0, v[150:151]
	s_mov_b32 m0, s33
	s_nop 0
	global_load_lds_dwordx4 v[186:187], off
	s_waitcnt lgkmcnt(8)
	s_barrier
	s_waitcnt lgkmcnt(0)
	s_waitcnt lgkmcnt(0)
	v_mfma_i32_16x16x64_i8 v[126:129], v[130:133], v[174:177], v[126:129]
	s_nop 0
	v_mfma_i32_16x16x64_i8 v[126:129], v[134:137], v[178:181], v[126:129]
	v_mfma_i32_16x16x64_i8 v[122:125], v[138:141], v[174:177], v[122:125]
	s_nop 0
	v_mfma_i32_16x16x64_i8 v[122:125], v[142:145], v[178:181], v[122:125]
	v_mfma_i32_16x16x64_i8 v[110:113], v[130:133], v[182:185], v[110:113]
	s_nop 0
	v_mfma_i32_16x16x64_i8 v[110:113], v[134:137], v[204:207], v[110:113]
	v_mfma_i32_16x16x64_i8 v[106:109], v[138:141], v[182:185], v[106:109]
	s_nop 0
	v_mfma_i32_16x16x64_i8 v[106:109], v[142:145], v[204:207], v[106:109]
	v_mfma_i32_16x16x64_i8 v[94:97], v[130:133], v[208:211], v[94:97]
	s_nop 0
	v_mfma_i32_16x16x64_i8 v[94:97], v[134:137], v[212:215], v[94:97]
	v_mfma_i32_16x16x64_i8 v[90:93], v[138:141], v[208:211], v[90:93]
	s_nop 0
	v_mfma_i32_16x16x64_i8 v[90:93], v[142:145], v[212:215], v[90:93]
	v_mfma_i32_16x16x64_i8 v[78:81], v[130:133], v[216:219], v[78:81]
	s_nop 0
	v_mfma_i32_16x16x64_i8 v[78:81], v[134:137], v[220:223], v[78:81]
	v_mfma_i32_16x16x64_i8 v[74:77], v[138:141], v[216:219], v[74:77]
	s_nop 0
	v_mfma_i32_16x16x64_i8 v[74:77], v[142:145], v[220:223], v[74:77]
	s_barrier
	s_add_i32 s48, 0, 0x1c000
	s_add_i32 s49, s50, s8
	v_add_u32_e32 v156, s48, v188
	v_lshl_add_u64 v[166:167], v[166:167], 0, s[22:23]
	s_mov_b32 m0, s49
	ds_read_b128 v[224:227], v156
	ds_read_b128 v[234:237], v156 offset:1024
	ds_read_b128 v[238:241], v156 offset:2048
	ds_read_b128 v[242:245], v156 offset:3072
	global_load_lds_dwordx4 v[166:167], off
	v_lshl_add_u64 v[166:167], v[168:169], 0, s[22:23]
	s_add_i32 m0, s49, 0x2000
	s_nop 0
	global_load_lds_dwordx4 v[166:167], off
	s_barrier
	s_waitcnt lgkmcnt(0)
	s_waitcnt lgkmcnt(0)
	v_mfma_i32_16x16x64_i8 v[118:121], v[224:227], v[174:177], v[118:121]
	s_nop 0
	v_mfma_i32_16x16x64_i8 v[118:121], v[234:237], v[178:181], v[118:121]
	v_mfma_i32_16x16x64_i8 v[114:117], v[238:241], v[174:177], v[114:117]
	s_nop 0
	v_mfma_i32_16x16x64_i8 v[114:117], v[242:245], v[178:181], v[114:117]
	v_mfma_i32_16x16x64_i8 v[102:105], v[224:227], v[182:185], v[102:105]
	s_nop 0
	v_mfma_i32_16x16x64_i8 v[102:105], v[234:237], v[204:207], v[102:105]
	v_mfma_i32_16x16x64_i8 v[98:101], v[238:241], v[182:185], v[98:101]
	s_nop 0
	v_mfma_i32_16x16x64_i8 v[98:101], v[242:245], v[204:207], v[98:101]
	v_mfma_i32_16x16x64_i8 v[86:89], v[224:227], v[208:211], v[86:89]
	s_nop 0
	v_mfma_i32_16x16x64_i8 v[86:89], v[234:237], v[212:215], v[86:89]
	v_mfma_i32_16x16x64_i8 v[82:85], v[238:241], v[208:211], v[82:85]
	s_nop 0
	v_mfma_i32_16x16x64_i8 v[82:85], v[242:245], v[212:215], v[82:85]
	v_mfma_i32_16x16x64_i8 v[70:73], v[224:227], v[216:219], v[70:73]
	s_nop 0
	v_mfma_i32_16x16x64_i8 v[70:73], v[234:237], v[220:223], v[70:73]
	v_mfma_i32_16x16x64_i8 v[66:69], v[238:241], v[216:219], v[66:69]
	s_nop 0
	v_mfma_i32_16x16x64_i8 v[66:69], v[242:245], v[220:223], v[66:69]
	s_mov_b32 m0, s53
	v_lshl_add_u64 v[170:171], v[170:171], 0, s[22:23]
	s_barrier
	ds_read_b128 v[166:169], v192 offset:49152
	ds_read_b128 v[174:177], v192 offset:50176
	ds_read_b128 v[178:181], v192 offset:51200
	ds_read_b128 v[182:185], v192 offset:52224
	ds_read_b128 v[204:207], v192 offset:53248
	ds_read_b128 v[208:211], v192 offset:54272
	ds_read_b128 v[212:215], v192 offset:55296
	ds_read_b128 v[216:219], v192 offset:56320
	global_load_lds_dwordx4 v[170:171], off
	v_lshl_add_u64 v[170:171], v[172:173], 0, s[22:23]
	s_mov_b32 m0, s54
	s_nop 0
	global_load_lds_dwordx4 v[170:171], off
	s_barrier
	s_waitcnt lgkmcnt(0)
	s_waitcnt lgkmcnt(0)
	v_mfma_i32_16x16x64_i8 v[62:65], v[130:133], v[166:169], v[62:65]
	s_nop 0
	v_mfma_i32_16x16x64_i8 v[62:65], v[134:137], v[174:177], v[62:65]
	v_mfma_i32_16x16x64_i8 v[58:61], v[138:141], v[166:169], v[58:61]
	s_nop 0
	v_mfma_i32_16x16x64_i8 v[58:61], v[142:145], v[174:177], v[58:61]
	v_mfma_i32_16x16x64_i8 v[46:49], v[130:133], v[178:181], v[46:49]
	s_nop 0
	v_mfma_i32_16x16x64_i8 v[46:49], v[134:137], v[182:185], v[46:49]
	v_mfma_i32_16x16x64_i8 v[42:45], v[138:141], v[178:181], v[42:45]
	s_nop 0
	v_mfma_i32_16x16x64_i8 v[42:45], v[142:145], v[182:185], v[42:45]
	v_mfma_i32_16x16x64_i8 v[30:33], v[130:133], v[204:207], v[30:33]
	s_nop 0
	v_mfma_i32_16x16x64_i8 v[30:33], v[134:137], v[208:211], v[30:33]
	v_mfma_i32_16x16x64_i8 v[26:29], v[138:141], v[204:207], v[26:29]
	s_nop 0
	v_mfma_i32_16x16x64_i8 v[26:29], v[142:145], v[208:211], v[26:29]
	v_mfma_i32_16x16x64_i8 v[14:17], v[130:133], v[212:215], v[14:17]
	s_nop 0
	v_mfma_i32_16x16x64_i8 v[14:17], v[134:137], v[216:219], v[14:17]
	v_mfma_i32_16x16x64_i8 v[10:13], v[138:141], v[212:215], v[10:13]
	s_nop 0
	v_mfma_i32_16x16x64_i8 v[10:13], v[142:145], v[216:219], v[10:13]
	s_barrier
	s_add_u32 s46, s46, 0x80080
	s_addc_u32 s47, s47, 0
	s_add_i32 s48, s48, s8
	v_lshl_add_u64 v[130:131], s[46:47], 0, v[148:149]
	s_mov_b32 m0, s48
	s_nop 0
	global_load_lds_dwordx4 v[130:131], off
	v_lshl_add_u64 v[130:131], s[46:47], 0, v[152:153]
	s_add_i32 m0, s48, 0x2000
	s_nop 0
	global_load_lds_dwordx4 v[130:131], off
	s_waitcnt vmcnt(6)
	s_barrier
	v_mfma_i32_16x16x64_i8 v[54:57], v[224:227], v[166:169], v[54:57]
	s_nop 0
	v_mfma_i32_16x16x64_i8 v[54:57], v[234:237], v[174:177], v[54:57]
	v_mfma_i32_16x16x64_i8 v[50:53], v[238:241], v[166:169], v[50:53]
	s_nop 0
	v_mfma_i32_16x16x64_i8 v[50:53], v[242:245], v[174:177], v[50:53]
	v_mfma_i32_16x16x64_i8 v[38:41], v[224:227], v[178:181], v[38:41]
	s_nop 0
	v_mfma_i32_16x16x64_i8 v[38:41], v[234:237], v[182:185], v[38:41]
	v_mfma_i32_16x16x64_i8 v[34:37], v[238:241], v[178:181], v[34:37]
	s_nop 0
	v_mfma_i32_16x16x64_i8 v[34:37], v[242:245], v[182:185], v[34:37]
	v_mfma_i32_16x16x64_i8 v[22:25], v[224:227], v[204:207], v[22:25]
	s_nop 0
	v_mfma_i32_16x16x64_i8 v[22:25], v[234:237], v[208:211], v[22:25]
	v_mfma_i32_16x16x64_i8 v[18:21], v[238:241], v[204:207], v[18:21]
	s_nop 0
	v_mfma_i32_16x16x64_i8 v[18:21], v[242:245], v[208:211], v[18:21]
	v_mfma_i32_16x16x64_i8 v[6:9], v[224:227], v[212:215], v[6:9]
	s_nop 0
	v_mfma_i32_16x16x64_i8 v[6:9], v[234:237], v[216:219], v[6:9]
	v_mfma_i32_16x16x64_i8 v[2:5], v[238:241], v[212:215], v[2:5]
	s_nop 0
	v_mfma_i32_16x16x64_i8 v[2:5], v[242:245], v[216:219], v[2:5]
	s_add_i32 s37, s37, 2
	s_add_u32 s44, s44, 0x100
	s_addc_u32 s45, s45, 0
	s_add_u32 s15, s15, 0x100
	s_addc_u32 s31, s31, 0
	s_cmp_gt_u32 s37, 29
	s_barrier
	s_cbranch_scc0 .LBB0_308
	s_nop 15
	s_nop 15
	s_and_b64 vcc, exec, s[24:25]
	s_cbranch_vccz .LBB0_311
	s_barrier

.LBB0_412:
	ds_read_b128 v[130:133], v191
	ds_read_b128 v[134:137], v191 offset:1024
	ds_read_b128 v[138:141], v191 offset:2048
	ds_read_b128 v[142:145], v191 offset:3072
	ds_read_b128 v[146:149], v192
	ds_read_b128 v[150:153], v192 offset:1024
	ds_read_b128 v[174:177], v192 offset:2048
	s_waitcnt lgkmcnt(0)
	ds_read_b128 v[178:181], v192 offset:3072
	s_add_u32 s42, s40, 0xfff00080
	s_addc_u32 s43, s41, -1
	s_cmp_eq_u32 s29, 60
	s_cselect_b32 s45, s0, s43
	s_cselect_b32 s44, s1, s42
	s_cselect_b32 s43, s7, s27
	s_cselect_b32 s42, s14, s15
	v_lshl_add_u64 v[186:187], s[40:41], 0, v[170:171]
	s_add_i32 m0, s9, 0xc000
	ds_read_b128 v[182:185], v193
	ds_read_b128 v[204:207], v193 offset:1024
	ds_read_b128 v[208:211], v193 offset:2048
	ds_read_b128 v[212:215], v193 offset:3072
	ds_read_b128 v[216:219], v193 offset:4096
	ds_read_b128 v[220:223], v193 offset:5120
	ds_read_b128 v[224:227], v193 offset:6144
	ds_read_b128 v[234:237], v193 offset:7168
	global_load_lds_dwordx4 v[186:187], off
	v_lshl_add_u64 v[186:187], s[40:41], 0, v[172:173]
	s_add_i32 m0, s9, 0xe000
	s_nop 0
	global_load_lds_dwordx4 v[186:187], off
	s_waitcnt vmcnt(8)
	s_waitcnt lgkmcnt(0)
	s_barrier
	s_waitcnt lgkmcnt(0)
	v_mfma_f32_16x16x32_bf16 v[126:129], v[130:133], v[182:185], v[126:129]
	v_mfma_f32_16x16x32_bf16 v[122:125], v[138:141], v[182:185], v[122:125]
	v_mfma_f32_16x16x32_bf16 v[118:121], v[130:133], v[208:211], v[118:121]
	v_mfma_f32_16x16x32_bf16 v[110:113], v[138:141], v[208:211], v[110:113]
	v_mfma_f32_16x16x32_bf16 v[102:105], v[130:133], v[216:219], v[102:105]
	v_mfma_f32_16x16x32_bf16 v[94:97], v[138:141], v[216:219], v[94:97]
	v_mfma_f32_16x16x32_bf16 v[86:89], v[130:133], v[224:227], v[86:89]
	v_mfma_f32_16x16x32_bf16 v[78:81], v[138:141], v[224:227], v[78:81]
	v_mfma_f32_16x16x32_bf16 v[126:129], v[134:137], v[204:207], v[126:129]
	v_mfma_f32_16x16x32_bf16 v[122:125], v[142:145], v[204:207], v[122:125]
	v_mfma_f32_16x16x32_bf16 v[118:121], v[134:137], v[212:215], v[118:121]
	v_mfma_f32_16x16x32_bf16 v[110:113], v[142:145], v[212:215], v[110:113]
	v_mfma_f32_16x16x32_bf16 v[102:105], v[134:137], v[220:223], v[102:105]
	v_mfma_f32_16x16x32_bf16 v[94:97], v[142:145], v[220:223], v[94:97]
	v_mfma_f32_16x16x32_bf16 v[86:89], v[134:137], v[234:237], v[86:89]
	v_mfma_f32_16x16x32_bf16 v[78:81], v[142:145], v[234:237], v[78:81]
	v_mfma_f32_16x16x32_bf16 v[114:117], v[146:149], v[182:185], v[114:117]
	v_mfma_f32_16x16x32_bf16 v[106:109], v[174:177], v[182:185], v[106:109]
	v_mfma_f32_16x16x32_bf16 v[98:101], v[146:149], v[208:211], v[98:101]
	v_mfma_f32_16x16x32_bf16 v[90:93], v[174:177], v[208:211], v[90:93]
	v_mfma_f32_16x16x32_bf16 v[82:85], v[146:149], v[216:219], v[82:85]
	v_mfma_f32_16x16x32_bf16 v[74:77], v[174:177], v[216:219], v[74:77]
	v_mfma_f32_16x16x32_bf16 v[70:73], v[146:149], v[224:227], v[70:73]
	v_mfma_f32_16x16x32_bf16 v[66:69], v[174:177], v[224:227], v[66:69]
	v_mfma_f32_16x16x32_bf16 v[114:117], v[150:153], v[204:207], v[114:117]
	v_mfma_f32_16x16x32_bf16 v[106:109], v[178:181], v[204:207], v[106:109]
	v_mfma_f32_16x16x32_bf16 v[98:101], v[150:153], v[212:215], v[98:101]
	v_mfma_f32_16x16x32_bf16 v[90:93], v[178:181], v[212:215], v[90:93]
	v_mfma_f32_16x16x32_bf16 v[82:85], v[150:153], v[220:223], v[82:85]
	v_mfma_f32_16x16x32_bf16 v[74:77], v[178:181], v[220:223], v[74:77]
	v_mfma_f32_16x16x32_bf16 v[70:73], v[150:153], v[234:237], v[70:73]
	v_mfma_f32_16x16x32_bf16 v[66:69], v[178:181], v[234:237], v[66:69]
	s_barrier
	s_add_i32 s46, s52, s8
	v_lshl_add_u64 v[186:187], s[42:43], 0, v[158:159]
	s_mov_b32 m0, s46
	ds_read_b128 v[182:185], v193 offset:16384
	ds_read_b128 v[204:207], v193 offset:17408
	ds_read_b128 v[208:211], v193 offset:18432
	ds_read_b128 v[212:215], v193 offset:19456
	ds_read_b128 v[216:219], v193 offset:20480
	ds_read_b128 v[220:223], v193 offset:21504
	ds_read_b128 v[224:227], v193 offset:22528
	ds_read_b128 v[234:237], v193 offset:23552
	global_load_lds_dwordx4 v[186:187], off
	s_add_i32 m0, s46, 0x2000
	s_add_u32 s46, s42, 0x100000
	v_lshl_add_u64 v[194:195], s[42:43], 0, v[162:163]
	s_addc_u32 s47, s43, 0
	s_add_i32 s56, s53, s8
	global_load_lds_dwordx4 v[194:195], off
	v_lshl_add_u64 v[200:201], s[46:47], 0, v[158:159]
	s_mov_b32 m0, s56
	v_lshl_add_u64 v[238:239], s[44:45], 0, v[160:161]
	global_load_lds_dwordx4 v[200:201], off
	v_lshl_add_u64 v[200:201], s[46:47], 0, v[162:163]
	s_add_i32 m0, s56, 0x2000
	s_nop 0
	global_load_lds_dwordx4 v[200:201], off
	v_lshl_add_u64 v[200:201], s[44:45], 0, v[156:157]
	s_mov_b32 m0, s9
	s_nop 0
	global_load_lds_dwordx4 v[200:201], off
	s_mov_b32 m0, s13
	s_nop 0
	global_load_lds_dwordx4 v[238:239], off
	s_waitcnt vmcnt(8)
	s_waitcnt lgkmcnt(0)
	s_barrier
	s_waitcnt lgkmcnt(0)
	v_mfma_f32_16x16x32_bf16 v[62:65], v[130:133], v[182:185], v[62:65]
	v_mfma_f32_16x16x32_bf16 v[58:61], v[138:141], v[182:185], v[58:61]
	v_mfma_f32_16x16x32_bf16 v[54:57], v[130:133], v[208:211], v[54:57]
	v_mfma_f32_16x16x32_bf16 v[46:49], v[138:141], v[208:211], v[46:49]
	v_mfma_f32_16x16x32_bf16 v[38:41], v[130:133], v[216:219], v[38:41]
	v_mfma_f32_16x16x32_bf16 v[30:33], v[138:141], v[216:219], v[30:33]
	v_mfma_f32_16x16x32_bf16 v[22:25], v[130:133], v[224:227], v[22:25]
	v_mfma_f32_16x16x32_bf16 v[14:17], v[138:141], v[224:227], v[14:17]
	v_mfma_f32_16x16x32_bf16 v[62:65], v[134:137], v[204:207], v[62:65]
	v_mfma_f32_16x16x32_bf16 v[58:61], v[142:145], v[204:207], v[58:61]
	v_mfma_f32_16x16x32_bf16 v[54:57], v[134:137], v[212:215], v[54:57]
	v_mfma_f32_16x16x32_bf16 v[46:49], v[142:145], v[212:215], v[46:49]
	v_mfma_f32_16x16x32_bf16 v[38:41], v[134:137], v[220:223], v[38:41]
	v_mfma_f32_16x16x32_bf16 v[30:33], v[142:145], v[220:223], v[30:33]
	v_mfma_f32_16x16x32_bf16 v[22:25], v[134:137], v[234:237], v[22:25]
	v_mfma_f32_16x16x32_bf16 v[14:17], v[142:145], v[234:237], v[14:17]
	v_mfma_f32_16x16x32_bf16 v[50:53], v[146:149], v[182:185], v[50:53]
	v_mfma_f32_16x16x32_bf16 v[42:45], v[174:177], v[182:185], v[42:45]
	v_mfma_f32_16x16x32_bf16 v[34:37], v[146:149], v[208:211], v[34:37]
	v_mfma_f32_16x16x32_bf16 v[26:29], v[174:177], v[208:211], v[26:29]
	v_mfma_f32_16x16x32_bf16 v[18:21], v[146:149], v[216:219], v[18:21]
	v_mfma_f32_16x16x32_bf16 v[10:13], v[174:177], v[216:219], v[10:13]
	v_mfma_f32_16x16x32_bf16 v[6:9], v[146:149], v[224:227], v[6:9]
	v_mfma_f32_16x16x32_bf16 v[2:5], v[174:177], v[224:227], v[2:5]
	v_mfma_f32_16x16x32_bf16 v[50:53], v[150:153], v[204:207], v[50:53]
	v_mfma_f32_16x16x32_bf16 v[42:45], v[178:181], v[204:207], v[42:45]
	v_mfma_f32_16x16x32_bf16 v[34:37], v[150:153], v[212:215], v[34:37]
	v_mfma_f32_16x16x32_bf16 v[26:29], v[178:181], v[212:215], v[26:29]
	v_mfma_f32_16x16x32_bf16 v[18:21], v[150:153], v[220:223], v[18:21]
	v_mfma_f32_16x16x32_bf16 v[10:13], v[178:181], v[220:223], v[10:13]
	v_mfma_f32_16x16x32_bf16 v[6:9], v[150:153], v[234:237], v[6:9]
	v_mfma_f32_16x16x32_bf16 v[2:5], v[178:181], v[234:237], v[2:5]
	s_barrier
	s_add_i32 s46, 0, 0x18000
	s_add_i32 s47, 0, 0x1c000
	v_add_u32_e32 v142, s46, v188
	v_add_u32_e32 v164, s47, v188
	ds_read_b128 v[130:133], v142
	ds_read_b128 v[134:137], v142 offset:1024
	ds_read_b128 v[138:141], v142 offset:2048
	ds_read_b128 v[142:145], v142 offset:3072
	ds_read_b128 v[146:149], v164
	ds_read_b128 v[150:153], v164 offset:1024
	ds_read_b128 v[174:177], v164 offset:2048
	ds_read_b128 v[178:181], v164 offset:3072
	s_add_u32 s44, s44, 0x100000
	s_addc_u32 s45, s45, 0
	s_mov_b32 m0, s33
	v_lshl_add_u64 v[240:241], s[44:45], 0, v[156:157]
	ds_read_b128 v[182:185], v193 offset:32768
	ds_read_b128 v[204:207], v193 offset:33792
	ds_read_b128 v[208:211], v193 offset:34816
	ds_read_b128 v[212:215], v193 offset:35840
	ds_read_b128 v[216:219], v193 offset:36864
	ds_read_b128 v[220:223], v193 offset:37888
	ds_read_b128 v[224:227], v193 offset:38912
	ds_read_b128 v[234:237], v193 offset:39936
	global_load_lds_dwordx4 v[240:241], off
	v_lshl_add_u64 v[240:241], s[44:45], 0, v[160:161]
	s_mov_b32 m0, s39
	s_nop 0
	global_load_lds_dwordx4 v[240:241], off
	s_waitcnt vmcnt(8)
	s_waitcnt lgkmcnt(0)
	s_barrier
	s_waitcnt lgkmcnt(0)
	v_mfma_f32_16x16x32_bf16 v[126:129], v[130:133], v[182:185], v[126:129]
	v_mfma_f32_16x16x32_bf16 v[122:125], v[138:141], v[182:185], v[122:125]
	v_mfma_f32_16x16x32_bf16 v[118:121], v[130:133], v[208:211], v[118:121]
	v_mfma_f32_16x16x32_bf16 v[110:113], v[138:141], v[208:211], v[110:113]
	v_mfma_f32_16x16x32_bf16 v[102:105], v[130:133], v[216:219], v[102:105]
	v_mfma_f32_16x16x32_bf16 v[94:97], v[138:141], v[216:219], v[94:97]
	v_mfma_f32_16x16x32_bf16 v[86:89], v[130:133], v[224:227], v[86:89]
	v_mfma_f32_16x16x32_bf16 v[78:81], v[138:141], v[224:227], v[78:81]
	v_mfma_f32_16x16x32_bf16 v[126:129], v[134:137], v[204:207], v[126:129]
	v_mfma_f32_16x16x32_bf16 v[122:125], v[142:145], v[204:207], v[122:125]
	v_mfma_f32_16x16x32_bf16 v[118:121], v[134:137], v[212:215], v[118:121]
	v_mfma_f32_16x16x32_bf16 v[110:113], v[142:145], v[212:215], v[110:113]
	v_mfma_f32_16x16x32_bf16 v[102:105], v[134:137], v[220:223], v[102:105]
	v_mfma_f32_16x16x32_bf16 v[94:97], v[142:145], v[220:223], v[94:97]
	v_mfma_f32_16x16x32_bf16 v[86:89], v[134:137], v[234:237], v[86:89]
	v_mfma_f32_16x16x32_bf16 v[78:81], v[142:145], v[234:237], v[78:81]
	v_mfma_f32_16x16x32_bf16 v[114:117], v[146:149], v[182:185], v[114:117]
	v_mfma_f32_16x16x32_bf16 v[106:109], v[174:177], v[182:185], v[106:109]
	v_mfma_f32_16x16x32_bf16 v[98:101], v[146:149], v[208:211], v[98:101]
	v_mfma_f32_16x16x32_bf16 v[90:93], v[174:177], v[208:211], v[90:93]
	v_mfma_f32_16x16x32_bf16 v[82:85], v[146:149], v[216:219], v[82:85]
	v_mfma_f32_16x16x32_bf16 v[74:77], v[174:177], v[216:219], v[74:77]
	v_mfma_f32_16x16x32_bf16 v[70:73], v[146:149], v[224:227], v[70:73]
	v_mfma_f32_16x16x32_bf16 v[66:69], v[174:177], v[224:227], v[66:69]
	v_mfma_f32_16x16x32_bf16 v[114:117], v[150:153], v[204:207], v[114:117]
	v_mfma_f32_16x16x32_bf16 v[106:109], v[178:181], v[204:207], v[106:109]
	v_mfma_f32_16x16x32_bf16 v[98:101], v[150:153], v[212:215], v[98:101]
	v_mfma_f32_16x16x32_bf16 v[90:93], v[178:181], v[212:215], v[90:93]
	v_mfma_f32_16x16x32_bf16 v[82:85], v[150:153], v[220:223], v[82:85]
	v_mfma_f32_16x16x32_bf16 v[74:77], v[178:181], v[220:223], v[74:77]
	v_mfma_f32_16x16x32_bf16 v[70:73], v[150:153], v[234:237], v[70:73]
	v_mfma_f32_16x16x32_bf16 v[66:69], v[178:181], v[234:237], v[66:69]
	s_barrier
	s_add_i32 s44, s46, s8
	v_lshl_add_u64 v[186:187], v[186:187], 0, s[20:21]
	s_mov_b32 m0, s44
	ds_read_b128 v[182:185], v193 offset:49152
	ds_read_b128 v[204:207], v193 offset:50176
	ds_read_b128 v[208:211], v193 offset:51200
	ds_read_b128 v[212:215], v193 offset:52224
	ds_read_b128 v[216:219], v193 offset:53248
	ds_read_b128 v[220:223], v193 offset:54272
	ds_read_b128 v[224:227], v193 offset:55296
	ds_read_b128 v[234:237], v193 offset:56320
	global_load_lds_dwordx4 v[186:187], off
	s_add_i32 m0, s44, 0x2000
	s_add_u32 s42, s42, 0x100080
	v_lshl_add_u64 v[186:187], v[194:195], 0, s[20:21]
	s_addc_u32 s43, s43, 0
	s_add_i32 s44, s47, s8
	global_load_lds_dwordx4 v[186:187], off
	v_lshl_add_u64 v[186:187], s[42:43], 0, v[158:159]
	s_mov_b32 m0, s44
	s_nop 0
	global_load_lds_dwordx4 v[186:187], off
	v_lshl_add_u64 v[186:187], s[42:43], 0, v[162:163]
	s_add_i32 m0, s44, 0x2000
	s_nop 0
	global_load_lds_dwordx4 v[186:187], off
	v_lshl_add_u64 v[186:187], v[200:201], 0, s[20:21]
	s_mov_b32 m0, s50
	s_nop 0
	global_load_lds_dwordx4 v[186:187], off
	v_lshl_add_u64 v[186:187], v[238:239], 0, s[20:21]
	s_mov_b32 m0, s51
	s_nop 0
	global_load_lds_dwordx4 v[186:187], off
	s_waitcnt vmcnt(8)
	s_waitcnt lgkmcnt(0)
	s_barrier
	s_waitcnt lgkmcnt(0)
	v_mfma_f32_16x16x32_bf16 v[62:65], v[130:133], v[182:185], v[62:65]
	v_mfma_f32_16x16x32_bf16 v[58:61], v[138:141], v[182:185], v[58:61]
	v_mfma_f32_16x16x32_bf16 v[54:57], v[130:133], v[208:211], v[54:57]
	v_mfma_f32_16x16x32_bf16 v[46:49], v[138:141], v[208:211], v[46:49]
	v_mfma_f32_16x16x32_bf16 v[38:41], v[130:133], v[216:219], v[38:41]
	v_mfma_f32_16x16x32_bf16 v[30:33], v[138:141], v[216:219], v[30:33]
	v_mfma_f32_16x16x32_bf16 v[22:25], v[130:133], v[224:227], v[22:25]
	v_mfma_f32_16x16x32_bf16 v[14:17], v[138:141], v[224:227], v[14:17]
	v_mfma_f32_16x16x32_bf16 v[62:65], v[134:137], v[204:207], v[62:65]
	v_mfma_f32_16x16x32_bf16 v[58:61], v[142:145], v[204:207], v[58:61]
	v_mfma_f32_16x16x32_bf16 v[54:57], v[134:137], v[212:215], v[54:57]
	v_mfma_f32_16x16x32_bf16 v[46:49], v[142:145], v[212:215], v[46:49]
	v_mfma_f32_16x16x32_bf16 v[38:41], v[134:137], v[220:223], v[38:41]
	v_mfma_f32_16x16x32_bf16 v[30:33], v[142:145], v[220:223], v[30:33]
	v_mfma_f32_16x16x32_bf16 v[22:25], v[134:137], v[234:237], v[22:25]
	v_mfma_f32_16x16x32_bf16 v[14:17], v[142:145], v[234:237], v[14:17]
	v_mfma_f32_16x16x32_bf16 v[50:53], v[146:149], v[182:185], v[50:53]
	v_mfma_f32_16x16x32_bf16 v[42:45], v[174:177], v[182:185], v[42:45]
	v_mfma_f32_16x16x32_bf16 v[34:37], v[146:149], v[208:211], v[34:37]
	v_mfma_f32_16x16x32_bf16 v[26:29], v[174:177], v[208:211], v[26:29]
	v_mfma_f32_16x16x32_bf16 v[18:21], v[146:149], v[216:219], v[18:21]
	v_mfma_f32_16x16x32_bf16 v[10:13], v[174:177], v[216:219], v[10:13]
	v_mfma_f32_16x16x32_bf16 v[6:9], v[146:149], v[224:227], v[6:9]
	v_mfma_f32_16x16x32_bf16 v[2:5], v[174:177], v[224:227], v[2:5]
	v_mfma_f32_16x16x32_bf16 v[50:53], v[150:153], v[204:207], v[50:53]
	v_mfma_f32_16x16x32_bf16 v[42:45], v[178:181], v[204:207], v[42:45]
	v_mfma_f32_16x16x32_bf16 v[34:37], v[150:153], v[212:215], v[34:37]
	v_mfma_f32_16x16x32_bf16 v[26:29], v[178:181], v[212:215], v[26:29]
	v_mfma_f32_16x16x32_bf16 v[18:21], v[150:153], v[220:223], v[18:21]
	v_mfma_f32_16x16x32_bf16 v[10:13], v[178:181], v[220:223], v[10:13]
	v_mfma_f32_16x16x32_bf16 v[6:9], v[150:153], v[234:237], v[6:9]
	v_mfma_f32_16x16x32_bf16 v[2:5], v[178:181], v[234:237], v[2:5]
	s_barrier
	s_add_i32 s29, s29, 2
	s_add_u32 s40, s40, 0x100
	s_addc_u32 s41, s41, 0
	s_add_u32 s15, s15, 0x100
	s_addc_u32 s27, s27, 0
	s_cmp_gt_u32 s29, 61
	s_cbranch_scc0 .LBB0_412
	s_and_b64 vcc, exec, s[22:23]
	s_cbranch_vccz .LBB0_415
	s_barrier

.LBB0_514:
	ds_read_b128 v[156:159], v146
	ds_read_b128 v[160:163], v146 offset:1024
	ds_read_b128 v[164:167], v146 offset:2048
	ds_read_b128 v[168:171], v146 offset:3072
	ds_read_b128 v[172:175], v147
	s_waitcnt lgkmcnt(0)
	ds_read_b128 v[176:179], v147 offset:1024
	ds_read_b128 v[180:183], v147 offset:2048
	ds_read_b128 v[184:187], v147 offset:3072
	s_add_u32 s28, s26, 0xfff00080
	s_addc_u32 s29, s27, -1
	s_cmp_eq_u32 s50, 4
	s_cselect_b32 s31, s19, s29
	s_cselect_b32 s30, s18, s28
	s_cselect_b32 s29, s21, s49
	s_cselect_b32 s28, s20, s23
	s_mov_b32 m0, s36
	v_lshl_add_u64 v[142:143], s[26:27], 0, v[138:139]
	ds_read_b128 v[190:193], v148
	ds_read_b128 v[204:207], v148 offset:1024
	ds_read_b128 v[208:211], v148 offset:2048
	ds_read_b128 v[212:215], v148 offset:3072
	ds_read_b128 v[216:219], v148 offset:4096
	ds_read_b128 v[220:223], v148 offset:5120
	ds_read_b128 v[224:227], v148 offset:6144
	ds_read_b128 v[234:237], v148 offset:7168
	global_load_lds_dwordx4 v[142:143], off
	v_lshl_add_u64 v[142:143], s[26:27], 0, v[140:141]
	s_mov_b32 m0, s37
	s_nop 0
	global_load_lds_dwordx4 v[142:143], off
	s_waitcnt vmcnt(8)
	s_waitcnt lgkmcnt(0)
	s_barrier
	s_waitcnt lgkmcnt(0)
	v_mfma_f32_16x16x32_bf16 v[126:129], v[156:159], v[190:193], v[126:129]
	v_mfma_f32_16x16x32_bf16 v[122:125], v[164:167], v[190:193], v[122:125]
	v_mfma_f32_16x16x32_bf16 v[118:121], v[156:159], v[208:211], v[118:121]
	v_mfma_f32_16x16x32_bf16 v[110:113], v[164:167], v[208:211], v[110:113]
	v_mfma_f32_16x16x32_bf16 v[102:105], v[156:159], v[216:219], v[102:105]
	v_mfma_f32_16x16x32_bf16 v[94:97], v[164:167], v[216:219], v[94:97]
	v_mfma_f32_16x16x32_bf16 v[82:85], v[156:159], v[224:227], v[82:85]
	v_mfma_f32_16x16x32_bf16 v[74:77], v[164:167], v[224:227], v[74:77]
	v_mfma_f32_16x16x32_bf16 v[126:129], v[160:163], v[204:207], v[126:129]
	v_mfma_f32_16x16x32_bf16 v[122:125], v[168:171], v[204:207], v[122:125]
	v_mfma_f32_16x16x32_bf16 v[118:121], v[160:163], v[212:215], v[118:121]
	v_mfma_f32_16x16x32_bf16 v[110:113], v[168:171], v[212:215], v[110:113]
	v_mfma_f32_16x16x32_bf16 v[102:105], v[160:163], v[220:223], v[102:105]
	v_mfma_f32_16x16x32_bf16 v[94:97], v[168:171], v[220:223], v[94:97]
	v_mfma_f32_16x16x32_bf16 v[82:85], v[160:163], v[234:237], v[82:85]
	v_mfma_f32_16x16x32_bf16 v[74:77], v[168:171], v[234:237], v[74:77]
	v_mfma_f32_16x16x32_bf16 v[114:117], v[172:175], v[190:193], v[114:117]
	v_mfma_f32_16x16x32_bf16 v[106:109], v[180:183], v[190:193], v[106:109]
	v_mfma_f32_16x16x32_bf16 v[98:101], v[172:175], v[208:211], v[98:101]
	v_mfma_f32_16x16x32_bf16 v[90:93], v[180:183], v[208:211], v[90:93]
	v_mfma_f32_16x16x32_bf16 v[86:89], v[172:175], v[216:219], v[86:89]
	v_mfma_f32_16x16x32_bf16 v[78:81], v[180:183], v[216:219], v[78:81]
	v_mfma_f32_16x16x32_bf16 v[70:73], v[172:175], v[224:227], v[70:73]
	v_mfma_f32_16x16x32_bf16 v[66:69], v[180:183], v[224:227], v[66:69]
	v_mfma_f32_16x16x32_bf16 v[114:117], v[176:179], v[204:207], v[114:117]
	v_mfma_f32_16x16x32_bf16 v[106:109], v[184:187], v[204:207], v[106:109]
	v_mfma_f32_16x16x32_bf16 v[98:101], v[176:179], v[212:215], v[98:101]
	v_mfma_f32_16x16x32_bf16 v[90:93], v[184:187], v[212:215], v[90:93]
	v_mfma_f32_16x16x32_bf16 v[86:89], v[176:179], v[220:223], v[86:89]
	v_mfma_f32_16x16x32_bf16 v[78:81], v[184:187], v[220:223], v[78:81]
	v_mfma_f32_16x16x32_bf16 v[70:73], v[176:179], v[234:237], v[70:73]
	v_mfma_f32_16x16x32_bf16 v[66:69], v[184:187], v[234:237], v[66:69]
	s_barrier
	s_mov_b32 m0, s38
	v_lshl_add_u64 v[142:143], s[28:29], 0, v[134:135]
	s_add_u32 s52, s28, 0x20000
	ds_read_b128 v[190:193], v148 offset:16384
	ds_read_b128 v[204:207], v148 offset:17408
	ds_read_b128 v[208:211], v148 offset:18432
	ds_read_b128 v[212:215], v148 offset:19456
	ds_read_b128 v[216:219], v148 offset:20480
	ds_read_b128 v[220:223], v148 offset:21504
	ds_read_b128 v[224:227], v148 offset:22528
	ds_read_b128 v[234:237], v148 offset:23552
	global_load_lds_dwordx4 v[142:143], off
	v_lshl_add_u64 v[152:153], s[28:29], 0, v[130:131]
	s_mov_b32 m0, s39
	s_addc_u32 s53, s29, 0
	global_load_lds_dwordx4 v[152:153], off
	v_lshl_add_u64 v[194:195], s[52:53], 0, v[134:135]
	s_mov_b32 m0, s40
	v_lshl_add_u64 v[200:201], s[30:31], 0, v[132:133]
	global_load_lds_dwordx4 v[194:195], off
	v_lshl_add_u64 v[194:195], s[52:53], 0, v[130:131]
	s_mov_b32 m0, s41
	s_nop 0
	global_load_lds_dwordx4 v[194:195], off
	v_lshl_add_u64 v[194:195], s[30:31], 0, v[136:137]
	s_mov_b32 m0, s9
	s_nop 0
	global_load_lds_dwordx4 v[194:195], off
	s_mov_b32 m0, s13
	s_nop 0
	global_load_lds_dwordx4 v[200:201], off
	s_waitcnt vmcnt(8)
	s_waitcnt lgkmcnt(0)
	s_barrier
	s_waitcnt lgkmcnt(0)
	v_mfma_f32_16x16x32_bf16 v[62:65], v[156:159], v[190:193], v[62:65]
	v_mfma_f32_16x16x32_bf16 v[58:61], v[164:167], v[190:193], v[58:61]
	v_mfma_f32_16x16x32_bf16 v[54:57], v[156:159], v[208:211], v[54:57]
	v_mfma_f32_16x16x32_bf16 v[46:49], v[164:167], v[208:211], v[46:49]
	v_mfma_f32_16x16x32_bf16 v[38:41], v[156:159], v[216:219], v[38:41]
	v_mfma_f32_16x16x32_bf16 v[30:33], v[164:167], v[216:219], v[30:33]
	v_mfma_f32_16x16x32_bf16 v[22:25], v[156:159], v[224:227], v[22:25]
	v_mfma_f32_16x16x32_bf16 v[14:17], v[164:167], v[224:227], v[14:17]
	v_mfma_f32_16x16x32_bf16 v[62:65], v[160:163], v[204:207], v[62:65]
	v_mfma_f32_16x16x32_bf16 v[58:61], v[168:171], v[204:207], v[58:61]
	v_mfma_f32_16x16x32_bf16 v[54:57], v[160:163], v[212:215], v[54:57]
	v_mfma_f32_16x16x32_bf16 v[46:49], v[168:171], v[212:215], v[46:49]
	v_mfma_f32_16x16x32_bf16 v[38:41], v[160:163], v[220:223], v[38:41]
	v_mfma_f32_16x16x32_bf16 v[30:33], v[168:171], v[220:223], v[30:33]
	v_mfma_f32_16x16x32_bf16 v[22:25], v[160:163], v[234:237], v[22:25]
	v_mfma_f32_16x16x32_bf16 v[14:17], v[168:171], v[234:237], v[14:17]
	v_mfma_f32_16x16x32_bf16 v[50:53], v[172:175], v[190:193], v[50:53]
	v_mfma_f32_16x16x32_bf16 v[42:45], v[180:183], v[190:193], v[42:45]
	v_mfma_f32_16x16x32_bf16 v[34:37], v[172:175], v[208:211], v[34:37]
	v_mfma_f32_16x16x32_bf16 v[26:29], v[180:183], v[208:211], v[26:29]
	v_mfma_f32_16x16x32_bf16 v[18:21], v[172:175], v[216:219], v[18:21]
	v_mfma_f32_16x16x32_bf16 v[10:13], v[180:183], v[216:219], v[10:13]
	v_mfma_f32_16x16x32_bf16 v[6:9], v[172:175], v[224:227], v[6:9]
	v_mfma_f32_16x16x32_bf16 v[2:5], v[180:183], v[224:227], v[2:5]
	v_mfma_f32_16x16x32_bf16 v[50:53], v[176:179], v[204:207], v[50:53]
	v_mfma_f32_16x16x32_bf16 v[42:45], v[184:187], v[204:207], v[42:45]
	v_mfma_f32_16x16x32_bf16 v[34:37], v[176:179], v[212:215], v[34:37]
	v_mfma_f32_16x16x32_bf16 v[26:29], v[184:187], v[212:215], v[26:29]
	v_mfma_f32_16x16x32_bf16 v[18:21], v[176:179], v[220:223], v[18:21]
	v_mfma_f32_16x16x32_bf16 v[10:13], v[184:187], v[220:223], v[10:13]
	v_mfma_f32_16x16x32_bf16 v[6:9], v[176:179], v[234:237], v[6:9]
	v_mfma_f32_16x16x32_bf16 v[2:5], v[184:187], v[234:237], v[2:5]
	s_barrier
	ds_read_b128 v[156:159], v149
	ds_read_b128 v[160:163], v149 offset:1024
	ds_read_b128 v[164:167], v149 offset:2048
	ds_read_b128 v[168:171], v149 offset:3072
	ds_read_b128 v[172:175], v150
	ds_read_b128 v[176:179], v150 offset:1024
	ds_read_b128 v[180:183], v150 offset:2048
	ds_read_b128 v[184:187], v150 offset:3072
	s_add_u32 s30, s30, 0x100000
	s_addc_u32 s31, s31, 0
	s_mov_b32 m0, s14
	v_lshl_add_u64 v[238:239], s[30:31], 0, v[136:137]
	ds_read_b128 v[190:193], v148 offset:32768
	ds_read_b128 v[204:207], v148 offset:33792
	ds_read_b128 v[208:211], v148 offset:34816
	ds_read_b128 v[212:215], v148 offset:35840
	ds_read_b128 v[216:219], v148 offset:36864
	ds_read_b128 v[220:223], v148 offset:37888
	ds_read_b128 v[224:227], v148 offset:38912
	ds_read_b128 v[234:237], v148 offset:39936
	global_load_lds_dwordx4 v[238:239], off
	v_lshl_add_u64 v[238:239], s[30:31], 0, v[132:133]
	s_mov_b32 m0, s15
	s_nop 0
	global_load_lds_dwordx4 v[238:239], off
	s_waitcnt vmcnt(8)
	s_waitcnt lgkmcnt(0)
	s_barrier
	s_waitcnt lgkmcnt(0)
	v_mfma_f32_16x16x32_bf16 v[126:129], v[156:159], v[190:193], v[126:129]
	v_mfma_f32_16x16x32_bf16 v[122:125], v[164:167], v[190:193], v[122:125]
	v_mfma_f32_16x16x32_bf16 v[118:121], v[156:159], v[208:211], v[118:121]
	v_mfma_f32_16x16x32_bf16 v[110:113], v[164:167], v[208:211], v[110:113]
	v_mfma_f32_16x16x32_bf16 v[102:105], v[156:159], v[216:219], v[102:105]
	v_mfma_f32_16x16x32_bf16 v[94:97], v[164:167], v[216:219], v[94:97]
	v_mfma_f32_16x16x32_bf16 v[82:85], v[156:159], v[224:227], v[82:85]
	v_mfma_f32_16x16x32_bf16 v[74:77], v[164:167], v[224:227], v[74:77]
	v_mfma_f32_16x16x32_bf16 v[126:129], v[160:163], v[204:207], v[126:129]
	v_mfma_f32_16x16x32_bf16 v[122:125], v[168:171], v[204:207], v[122:125]
	v_mfma_f32_16x16x32_bf16 v[118:121], v[160:163], v[212:215], v[118:121]
	v_mfma_f32_16x16x32_bf16 v[110:113], v[168:171], v[212:215], v[110:113]
	v_mfma_f32_16x16x32_bf16 v[102:105], v[160:163], v[220:223], v[102:105]
	v_mfma_f32_16x16x32_bf16 v[94:97], v[168:171], v[220:223], v[94:97]
	v_mfma_f32_16x16x32_bf16 v[82:85], v[160:163], v[234:237], v[82:85]
	v_mfma_f32_16x16x32_bf16 v[74:77], v[168:171], v[234:237], v[74:77]
	v_mfma_f32_16x16x32_bf16 v[114:117], v[172:175], v[190:193], v[114:117]
	v_mfma_f32_16x16x32_bf16 v[106:109], v[180:183], v[190:193], v[106:109]
	v_mfma_f32_16x16x32_bf16 v[98:101], v[172:175], v[208:211], v[98:101]
	v_mfma_f32_16x16x32_bf16 v[90:93], v[180:183], v[208:211], v[90:93]
	v_mfma_f32_16x16x32_bf16 v[86:89], v[172:175], v[216:219], v[86:89]
	v_mfma_f32_16x16x32_bf16 v[78:81], v[180:183], v[216:219], v[78:81]
	v_mfma_f32_16x16x32_bf16 v[70:73], v[172:175], v[224:227], v[70:73]
	v_mfma_f32_16x16x32_bf16 v[66:69], v[180:183], v[224:227], v[66:69]
	v_mfma_f32_16x16x32_bf16 v[114:117], v[176:179], v[204:207], v[114:117]
	v_mfma_f32_16x16x32_bf16 v[106:109], v[184:187], v[204:207], v[106:109]
	v_mfma_f32_16x16x32_bf16 v[98:101], v[176:179], v[212:215], v[98:101]
	v_mfma_f32_16x16x32_bf16 v[90:93], v[184:187], v[212:215], v[90:93]
	v_mfma_f32_16x16x32_bf16 v[86:89], v[176:179], v[220:223], v[86:89]
	v_mfma_f32_16x16x32_bf16 v[78:81], v[184:187], v[220:223], v[78:81]
	v_mfma_f32_16x16x32_bf16 v[70:73], v[176:179], v[234:237], v[70:73]
	v_mfma_f32_16x16x32_bf16 v[66:69], v[184:187], v[234:237], v[66:69]
	s_barrier
	s_mov_b32 m0, s42
	v_lshl_add_u64 v[142:143], v[142:143], 0, s[4:5]
	s_add_u32 s28, s28, 0x20080
	ds_read_b128 v[190:193], v148 offset:49152
	ds_read_b128 v[204:207], v148 offset:50176
	ds_read_b128 v[208:211], v148 offset:51200
	ds_read_b128 v[212:215], v148 offset:52224
	ds_read_b128 v[216:219], v148 offset:53248
	ds_read_b128 v[220:223], v148 offset:54272
	ds_read_b128 v[224:227], v148 offset:55296
	ds_read_b128 v[234:237], v148 offset:56320
	global_load_lds_dwordx4 v[142:143], off
	v_lshl_add_u64 v[142:143], v[152:153], 0, s[4:5]
	s_mov_b32 m0, s43
	s_addc_u32 s29, s29, 0
	global_load_lds_dwordx4 v[142:143], off
	v_lshl_add_u64 v[142:143], s[28:29], 0, v[134:135]
	s_mov_b32 m0, s44
	s_nop 0
	global_load_lds_dwordx4 v[142:143], off
	v_lshl_add_u64 v[142:143], s[28:29], 0, v[130:131]
	s_mov_b32 m0, s45
	s_nop 0
	global_load_lds_dwordx4 v[142:143], off
	v_lshl_add_u64 v[142:143], v[194:195], 0, s[4:5]
	s_mov_b32 m0, s34
	s_nop 0
	global_load_lds_dwordx4 v[142:143], off
	v_lshl_add_u64 v[142:143], v[200:201], 0, s[4:5]
	s_mov_b32 m0, s35
	s_nop 0
	global_load_lds_dwordx4 v[142:143], off
	s_waitcnt vmcnt(8)
	s_waitcnt lgkmcnt(0)
	s_barrier
	s_waitcnt lgkmcnt(0)
	v_mfma_f32_16x16x32_bf16 v[62:65], v[156:159], v[190:193], v[62:65]
	v_mfma_f32_16x16x32_bf16 v[58:61], v[164:167], v[190:193], v[58:61]
	v_mfma_f32_16x16x32_bf16 v[54:57], v[156:159], v[208:211], v[54:57]
	v_mfma_f32_16x16x32_bf16 v[46:49], v[164:167], v[208:211], v[46:49]
	v_mfma_f32_16x16x32_bf16 v[38:41], v[156:159], v[216:219], v[38:41]
	v_mfma_f32_16x16x32_bf16 v[30:33], v[164:167], v[216:219], v[30:33]
	v_mfma_f32_16x16x32_bf16 v[22:25], v[156:159], v[224:227], v[22:25]
	v_mfma_f32_16x16x32_bf16 v[14:17], v[164:167], v[224:227], v[14:17]
	v_mfma_f32_16x16x32_bf16 v[62:65], v[160:163], v[204:207], v[62:65]
	v_mfma_f32_16x16x32_bf16 v[58:61], v[168:171], v[204:207], v[58:61]
	v_mfma_f32_16x16x32_bf16 v[54:57], v[160:163], v[212:215], v[54:57]
	v_mfma_f32_16x16x32_bf16 v[46:49], v[168:171], v[212:215], v[46:49]
	v_mfma_f32_16x16x32_bf16 v[38:41], v[160:163], v[220:223], v[38:41]
	v_mfma_f32_16x16x32_bf16 v[30:33], v[168:171], v[220:223], v[30:33]
	v_mfma_f32_16x16x32_bf16 v[22:25], v[160:163], v[234:237], v[22:25]
	v_mfma_f32_16x16x32_bf16 v[14:17], v[168:171], v[234:237], v[14:17]
	v_mfma_f32_16x16x32_bf16 v[50:53], v[172:175], v[190:193], v[50:53]
	v_mfma_f32_16x16x32_bf16 v[42:45], v[180:183], v[190:193], v[42:45]
	v_mfma_f32_16x16x32_bf16 v[34:37], v[172:175], v[208:211], v[34:37]
	v_mfma_f32_16x16x32_bf16 v[26:29], v[180:183], v[208:211], v[26:29]
	v_mfma_f32_16x16x32_bf16 v[18:21], v[172:175], v[216:219], v[18:21]
	v_mfma_f32_16x16x32_bf16 v[10:13], v[180:183], v[216:219], v[10:13]
	v_mfma_f32_16x16x32_bf16 v[6:9], v[172:175], v[224:227], v[6:9]
	v_mfma_f32_16x16x32_bf16 v[2:5], v[180:183], v[224:227], v[2:5]
	v_mfma_f32_16x16x32_bf16 v[50:53], v[176:179], v[204:207], v[50:53]
	v_mfma_f32_16x16x32_bf16 v[42:45], v[184:187], v[204:207], v[42:45]
	v_mfma_f32_16x16x32_bf16 v[34:37], v[176:179], v[212:215], v[34:37]
	v_mfma_f32_16x16x32_bf16 v[26:29], v[184:187], v[212:215], v[26:29]
	v_mfma_f32_16x16x32_bf16 v[18:21], v[176:179], v[220:223], v[18:21]
	v_mfma_f32_16x16x32_bf16 v[10:13], v[184:187], v[220:223], v[10:13]
	v_mfma_f32_16x16x32_bf16 v[6:9], v[176:179], v[234:237], v[6:9]
	v_mfma_f32_16x16x32_bf16 v[2:5], v[184:187], v[234:237], v[2:5]
	s_barrier
	s_add_i32 s50, s50, 2
	s_add_u32 s26, s26, 0x100
	s_addc_u32 s27, s27, 0
	s_add_u32 s23, s23, 0x100
	s_addc_u32 s49, s49, 0
	s_cmp_gt_u32 s50, 5
	s_cbranch_scc0 .LBB0_514
	s_and_b64 vcc, exec, s[6:7]
	s_cbranch_vccz .LBB0_517
	s_barrier

.LBB0_734:
	ds_read_b128 v[158:161], v227
	ds_read_b128 v[154:157], v227 offset:1024
	ds_read_b128 v[150:153], v227 offset:2048
	ds_read_b128 v[146:149], v227 offset:3072
	ds_read_b128 v[62:65], v233
	ds_read_b128 v[58:61], v233 offset:1024
	ds_read_b128 v[54:57], v233 offset:2048
	ds_read_b128 v[50:53], v233 offset:3072
	s_add_u32 s14, s30, s34
	s_addc_u32 s15, s31, s35
	s_add_u32 s14, s14, 0x100
	s_addc_u32 s15, s15, 0
	s_add_u32 s25, s77, s34
	s_addc_u32 s29, s78, s35
	s_cmpk_eq_i32 s34, 0xf00
	s_cselect_b32 s41, s31, s15
	s_cselect_b32 s40, s30, s14
	s_cselect_b32 s39, s1, s29
	s_cselect_b32 s38, s0, s25
	s_add_i32 s66, s23, 0xc000
	v_lshl_add_u64 v[240:241], v[162:163], 0, s[34:35]
	s_mov_b32 m0, s66
	s_add_i32 s67, s23, 0xe000
	ds_read_b128 v[166:169], v226
	ds_read_b128 v[170:173], v226 offset:1024
	ds_read_b128 v[174:177], v226 offset:2048
	ds_read_b128 v[178:181], v226 offset:3072
	ds_read_b128 v[182:185], v226 offset:4096
	ds_read_b128 v[186:189], v226 offset:5120
	ds_read_b128 v[190:193], v226 offset:6144
	ds_read_b128 v[236:239], v226 offset:7168
	global_load_lds_dwordx4 v[240:241], off
	v_lshl_add_u64 v[240:241], v[164:165], 0, s[34:35]
	s_mov_b32 m0, s67
	s_nop 0
	global_load_lds_dwordx4 v[240:241], off
	s_waitcnt vmcnt(8)
	s_waitcnt lgkmcnt(0)
	s_barrier
	s_waitcnt lgkmcnt(0)
	v_mfma_i32_16x16x64_i8 v[142:145], v[158:161], v[166:169], v[142:145]
	s_nop 0
	v_mfma_i32_16x16x64_i8 v[142:145], v[154:157], v[170:173], v[142:145]
	v_mfma_i32_16x16x64_i8 v[138:141], v[150:153], v[166:169], v[138:141]
	s_nop 0
	v_mfma_i32_16x16x64_i8 v[138:141], v[146:149], v[170:173], v[138:141]
	v_mfma_i32_16x16x64_i8 v[126:129], v[158:161], v[174:177], v[126:129]
	s_nop 0
	v_mfma_i32_16x16x64_i8 v[126:129], v[154:157], v[178:181], v[126:129]
	v_mfma_i32_16x16x64_i8 v[122:125], v[150:153], v[174:177], v[122:125]
	s_nop 0
	v_mfma_i32_16x16x64_i8 v[122:125], v[146:149], v[178:181], v[122:125]
	v_mfma_i32_16x16x64_i8 v[110:113], v[158:161], v[182:185], v[110:113]
	s_nop 0
	v_mfma_i32_16x16x64_i8 v[110:113], v[154:157], v[186:189], v[110:113]
	v_mfma_i32_16x16x64_i8 v[106:109], v[150:153], v[182:185], v[106:109]
	s_nop 0
	v_mfma_i32_16x16x64_i8 v[106:109], v[146:149], v[186:189], v[106:109]
	v_mfma_i32_16x16x64_i8 v[94:97], v[158:161], v[190:193], v[94:97]
	s_nop 0
	v_mfma_i32_16x16x64_i8 v[94:97], v[154:157], v[236:239], v[94:97]
	v_mfma_i32_16x16x64_i8 v[90:93], v[150:153], v[190:193], v[90:93]
	s_nop 0
	v_mfma_i32_16x16x64_i8 v[90:93], v[146:149], v[236:239], v[90:93]
	v_mfma_i32_16x16x64_i8 v[134:137], v[62:65], v[166:169], v[134:137]
	s_nop 0
	v_mfma_i32_16x16x64_i8 v[134:137], v[58:61], v[170:173], v[134:137]
	v_mfma_i32_16x16x64_i8 v[130:133], v[54:57], v[166:169], v[130:133]
	s_nop 0
	v_mfma_i32_16x16x64_i8 v[130:133], v[50:53], v[170:173], v[130:133]
	v_mfma_i32_16x16x64_i8 v[118:121], v[62:65], v[174:177], v[118:121]
	s_nop 0
	v_mfma_i32_16x16x64_i8 v[118:121], v[58:61], v[178:181], v[118:121]
	v_mfma_i32_16x16x64_i8 v[114:117], v[54:57], v[174:177], v[114:117]
	s_nop 0
	v_mfma_i32_16x16x64_i8 v[114:117], v[50:53], v[178:181], v[114:117]
	v_mfma_i32_16x16x64_i8 v[102:105], v[62:65], v[182:185], v[102:105]
	s_nop 0
	v_mfma_i32_16x16x64_i8 v[102:105], v[58:61], v[186:189], v[102:105]
	v_mfma_i32_16x16x64_i8 v[98:101], v[54:57], v[182:185], v[98:101]
	s_nop 0
	v_mfma_i32_16x16x64_i8 v[98:101], v[50:53], v[186:189], v[98:101]
	v_mfma_i32_16x16x64_i8 v[86:89], v[62:65], v[190:193], v[86:89]
	s_nop 0
	v_mfma_i32_16x16x64_i8 v[86:89], v[58:61], v[236:239], v[86:89]
	v_mfma_i32_16x16x64_i8 v[82:85], v[54:57], v[190:193], v[82:85]
	s_nop 0
	v_mfma_i32_16x16x64_i8 v[82:85], v[50:53], v[236:239], v[82:85]
	s_barrier
	s_add_i32 s68, s60, s21
	s_add_i32 s69, s68, 0x2000
	v_lshl_add_u64 v[166:167], s[38:39], 0, v[202:203]
	s_mov_b32 m0, s68
	s_add_u32 s14, s38, 0x80000
	ds_read_b128 v[174:177], v226 offset:16384
	ds_read_b128 v[178:181], v226 offset:17408
	ds_read_b128 v[182:185], v226 offset:18432
	ds_read_b128 v[186:189], v226 offset:19456
	ds_read_b128 v[190:193], v226 offset:20480
	ds_read_b128 v[236:239], v226 offset:21504
	ds_read_b128 v[240:243], v226 offset:22528
	ds_read_b128 v[244:247], v226 offset:23552
	global_load_lds_dwordx4 v[166:167], off
	v_lshl_add_u64 v[168:169], s[38:39], 0, v[206:207]
	s_mov_b32 m0, s69
	s_addc_u32 s15, s39, 0
	s_add_i32 s70, s61, s21
	global_load_lds_dwordx4 v[168:169], off
	v_lshl_add_u64 v[170:171], s[14:15], 0, v[202:203]
	s_mov_b32 m0, s70
	s_add_i32 s71, s70, 0x2000
	global_load_lds_dwordx4 v[170:171], off
	v_lshl_add_u64 v[170:171], s[14:15], 0, v[206:207]
	s_mov_b32 m0, s71
	v_lshl_add_u64 v[172:173], s[40:41], 0, v[204:205]
	global_load_lds_dwordx4 v[170:171], off
	v_lshl_add_u64 v[170:171], s[40:41], 0, v[194:195]
	s_mov_b32 m0, s23
	s_nop 0
	global_load_lds_dwordx4 v[170:171], off
	s_mov_b32 m0, s42
	s_nop 0
	global_load_lds_dwordx4 v[172:173], off
	s_waitcnt vmcnt(8)
	s_waitcnt lgkmcnt(0)
	s_barrier
	s_waitcnt lgkmcnt(0)
	v_mfma_i32_16x16x64_i8 v[78:81], v[158:161], v[174:177], v[78:81]
	s_nop 0
	v_mfma_i32_16x16x64_i8 v[78:81], v[154:157], v[178:181], v[78:81]
	v_mfma_i32_16x16x64_i8 v[74:77], v[150:153], v[174:177], v[74:77]
	s_nop 0
	v_mfma_i32_16x16x64_i8 v[74:77], v[146:149], v[178:181], v[74:77]
	v_mfma_i32_16x16x64_i8 v[46:49], v[158:161], v[182:185], v[46:49]
	s_nop 0
	v_mfma_i32_16x16x64_i8 v[46:49], v[154:157], v[186:189], v[46:49]
	v_mfma_i32_16x16x64_i8 v[42:45], v[150:153], v[182:185], v[42:45]
	s_nop 0
	v_mfma_i32_16x16x64_i8 v[42:45], v[146:149], v[186:189], v[42:45]
	v_mfma_i32_16x16x64_i8 v[30:33], v[158:161], v[190:193], v[30:33]
	s_nop 0
	v_mfma_i32_16x16x64_i8 v[30:33], v[154:157], v[236:239], v[30:33]
	v_mfma_i32_16x16x64_i8 v[26:29], v[150:153], v[190:193], v[26:29]
	s_nop 0
	v_mfma_i32_16x16x64_i8 v[26:29], v[146:149], v[236:239], v[26:29]
	v_mfma_i32_16x16x64_i8 v[14:17], v[158:161], v[240:243], v[14:17]
	s_nop 0
	v_mfma_i32_16x16x64_i8 v[14:17], v[154:157], v[244:247], v[14:17]
	v_mfma_i32_16x16x64_i8 v[10:13], v[150:153], v[240:243], v[10:13]
	s_nop 0
	v_mfma_i32_16x16x64_i8 v[10:13], v[146:149], v[244:247], v[10:13]
	v_mfma_i32_16x16x64_i8 v[70:73], v[62:65], v[174:177], v[70:73]
	s_nop 0
	v_mfma_i32_16x16x64_i8 v[70:73], v[58:61], v[178:181], v[70:73]
	v_mfma_i32_16x16x64_i8 v[66:69], v[54:57], v[174:177], v[66:69]
	s_nop 0
	v_mfma_i32_16x16x64_i8 v[66:69], v[50:53], v[178:181], v[66:69]
	v_mfma_i32_16x16x64_i8 v[38:41], v[62:65], v[182:185], v[38:41]
	s_nop 0
	v_mfma_i32_16x16x64_i8 v[38:41], v[58:61], v[186:189], v[38:41]
	v_mfma_i32_16x16x64_i8 v[34:37], v[54:57], v[182:185], v[34:37]
	s_nop 0
	v_mfma_i32_16x16x64_i8 v[34:37], v[50:53], v[186:189], v[34:37]
	v_mfma_i32_16x16x64_i8 v[22:25], v[62:65], v[190:193], v[22:25]
	s_nop 0
	v_mfma_i32_16x16x64_i8 v[22:25], v[58:61], v[236:239], v[22:25]
	v_mfma_i32_16x16x64_i8 v[18:21], v[54:57], v[190:193], v[18:21]
	s_nop 0
	v_mfma_i32_16x16x64_i8 v[18:21], v[50:53], v[236:239], v[18:21]
	v_mfma_i32_16x16x64_i8 v[6:9], v[62:65], v[240:243], v[6:9]
	s_nop 0
	v_mfma_i32_16x16x64_i8 v[6:9], v[58:61], v[244:247], v[6:9]
	v_mfma_i32_16x16x64_i8 v[2:5], v[54:57], v[240:243], v[2:5]
	s_nop 0
	v_mfma_i32_16x16x64_i8 v[2:5], v[50:53], v[244:247], v[2:5]
	s_barrier
	s_add_i32 s72, 0, 0x18000
	v_add_u32_e32 v235, s72, v225
	s_add_i32 s74, 0, 0x1c000
	v_add_u32_e32 v236, s74, v225
	ds_read_b128 v[50:53], v235
	ds_read_b128 v[54:57], v235 offset:1024
	ds_read_b128 v[58:61], v235 offset:2048
	ds_read_b128 v[62:65], v235 offset:3072
	ds_read_b128 v[146:149], v236
	ds_read_b128 v[150:153], v236 offset:1024
	ds_read_b128 v[154:157], v236 offset:2048
	ds_read_b128 v[158:161], v236 offset:3072
	s_add_u32 s14, s40, 0x80000
	s_addc_u32 s15, s41, 0
	s_mov_b32 m0, s43
	v_lshl_add_u64 v[250:251], s[14:15], 0, v[194:195]
	ds_read_b128 v[174:177], v226 offset:32768
	ds_read_b128 v[178:181], v226 offset:33792
	ds_read_b128 v[182:185], v226 offset:34816
	ds_read_b128 v[186:189], v226 offset:35840
	ds_read_b128 v[190:193], v226 offset:36864
	ds_read_b128 v[238:241], v226 offset:37888
	ds_read_b128 v[242:245], v226 offset:38912
	ds_read_b128 v[246:249], v226 offset:39936
	global_load_lds_dwordx4 v[250:251], off
	v_lshl_add_u64 v[250:251], s[14:15], 0, v[204:205]
	s_mov_b32 m0, s44
	s_nop 0
	global_load_lds_dwordx4 v[250:251], off
	s_waitcnt vmcnt(8)
	s_waitcnt lgkmcnt(0)
	s_barrier
	s_waitcnt lgkmcnt(0)
	v_mfma_i32_16x16x64_i8 v[142:145], v[50:53], v[174:177], v[142:145]
	s_nop 0
	v_mfma_i32_16x16x64_i8 v[142:145], v[54:57], v[178:181], v[142:145]
	v_mfma_i32_16x16x64_i8 v[138:141], v[58:61], v[174:177], v[138:141]
	s_nop 0
	v_mfma_i32_16x16x64_i8 v[138:141], v[62:65], v[178:181], v[138:141]
	v_mfma_i32_16x16x64_i8 v[126:129], v[50:53], v[182:185], v[126:129]
	s_nop 0
	v_mfma_i32_16x16x64_i8 v[126:129], v[54:57], v[186:189], v[126:129]
	v_mfma_i32_16x16x64_i8 v[122:125], v[58:61], v[182:185], v[122:125]
	s_nop 0
	v_mfma_i32_16x16x64_i8 v[122:125], v[62:65], v[186:189], v[122:125]
	v_mfma_i32_16x16x64_i8 v[110:113], v[50:53], v[190:193], v[110:113]
	s_nop 0
	v_mfma_i32_16x16x64_i8 v[110:113], v[54:57], v[238:241], v[110:113]
	v_mfma_i32_16x16x64_i8 v[106:109], v[58:61], v[190:193], v[106:109]
	s_nop 0
	v_mfma_i32_16x16x64_i8 v[106:109], v[62:65], v[238:241], v[106:109]
	v_mfma_i32_16x16x64_i8 v[94:97], v[50:53], v[242:245], v[94:97]
	s_nop 0
	v_mfma_i32_16x16x64_i8 v[94:97], v[54:57], v[246:249], v[94:97]
	v_mfma_i32_16x16x64_i8 v[90:93], v[58:61], v[242:245], v[90:93]
	s_nop 0
	v_mfma_i32_16x16x64_i8 v[90:93], v[62:65], v[246:249], v[90:93]
	v_mfma_i32_16x16x64_i8 v[134:137], v[146:149], v[174:177], v[134:137]
	s_nop 0
	v_mfma_i32_16x16x64_i8 v[134:137], v[150:153], v[178:181], v[134:137]
	v_mfma_i32_16x16x64_i8 v[130:133], v[154:157], v[174:177], v[130:133]
	s_nop 0
	v_mfma_i32_16x16x64_i8 v[130:133], v[158:161], v[178:181], v[130:133]
	v_mfma_i32_16x16x64_i8 v[118:121], v[146:149], v[182:185], v[118:121]
	s_nop 0
	v_mfma_i32_16x16x64_i8 v[118:121], v[150:153], v[186:189], v[118:121]
	v_mfma_i32_16x16x64_i8 v[114:117], v[154:157], v[182:185], v[114:117]
	s_nop 0
	v_mfma_i32_16x16x64_i8 v[114:117], v[158:161], v[186:189], v[114:117]
	v_mfma_i32_16x16x64_i8 v[102:105], v[146:149], v[190:193], v[102:105]
	s_nop 0
	v_mfma_i32_16x16x64_i8 v[102:105], v[150:153], v[238:241], v[102:105]
	v_mfma_i32_16x16x64_i8 v[98:101], v[154:157], v[190:193], v[98:101]
	s_nop 0
	v_mfma_i32_16x16x64_i8 v[98:101], v[158:161], v[238:241], v[98:101]
	v_mfma_i32_16x16x64_i8 v[86:89], v[146:149], v[242:245], v[86:89]
	s_nop 0
	v_mfma_i32_16x16x64_i8 v[86:89], v[150:153], v[246:249], v[86:89]
	v_mfma_i32_16x16x64_i8 v[82:85], v[154:157], v[242:245], v[82:85]
	s_nop 0
	v_mfma_i32_16x16x64_i8 v[82:85], v[158:161], v[246:249], v[82:85]
	s_barrier
	s_add_i32 s72, s72, s21
	s_add_i32 s73, s72, 0x2000
	v_lshl_add_u64 v[166:167], v[166:167], 0, s[6:7]
	s_mov_b32 m0, s72
	s_add_u32 s14, s38, 0x80080
	ds_read_b128 v[174:177], v226 offset:49152
	ds_read_b128 v[178:181], v226 offset:50176
	ds_read_b128 v[182:185], v226 offset:51200
	ds_read_b128 v[186:189], v226 offset:52224
	ds_read_b128 v[190:193], v226 offset:53248
	ds_read_b128 v[238:241], v226 offset:54272
	ds_read_b128 v[242:245], v226 offset:55296
	ds_read_b128 v[246:249], v226 offset:56320
	global_load_lds_dwordx4 v[166:167], off
	v_lshl_add_u64 v[166:167], v[168:169], 0, s[6:7]
	s_mov_b32 m0, s73
	s_addc_u32 s15, s39, 0
	s_add_i32 s74, s74, s21
	global_load_lds_dwordx4 v[166:167], off
	v_lshl_add_u64 v[166:167], s[14:15], 0, v[202:203]
	s_mov_b32 m0, s74
	s_add_i32 s75, s74, 0x2000
	global_load_lds_dwordx4 v[166:167], off
	v_lshl_add_u64 v[166:167], s[14:15], 0, v[206:207]
	s_mov_b32 m0, s75
	s_nop 0
	global_load_lds_dwordx4 v[166:167], off
	v_lshl_add_u64 v[166:167], v[170:171], 0, s[6:7]
	s_mov_b32 m0, s51
	s_nop 0
	global_load_lds_dwordx4 v[166:167], off
	v_lshl_add_u64 v[166:167], v[172:173], 0, s[6:7]
	s_mov_b32 m0, s53
	s_nop 0
	global_load_lds_dwordx4 v[166:167], off
	s_waitcnt vmcnt(8)
	s_waitcnt lgkmcnt(0)
	s_barrier
	s_waitcnt lgkmcnt(0)
	v_mfma_i32_16x16x64_i8 v[78:81], v[50:53], v[174:177], v[78:81]
	s_nop 0
	v_mfma_i32_16x16x64_i8 v[78:81], v[54:57], v[178:181], v[78:81]
	v_mfma_i32_16x16x64_i8 v[74:77], v[58:61], v[174:177], v[74:77]
	s_nop 0
	v_mfma_i32_16x16x64_i8 v[74:77], v[62:65], v[178:181], v[74:77]
	v_mfma_i32_16x16x64_i8 v[46:49], v[50:53], v[182:185], v[46:49]
	s_nop 0
	v_mfma_i32_16x16x64_i8 v[46:49], v[54:57], v[186:189], v[46:49]
	v_mfma_i32_16x16x64_i8 v[42:45], v[58:61], v[182:185], v[42:45]
	s_nop 0
	v_mfma_i32_16x16x64_i8 v[42:45], v[62:65], v[186:189], v[42:45]
	v_mfma_i32_16x16x64_i8 v[30:33], v[50:53], v[190:193], v[30:33]
	s_nop 0
	v_mfma_i32_16x16x64_i8 v[30:33], v[54:57], v[238:241], v[30:33]
	v_mfma_i32_16x16x64_i8 v[26:29], v[58:61], v[190:193], v[26:29]
	s_nop 0
	v_mfma_i32_16x16x64_i8 v[26:29], v[62:65], v[238:241], v[26:29]
	v_mfma_i32_16x16x64_i8 v[14:17], v[50:53], v[242:245], v[14:17]
	s_nop 0
	v_mfma_i32_16x16x64_i8 v[14:17], v[54:57], v[246:249], v[14:17]
	v_mfma_i32_16x16x64_i8 v[10:13], v[58:61], v[242:245], v[10:13]
	s_nop 0
	v_mfma_i32_16x16x64_i8 v[10:13], v[62:65], v[246:249], v[10:13]
	v_mfma_i32_16x16x64_i8 v[70:73], v[146:149], v[174:177], v[70:73]
	s_nop 0
	v_mfma_i32_16x16x64_i8 v[70:73], v[150:153], v[178:181], v[70:73]
	v_mfma_i32_16x16x64_i8 v[66:69], v[154:157], v[174:177], v[66:69]
	s_nop 0
	v_mfma_i32_16x16x64_i8 v[66:69], v[158:161], v[178:181], v[66:69]
	v_mfma_i32_16x16x64_i8 v[38:41], v[146:149], v[182:185], v[38:41]
	s_nop 0
	v_mfma_i32_16x16x64_i8 v[38:41], v[150:153], v[186:189], v[38:41]
	v_mfma_i32_16x16x64_i8 v[34:37], v[154:157], v[182:185], v[34:37]
	s_nop 0
	v_mfma_i32_16x16x64_i8 v[34:37], v[158:161], v[186:189], v[34:37]
	v_mfma_i32_16x16x64_i8 v[22:25], v[146:149], v[190:193], v[22:25]
	s_nop 0
	v_mfma_i32_16x16x64_i8 v[22:25], v[150:153], v[238:241], v[22:25]
	v_mfma_i32_16x16x64_i8 v[18:21], v[154:157], v[190:193], v[18:21]
	s_nop 0
	v_mfma_i32_16x16x64_i8 v[18:21], v[158:161], v[238:241], v[18:21]
	v_mfma_i32_16x16x64_i8 v[6:9], v[146:149], v[242:245], v[6:9]
	s_nop 0
	v_mfma_i32_16x16x64_i8 v[6:9], v[150:153], v[246:249], v[6:9]
	v_mfma_i32_16x16x64_i8 v[2:5], v[154:157], v[242:245], v[2:5]
	s_nop 0
	v_mfma_i32_16x16x64_i8 v[2:5], v[158:161], v[246:249], v[2:5]
	s_barrier
	s_add_i32 s3, s3, 2
	s_add_u32 s34, s34, 0x100
	s_addc_u32 s35, s35, 0
	s_cmp_gt_u32 s3, 29
	s_cbranch_scc0 .LBB0_734
	s_nop 15
	s_nop 15
	s_and_b64 vcc, exec, s[8:9]
	s_cbranch_vccz .LBB0_737
	s_barrier

.LBB0_740:
	ds_read_b128 v[158:161], v227
	ds_read_b128 v[154:157], v227 offset:1024
	ds_read_b128 v[150:153], v227 offset:2048
	ds_read_b128 v[146:149], v227 offset:3072
	ds_read_b128 v[62:65], v233
	ds_read_b128 v[58:61], v233 offset:1024
	ds_read_b128 v[54:57], v233 offset:2048
	ds_read_b128 v[50:53], v233 offset:3072
	s_add_u32 s36, s38, 0xfff80080
	s_addc_u32 s37, s39, -1
	s_cmp_eq_u32 s33, 28
	s_cselect_b32 s41, s1, s37
	s_cselect_b32 s40, s0, s36
	s_cselect_b32 s37, s15, s29
	s_cselect_b32 s36, s14, s25
	s_mov_b32 m0, s66
	v_lshl_add_u64 v[238:239], s[38:39], 0, v[208:209]
	ds_read_b128 v[162:165], v226
	ds_read_b128 v[166:169], v226 offset:1024
	ds_read_b128 v[170:173], v226 offset:2048
	ds_read_b128 v[174:177], v226 offset:3072
	ds_read_b128 v[178:181], v226 offset:4096
	ds_read_b128 v[182:185], v226 offset:5120
	ds_read_b128 v[186:189], v226 offset:6144
	ds_read_b128 v[190:193], v226 offset:7168
	global_load_lds_dwordx4 v[238:239], off
	v_lshl_add_u64 v[238:239], s[38:39], 0, v[212:213]
	s_mov_b32 m0, s67
	s_nop 0
	global_load_lds_dwordx4 v[238:239], off
	s_waitcnt vmcnt(8)
	s_waitcnt lgkmcnt(0)
	s_barrier
	s_waitcnt lgkmcnt(0)
	v_mfma_i32_16x16x64_i8 v[142:145], v[158:161], v[162:165], v[142:145]
	s_nop 0
	v_mfma_i32_16x16x64_i8 v[142:145], v[154:157], v[166:169], v[142:145]
	v_mfma_i32_16x16x64_i8 v[138:141], v[150:153], v[162:165], v[138:141]
	s_nop 0
	v_mfma_i32_16x16x64_i8 v[138:141], v[146:149], v[166:169], v[138:141]
	v_mfma_i32_16x16x64_i8 v[126:129], v[158:161], v[170:173], v[126:129]
	s_nop 0
	v_mfma_i32_16x16x64_i8 v[126:129], v[154:157], v[174:177], v[126:129]
	v_mfma_i32_16x16x64_i8 v[122:125], v[150:153], v[170:173], v[122:125]
	s_nop 0
	v_mfma_i32_16x16x64_i8 v[122:125], v[146:149], v[174:177], v[122:125]
	v_mfma_i32_16x16x64_i8 v[110:113], v[158:161], v[178:181], v[110:113]
	s_nop 0
	v_mfma_i32_16x16x64_i8 v[110:113], v[154:157], v[182:185], v[110:113]
	v_mfma_i32_16x16x64_i8 v[106:109], v[150:153], v[178:181], v[106:109]
	s_nop 0
	v_mfma_i32_16x16x64_i8 v[106:109], v[146:149], v[182:185], v[106:109]
	v_mfma_i32_16x16x64_i8 v[94:97], v[158:161], v[186:189], v[94:97]
	s_nop 0
	v_mfma_i32_16x16x64_i8 v[94:97], v[154:157], v[190:193], v[94:97]
	v_mfma_i32_16x16x64_i8 v[90:93], v[150:153], v[186:189], v[90:93]
	s_nop 0
	v_mfma_i32_16x16x64_i8 v[90:93], v[146:149], v[190:193], v[90:93]
	v_mfma_i32_16x16x64_i8 v[134:137], v[62:65], v[162:165], v[134:137]
	s_nop 0
	v_mfma_i32_16x16x64_i8 v[134:137], v[58:61], v[166:169], v[134:137]
	v_mfma_i32_16x16x64_i8 v[130:133], v[54:57], v[162:165], v[130:133]
	s_nop 0
	v_mfma_i32_16x16x64_i8 v[130:133], v[50:53], v[166:169], v[130:133]
	v_mfma_i32_16x16x64_i8 v[118:121], v[62:65], v[170:173], v[118:121]
	s_nop 0
	v_mfma_i32_16x16x64_i8 v[118:121], v[58:61], v[174:177], v[118:121]
	v_mfma_i32_16x16x64_i8 v[114:117], v[54:57], v[170:173], v[114:117]
	s_nop 0
	v_mfma_i32_16x16x64_i8 v[114:117], v[50:53], v[174:177], v[114:117]
	v_mfma_i32_16x16x64_i8 v[102:105], v[62:65], v[178:181], v[102:105]
	s_nop 0
	v_mfma_i32_16x16x64_i8 v[102:105], v[58:61], v[182:185], v[102:105]
	v_mfma_i32_16x16x64_i8 v[98:101], v[54:57], v[178:181], v[98:101]
	s_nop 0
	v_mfma_i32_16x16x64_i8 v[98:101], v[50:53], v[182:185], v[98:101]
	v_mfma_i32_16x16x64_i8 v[86:89], v[62:65], v[186:189], v[86:89]
	s_nop 0
	v_mfma_i32_16x16x64_i8 v[86:89], v[58:61], v[190:193], v[86:89]
	v_mfma_i32_16x16x64_i8 v[82:85], v[54:57], v[186:189], v[82:85]
	s_nop 0
	v_mfma_i32_16x16x64_i8 v[82:85], v[50:53], v[190:193], v[82:85]
	s_barrier
	s_mov_b32 m0, s68
	v_lshl_add_u64 v[162:163], s[36:37], 0, v[202:203]
	s_add_u32 s80, s36, 0x80000
	ds_read_b128 v[170:173], v226 offset:16384
	ds_read_b128 v[174:177], v226 offset:17408
	ds_read_b128 v[178:181], v226 offset:18432
	ds_read_b128 v[182:185], v226 offset:19456
	ds_read_b128 v[186:189], v226 offset:20480
	ds_read_b128 v[190:193], v226 offset:21504
	ds_read_b128 v[238:241], v226 offset:22528
	ds_read_b128 v[242:245], v226 offset:23552
	global_load_lds_dwordx4 v[162:163], off
	v_lshl_add_u64 v[164:165], s[36:37], 0, v[206:207]
	s_mov_b32 m0, s69
	s_addc_u32 s81, s37, 0
	global_load_lds_dwordx4 v[164:165], off
	v_lshl_add_u64 v[166:167], s[80:81], 0, v[202:203]
	s_mov_b32 m0, s70
	v_lshl_add_u64 v[168:169], s[40:41], 0, v[204:205]
	global_load_lds_dwordx4 v[166:167], off
	v_lshl_add_u64 v[166:167], s[80:81], 0, v[206:207]
	s_mov_b32 m0, s71
	s_nop 0
	global_load_lds_dwordx4 v[166:167], off
	v_lshl_add_u64 v[166:167], s[40:41], 0, v[194:195]
	s_mov_b32 m0, s23
	s_nop 0
	global_load_lds_dwordx4 v[166:167], off
	s_mov_b32 m0, s42
	s_nop 0
	global_load_lds_dwordx4 v[168:169], off
	s_waitcnt vmcnt(8)
	s_waitcnt lgkmcnt(0)
	s_barrier
	s_waitcnt lgkmcnt(0)
	v_mfma_i32_16x16x64_i8 v[78:81], v[158:161], v[170:173], v[78:81]
	s_nop 0
	v_mfma_i32_16x16x64_i8 v[78:81], v[154:157], v[174:177], v[78:81]
	v_mfma_i32_16x16x64_i8 v[74:77], v[150:153], v[170:173], v[74:77]
	s_nop 0
	v_mfma_i32_16x16x64_i8 v[74:77], v[146:149], v[174:177], v[74:77]
	v_mfma_i32_16x16x64_i8 v[46:49], v[158:161], v[178:181], v[46:49]
	s_nop 0
	v_mfma_i32_16x16x64_i8 v[46:49], v[154:157], v[182:185], v[46:49]
	v_mfma_i32_16x16x64_i8 v[42:45], v[150:153], v[178:181], v[42:45]
	s_nop 0
	v_mfma_i32_16x16x64_i8 v[42:45], v[146:149], v[182:185], v[42:45]
	v_mfma_i32_16x16x64_i8 v[30:33], v[158:161], v[186:189], v[30:33]
	s_nop 0
	v_mfma_i32_16x16x64_i8 v[30:33], v[154:157], v[190:193], v[30:33]
	v_mfma_i32_16x16x64_i8 v[26:29], v[150:153], v[186:189], v[26:29]
	s_nop 0
	v_mfma_i32_16x16x64_i8 v[26:29], v[146:149], v[190:193], v[26:29]
	v_mfma_i32_16x16x64_i8 v[14:17], v[158:161], v[238:241], v[14:17]
	s_nop 0
	v_mfma_i32_16x16x64_i8 v[14:17], v[154:157], v[242:245], v[14:17]
	v_mfma_i32_16x16x64_i8 v[10:13], v[150:153], v[238:241], v[10:13]
	s_nop 0
	v_mfma_i32_16x16x64_i8 v[10:13], v[146:149], v[242:245], v[10:13]
	v_mfma_i32_16x16x64_i8 v[70:73], v[62:65], v[170:173], v[70:73]
	s_nop 0
	v_mfma_i32_16x16x64_i8 v[70:73], v[58:61], v[174:177], v[70:73]
	v_mfma_i32_16x16x64_i8 v[66:69], v[54:57], v[170:173], v[66:69]
	s_nop 0
	v_mfma_i32_16x16x64_i8 v[66:69], v[50:53], v[174:177], v[66:69]
	v_mfma_i32_16x16x64_i8 v[38:41], v[62:65], v[178:181], v[38:41]
	s_nop 0
	v_mfma_i32_16x16x64_i8 v[38:41], v[58:61], v[182:185], v[38:41]
	v_mfma_i32_16x16x64_i8 v[34:37], v[54:57], v[178:181], v[34:37]
	s_nop 0
	v_mfma_i32_16x16x64_i8 v[34:37], v[50:53], v[182:185], v[34:37]
	v_mfma_i32_16x16x64_i8 v[22:25], v[62:65], v[186:189], v[22:25]
	s_nop 0
	v_mfma_i32_16x16x64_i8 v[22:25], v[58:61], v[190:193], v[22:25]
	v_mfma_i32_16x16x64_i8 v[18:21], v[54:57], v[186:189], v[18:21]
	s_nop 0
	v_mfma_i32_16x16x64_i8 v[18:21], v[50:53], v[190:193], v[18:21]
	v_mfma_i32_16x16x64_i8 v[6:9], v[62:65], v[238:241], v[6:9]
	s_nop 0
	v_mfma_i32_16x16x64_i8 v[6:9], v[58:61], v[242:245], v[6:9]
	v_mfma_i32_16x16x64_i8 v[2:5], v[54:57], v[238:241], v[2:5]
	s_nop 0
	v_mfma_i32_16x16x64_i8 v[2:5], v[50:53], v[242:245], v[2:5]
	s_barrier
	ds_read_b128 v[50:53], v235
	ds_read_b128 v[54:57], v235 offset:1024
	ds_read_b128 v[58:61], v235 offset:2048
	ds_read_b128 v[62:65], v235 offset:3072
	ds_read_b128 v[146:149], v236
	ds_read_b128 v[150:153], v236 offset:1024
	ds_read_b128 v[154:157], v236 offset:2048
	ds_read_b128 v[158:161], v236 offset:3072
	s_add_u32 s40, s40, 0x80000
	s_addc_u32 s41, s41, 0
	s_mov_b32 m0, s43
	v_lshl_add_u64 v[246:247], s[40:41], 0, v[194:195]
	ds_read_b128 v[170:173], v226 offset:32768
	ds_read_b128 v[174:177], v226 offset:33792
	ds_read_b128 v[178:181], v226 offset:34816
	ds_read_b128 v[182:185], v226 offset:35840
	ds_read_b128 v[186:189], v226 offset:36864
	ds_read_b128 v[190:193], v226 offset:37888
	ds_read_b128 v[238:241], v226 offset:38912
	ds_read_b128 v[242:245], v226 offset:39936
	global_load_lds_dwordx4 v[246:247], off
	v_lshl_add_u64 v[246:247], s[40:41], 0, v[204:205]
	s_mov_b32 m0, s44
	s_nop 0
	global_load_lds_dwordx4 v[246:247], off
	s_waitcnt vmcnt(8)
	s_waitcnt lgkmcnt(0)
	s_barrier
	s_waitcnt lgkmcnt(0)
	v_mfma_i32_16x16x64_i8 v[142:145], v[50:53], v[170:173], v[142:145]
	s_nop 0
	v_mfma_i32_16x16x64_i8 v[142:145], v[54:57], v[174:177], v[142:145]
	v_mfma_i32_16x16x64_i8 v[138:141], v[58:61], v[170:173], v[138:141]
	s_nop 0
	v_mfma_i32_16x16x64_i8 v[138:141], v[62:65], v[174:177], v[138:141]
	v_mfma_i32_16x16x64_i8 v[126:129], v[50:53], v[178:181], v[126:129]
	s_nop 0
	v_mfma_i32_16x16x64_i8 v[126:129], v[54:57], v[182:185], v[126:129]
	v_mfma_i32_16x16x64_i8 v[122:125], v[58:61], v[178:181], v[122:125]
	s_nop 0
	v_mfma_i32_16x16x64_i8 v[122:125], v[62:65], v[182:185], v[122:125]
	v_mfma_i32_16x16x64_i8 v[110:113], v[50:53], v[186:189], v[110:113]
	s_nop 0
	v_mfma_i32_16x16x64_i8 v[110:113], v[54:57], v[190:193], v[110:113]
	v_mfma_i32_16x16x64_i8 v[106:109], v[58:61], v[186:189], v[106:109]
	s_nop 0
	v_mfma_i32_16x16x64_i8 v[106:109], v[62:65], v[190:193], v[106:109]
	v_mfma_i32_16x16x64_i8 v[94:97], v[50:53], v[238:241], v[94:97]
	s_nop 0
	v_mfma_i32_16x16x64_i8 v[94:97], v[54:57], v[242:245], v[94:97]
	v_mfma_i32_16x16x64_i8 v[90:93], v[58:61], v[238:241], v[90:93]
	s_nop 0
	v_mfma_i32_16x16x64_i8 v[90:93], v[62:65], v[242:245], v[90:93]
	v_mfma_i32_16x16x64_i8 v[134:137], v[146:149], v[170:173], v[134:137]
	s_nop 0
	v_mfma_i32_16x16x64_i8 v[134:137], v[150:153], v[174:177], v[134:137]
	v_mfma_i32_16x16x64_i8 v[130:133], v[154:157], v[170:173], v[130:133]
	s_nop 0
	v_mfma_i32_16x16x64_i8 v[130:133], v[158:161], v[174:177], v[130:133]
	v_mfma_i32_16x16x64_i8 v[118:121], v[146:149], v[178:181], v[118:121]
	s_nop 0
	v_mfma_i32_16x16x64_i8 v[118:121], v[150:153], v[182:185], v[118:121]
	v_mfma_i32_16x16x64_i8 v[114:117], v[154:157], v[178:181], v[114:117]
	s_nop 0
	v_mfma_i32_16x16x64_i8 v[114:117], v[158:161], v[182:185], v[114:117]
	v_mfma_i32_16x16x64_i8 v[102:105], v[146:149], v[186:189], v[102:105]
	s_nop 0
	v_mfma_i32_16x16x64_i8 v[102:105], v[150:153], v[190:193], v[102:105]
	v_mfma_i32_16x16x64_i8 v[98:101], v[154:157], v[186:189], v[98:101]
	s_nop 0
	v_mfma_i32_16x16x64_i8 v[98:101], v[158:161], v[190:193], v[98:101]
	v_mfma_i32_16x16x64_i8 v[86:89], v[146:149], v[238:241], v[86:89]
	s_nop 0
	v_mfma_i32_16x16x64_i8 v[86:89], v[150:153], v[242:245], v[86:89]
	v_mfma_i32_16x16x64_i8 v[82:85], v[154:157], v[238:241], v[82:85]
	s_nop 0
	v_mfma_i32_16x16x64_i8 v[82:85], v[158:161], v[242:245], v[82:85]
	s_barrier
	s_mov_b32 m0, s72
	v_lshl_add_u64 v[162:163], v[162:163], 0, s[6:7]
	s_add_u32 s36, s36, 0x80080
	ds_read_b128 v[170:173], v226 offset:49152
	ds_read_b128 v[174:177], v226 offset:50176
	ds_read_b128 v[178:181], v226 offset:51200
	ds_read_b128 v[182:185], v226 offset:52224
	ds_read_b128 v[186:189], v226 offset:53248
	ds_read_b128 v[190:193], v226 offset:54272
	ds_read_b128 v[238:241], v226 offset:55296
	ds_read_b128 v[242:245], v226 offset:56320
	global_load_lds_dwordx4 v[162:163], off
	v_lshl_add_u64 v[162:163], v[164:165], 0, s[6:7]
	s_mov_b32 m0, s73
	s_addc_u32 s37, s37, 0
	global_load_lds_dwordx4 v[162:163], off
	v_lshl_add_u64 v[162:163], s[36:37], 0, v[202:203]
	s_mov_b32 m0, s74
	s_nop 0
	global_load_lds_dwordx4 v[162:163], off
	v_lshl_add_u64 v[162:163], s[36:37], 0, v[206:207]
	s_mov_b32 m0, s75
	s_nop 0
	global_load_lds_dwordx4 v[162:163], off
	v_lshl_add_u64 v[162:163], v[166:167], 0, s[6:7]
	s_mov_b32 m0, s51
	s_nop 0
	global_load_lds_dwordx4 v[162:163], off
	v_lshl_add_u64 v[162:163], v[168:169], 0, s[6:7]
	s_mov_b32 m0, s53
	s_nop 0
	global_load_lds_dwordx4 v[162:163], off
	s_waitcnt vmcnt(8)
	s_waitcnt lgkmcnt(0)
	s_barrier
	s_waitcnt lgkmcnt(0)
	v_mfma_i32_16x16x64_i8 v[78:81], v[50:53], v[170:173], v[78:81]
	s_nop 0
	v_mfma_i32_16x16x64_i8 v[78:81], v[54:57], v[174:177], v[78:81]
	v_mfma_i32_16x16x64_i8 v[74:77], v[58:61], v[170:173], v[74:77]
	s_nop 0
	v_mfma_i32_16x16x64_i8 v[74:77], v[62:65], v[174:177], v[74:77]
	v_mfma_i32_16x16x64_i8 v[46:49], v[50:53], v[178:181], v[46:49]
	s_nop 0
	v_mfma_i32_16x16x64_i8 v[46:49], v[54:57], v[182:185], v[46:49]
	v_mfma_i32_16x16x64_i8 v[42:45], v[58:61], v[178:181], v[42:45]
	s_nop 0
	v_mfma_i32_16x16x64_i8 v[42:45], v[62:65], v[182:185], v[42:45]
	v_mfma_i32_16x16x64_i8 v[30:33], v[50:53], v[186:189], v[30:33]
	s_nop 0
	v_mfma_i32_16x16x64_i8 v[30:33], v[54:57], v[190:193], v[30:33]
	v_mfma_i32_16x16x64_i8 v[26:29], v[58:61], v[186:189], v[26:29]
	s_nop 0
	v_mfma_i32_16x16x64_i8 v[26:29], v[62:65], v[190:193], v[26:29]
	v_mfma_i32_16x16x64_i8 v[14:17], v[50:53], v[238:241], v[14:17]
	s_nop 0
	v_mfma_i32_16x16x64_i8 v[14:17], v[54:57], v[242:245], v[14:17]
	v_mfma_i32_16x16x64_i8 v[10:13], v[58:61], v[238:241], v[10:13]
	s_nop 0
	v_mfma_i32_16x16x64_i8 v[10:13], v[62:65], v[242:245], v[10:13]
	v_mfma_i32_16x16x64_i8 v[70:73], v[146:149], v[170:173], v[70:73]
	s_nop 0
	v_mfma_i32_16x16x64_i8 v[70:73], v[150:153], v[174:177], v[70:73]
	v_mfma_i32_16x16x64_i8 v[66:69], v[154:157], v[170:173], v[66:69]
	s_nop 0
	v_mfma_i32_16x16x64_i8 v[66:69], v[158:161], v[174:177], v[66:69]
	v_mfma_i32_16x16x64_i8 v[38:41], v[146:149], v[178:181], v[38:41]
	s_nop 0
	v_mfma_i32_16x16x64_i8 v[38:41], v[150:153], v[182:185], v[38:41]
	v_mfma_i32_16x16x64_i8 v[34:37], v[154:157], v[178:181], v[34:37]
	s_nop 0
	v_mfma_i32_16x16x64_i8 v[34:37], v[158:161], v[182:185], v[34:37]
	v_mfma_i32_16x16x64_i8 v[22:25], v[146:149], v[186:189], v[22:25]
	s_nop 0
	v_mfma_i32_16x16x64_i8 v[22:25], v[150:153], v[190:193], v[22:25]
	v_mfma_i32_16x16x64_i8 v[18:21], v[154:157], v[186:189], v[18:21]
	s_nop 0
	v_mfma_i32_16x16x64_i8 v[18:21], v[158:161], v[190:193], v[18:21]
	v_mfma_i32_16x16x64_i8 v[6:9], v[146:149], v[238:241], v[6:9]
	s_nop 0
	v_mfma_i32_16x16x64_i8 v[6:9], v[150:153], v[242:245], v[6:9]
	v_mfma_i32_16x16x64_i8 v[2:5], v[154:157], v[238:241], v[2:5]
	s_nop 0
	v_mfma_i32_16x16x64_i8 v[2:5], v[158:161], v[242:245], v[2:5]
	s_barrier
	s_add_i32 s33, s33, 2
	s_add_u32 s38, s38, 0x100
	s_addc_u32 s39, s39, 0
	s_add_u32 s25, s25, 0x100
	s_addc_u32 s29, s29, 0
	s_cmp_gt_u32 s33, 29
	s_cbranch_scc0 .LBB0_740
	s_nop 15
	s_nop 15
	s_and_b64 vcc, exec, s[8:9]
	s_cbranch_vccz .LBB0_743
	s_barrier

.LBB0_746:
	ds_read_b128 v[158:161], v227
	ds_read_b128 v[154:157], v227 offset:1024
	ds_read_b128 v[150:153], v227 offset:2048
	ds_read_b128 v[146:149], v227 offset:3072
	ds_read_b128 v[142:145], v233
	ds_read_b128 v[138:141], v233 offset:1024
	ds_read_b128 v[134:137], v233 offset:2048
	ds_read_b128 v[130:133], v233 offset:3072
	s_add_u32 s38, s29, s36
	s_addc_u32 s39, s33, s37
	s_add_u32 s38, s38, 0x3d000100
	s_addc_u32 s39, s39, 0
	s_add_u32 s81, s25, s36
	s_addc_u32 s82, s79, s37
	s_cmpk_eq_i32 s36, 0x700
	s_cselect_b32 s41, s1, s39
	s_cselect_b32 s40, s0, s38
	s_cselect_b32 s39, s15, s82
	s_cselect_b32 s38, s14, s81
	s_mov_b32 m0, s66
	v_lshl_add_u64 v[242:243], v[162:163], 0, s[36:37]
	ds_read_b128 v[166:169], v226
	ds_read_b128 v[170:173], v226 offset:1024
	ds_read_b128 v[174:177], v226 offset:2048
	ds_read_b128 v[178:181], v226 offset:3072
	ds_read_b128 v[182:185], v226 offset:4096
	ds_read_b128 v[186:189], v226 offset:5120
	ds_read_b128 v[190:193], v226 offset:6144
	ds_read_b128 v[238:241], v226 offset:7168
	global_load_lds_dwordx4 v[242:243], off
	v_lshl_add_u64 v[242:243], v[164:165], 0, s[36:37]
	s_mov_b32 m0, s67
	s_nop 0
	global_load_lds_dwordx4 v[242:243], off
	s_waitcnt vmcnt(8)
	s_waitcnt lgkmcnt(0)
	s_barrier
	s_waitcnt lgkmcnt(0)
	v_mfma_i32_16x16x64_i8 v[30:33], v[158:161], v[166:169], v[30:33]
	s_nop 0
	v_mfma_i32_16x16x64_i8 v[30:33], v[154:157], v[170:173], v[30:33]
	v_mfma_i32_16x16x64_i8 v[26:29], v[150:153], v[166:169], v[26:29]
	s_nop 0
	v_mfma_i32_16x16x64_i8 v[26:29], v[146:149], v[170:173], v[26:29]
	v_mfma_i32_16x16x64_i8 v[46:49], v[158:161], v[174:177], v[46:49]
	s_nop 0
	v_mfma_i32_16x16x64_i8 v[46:49], v[154:157], v[178:181], v[46:49]
	v_mfma_i32_16x16x64_i8 v[42:45], v[150:153], v[174:177], v[42:45]
	s_nop 0
	v_mfma_i32_16x16x64_i8 v[42:45], v[146:149], v[178:181], v[42:45]
	v_mfma_i32_16x16x64_i8 v[74:77], v[158:161], v[182:185], v[74:77]
	s_nop 0
	v_mfma_i32_16x16x64_i8 v[74:77], v[154:157], v[186:189], v[74:77]
	v_mfma_i32_16x16x64_i8 v[70:73], v[150:153], v[182:185], v[70:73]
	s_nop 0
	v_mfma_i32_16x16x64_i8 v[70:73], v[146:149], v[186:189], v[70:73]
	v_mfma_i32_16x16x64_i8 v[94:97], v[158:161], v[190:193], v[94:97]
	s_nop 0
	v_mfma_i32_16x16x64_i8 v[94:97], v[154:157], v[238:241], v[94:97]
	v_mfma_i32_16x16x64_i8 v[90:93], v[150:153], v[190:193], v[90:93]
	s_nop 0
	v_mfma_i32_16x16x64_i8 v[90:93], v[146:149], v[238:241], v[90:93]
	v_mfma_i32_16x16x64_i8 v[38:41], v[142:145], v[166:169], v[38:41]
	s_nop 0
	v_mfma_i32_16x16x64_i8 v[38:41], v[138:141], v[170:173], v[38:41]
	v_mfma_i32_16x16x64_i8 v[34:37], v[134:137], v[166:169], v[34:37]
	s_nop 0
	v_mfma_i32_16x16x64_i8 v[34:37], v[130:133], v[170:173], v[34:37]
	v_mfma_i32_16x16x64_i8 v[58:61], v[142:145], v[174:177], v[58:61]
	s_nop 0
	v_mfma_i32_16x16x64_i8 v[58:61], v[138:141], v[178:181], v[58:61]
	v_mfma_i32_16x16x64_i8 v[54:57], v[134:137], v[174:177], v[54:57]
	s_nop 0
	v_mfma_i32_16x16x64_i8 v[54:57], v[130:133], v[178:181], v[54:57]
	v_mfma_i32_16x16x64_i8 v[86:89], v[142:145], v[182:185], v[86:89]
	s_nop 0
	v_mfma_i32_16x16x64_i8 v[86:89], v[138:141], v[186:189], v[86:89]
	v_mfma_i32_16x16x64_i8 v[82:85], v[134:137], v[182:185], v[82:85]
	s_nop 0
	v_mfma_i32_16x16x64_i8 v[82:85], v[130:133], v[186:189], v[82:85]
	v_mfma_i32_16x16x64_i8 v[102:105], v[142:145], v[190:193], v[102:105]
	s_nop 0
	v_mfma_i32_16x16x64_i8 v[102:105], v[138:141], v[238:241], v[102:105]
	v_mfma_i32_16x16x64_i8 v[98:101], v[134:137], v[190:193], v[98:101]
	s_nop 0
	v_mfma_i32_16x16x64_i8 v[98:101], v[130:133], v[238:241], v[98:101]
	s_barrier
	s_mov_b32 m0, s68
	v_lshl_add_u64 v[166:167], s[38:39], 0, v[202:203]
	s_add_u32 s82, s38, 0x80000
	ds_read_b128 v[174:177], v226 offset:16384
	ds_read_b128 v[178:181], v226 offset:17408
	ds_read_b128 v[182:185], v226 offset:18432
	ds_read_b128 v[186:189], v226 offset:19456
	ds_read_b128 v[190:193], v226 offset:20480
	ds_read_b128 v[238:241], v226 offset:21504
	ds_read_b128 v[242:245], v226 offset:22528
	ds_read_b128 v[246:249], v226 offset:23552
	global_load_lds_dwordx4 v[166:167], off
	v_lshl_add_u64 v[168:169], s[38:39], 0, v[206:207]
	s_mov_b32 m0, s69
	s_addc_u32 s83, s39, 0
	global_load_lds_dwordx4 v[168:169], off
	v_lshl_add_u64 v[170:171], s[82:83], 0, v[202:203]
	s_mov_b32 m0, s70
	v_lshl_add_u64 v[172:173], s[40:41], 0, v[204:205]
	global_load_lds_dwordx4 v[170:171], off
	v_lshl_add_u64 v[170:171], s[82:83], 0, v[206:207]
	s_mov_b32 m0, s71
	s_nop 0
	global_load_lds_dwordx4 v[170:171], off
	v_lshl_add_u64 v[170:171], s[40:41], 0, v[194:195]
	s_mov_b32 m0, s23
	s_nop 0
	global_load_lds_dwordx4 v[170:171], off
	s_mov_b32 m0, s42
	s_nop 0
	global_load_lds_dwordx4 v[172:173], off
	s_waitcnt vmcnt(8)
	s_waitcnt lgkmcnt(0)
	s_barrier
	s_waitcnt lgkmcnt(0)
	v_mfma_i32_16x16x64_i8 v[110:113], v[158:161], v[174:177], v[110:113]
	s_nop 0
	v_mfma_i32_16x16x64_i8 v[110:113], v[154:157], v[178:181], v[110:113]
	v_mfma_i32_16x16x64_i8 v[106:109], v[150:153], v[174:177], v[106:109]
	s_nop 0
	v_mfma_i32_16x16x64_i8 v[106:109], v[146:149], v[178:181], v[106:109]
	v_mfma_i32_16x16x64_i8 v[126:129], v[158:161], v[182:185], v[126:129]
	s_nop 0
	v_mfma_i32_16x16x64_i8 v[126:129], v[154:157], v[186:189], v[126:129]
	v_mfma_i32_16x16x64_i8 v[118:121], v[150:153], v[182:185], v[118:121]
	s_nop 0
	v_mfma_i32_16x16x64_i8 v[118:121], v[146:149], v[186:189], v[118:121]
	v_mfma_i32_16x16x64_i8 v[62:65], v[158:161], v[190:193], v[62:65]
	s_nop 0
	v_mfma_i32_16x16x64_i8 v[62:65], v[154:157], v[238:241], v[62:65]
	v_mfma_i32_16x16x64_i8 v[50:53], v[150:153], v[190:193], v[50:53]
	s_nop 0
	v_mfma_i32_16x16x64_i8 v[50:53], v[146:149], v[238:241], v[50:53]
	v_mfma_i32_16x16x64_i8 v[14:17], v[158:161], v[242:245], v[14:17]
	s_nop 0
	v_mfma_i32_16x16x64_i8 v[14:17], v[154:157], v[246:249], v[14:17]
	v_mfma_i32_16x16x64_i8 v[10:13], v[150:153], v[242:245], v[10:13]
	s_nop 0
	v_mfma_i32_16x16x64_i8 v[10:13], v[146:149], v[246:249], v[10:13]
	v_mfma_i32_16x16x64_i8 v[122:125], v[142:145], v[174:177], v[122:125]
	s_nop 0
	v_mfma_i32_16x16x64_i8 v[122:125], v[138:141], v[178:181], v[122:125]
	v_mfma_i32_16x16x64_i8 v[114:117], v[134:137], v[174:177], v[114:117]
	s_nop 0
	v_mfma_i32_16x16x64_i8 v[114:117], v[130:133], v[178:181], v[114:117]
	v_mfma_i32_16x16x64_i8 v[78:81], v[142:145], v[182:185], v[78:81]
	s_nop 0
	v_mfma_i32_16x16x64_i8 v[78:81], v[138:141], v[186:189], v[78:81]
	v_mfma_i32_16x16x64_i8 v[66:69], v[134:137], v[182:185], v[66:69]
	s_nop 0
	v_mfma_i32_16x16x64_i8 v[66:69], v[130:133], v[186:189], v[66:69]
	v_mfma_i32_16x16x64_i8 v[22:25], v[142:145], v[190:193], v[22:25]
	s_nop 0
	v_mfma_i32_16x16x64_i8 v[22:25], v[138:141], v[238:241], v[22:25]
	v_mfma_i32_16x16x64_i8 v[18:21], v[134:137], v[190:193], v[18:21]
	s_nop 0
	v_mfma_i32_16x16x64_i8 v[18:21], v[130:133], v[238:241], v[18:21]
	v_mfma_i32_16x16x64_i8 v[6:9], v[142:145], v[242:245], v[6:9]
	s_nop 0
	v_mfma_i32_16x16x64_i8 v[6:9], v[138:141], v[246:249], v[6:9]
	v_mfma_i32_16x16x64_i8 v[2:5], v[134:137], v[242:245], v[2:5]
	s_nop 0
	v_mfma_i32_16x16x64_i8 v[2:5], v[130:133], v[246:249], v[2:5]
	s_barrier
	ds_read_b128 v[130:133], v235
	ds_read_b128 v[134:137], v235 offset:1024
	ds_read_b128 v[138:141], v235 offset:2048
	ds_read_b128 v[142:145], v235 offset:3072
	ds_read_b128 v[146:149], v236
	ds_read_b128 v[150:153], v236 offset:1024
	ds_read_b128 v[154:157], v236 offset:2048
	ds_read_b128 v[158:161], v236 offset:3072
	s_add_u32 s40, s40, 0x80000
	s_addc_u32 s41, s41, 0
	s_mov_b32 m0, s43
	v_lshl_add_u64 v[250:251], s[40:41], 0, v[194:195]
	ds_read_b128 v[174:177], v226 offset:32768
	ds_read_b128 v[178:181], v226 offset:33792
	ds_read_b128 v[182:185], v226 offset:34816
	ds_read_b128 v[186:189], v226 offset:35840
	ds_read_b128 v[190:193], v226 offset:36864
	ds_read_b128 v[238:241], v226 offset:37888
	ds_read_b128 v[242:245], v226 offset:38912
	ds_read_b128 v[246:249], v226 offset:39936
	global_load_lds_dwordx4 v[250:251], off
	v_lshl_add_u64 v[250:251], s[40:41], 0, v[204:205]
	s_mov_b32 m0, s44
	s_nop 0
	global_load_lds_dwordx4 v[250:251], off
	s_waitcnt vmcnt(8)
	s_waitcnt lgkmcnt(0)
	s_barrier
	s_waitcnt lgkmcnt(0)
	v_mfma_i32_16x16x64_i8 v[30:33], v[130:133], v[174:177], v[30:33]
	s_nop 0
	v_mfma_i32_16x16x64_i8 v[30:33], v[134:137], v[178:181], v[30:33]
	v_mfma_i32_16x16x64_i8 v[26:29], v[138:141], v[174:177], v[26:29]
	s_nop 0
	v_mfma_i32_16x16x64_i8 v[26:29], v[142:145], v[178:181], v[26:29]
	v_mfma_i32_16x16x64_i8 v[46:49], v[130:133], v[182:185], v[46:49]
	s_nop 0
	v_mfma_i32_16x16x64_i8 v[46:49], v[134:137], v[186:189], v[46:49]
	v_mfma_i32_16x16x64_i8 v[42:45], v[138:141], v[182:185], v[42:45]
	s_nop 0
	v_mfma_i32_16x16x64_i8 v[42:45], v[142:145], v[186:189], v[42:45]
	v_mfma_i32_16x16x64_i8 v[74:77], v[130:133], v[190:193], v[74:77]
	s_nop 0
	v_mfma_i32_16x16x64_i8 v[74:77], v[134:137], v[238:241], v[74:77]
	v_mfma_i32_16x16x64_i8 v[70:73], v[138:141], v[190:193], v[70:73]
	s_nop 0
	v_mfma_i32_16x16x64_i8 v[70:73], v[142:145], v[238:241], v[70:73]
	v_mfma_i32_16x16x64_i8 v[94:97], v[130:133], v[242:245], v[94:97]
	s_nop 0
	v_mfma_i32_16x16x64_i8 v[94:97], v[134:137], v[246:249], v[94:97]
	v_mfma_i32_16x16x64_i8 v[90:93], v[138:141], v[242:245], v[90:93]
	s_nop 0
	v_mfma_i32_16x16x64_i8 v[90:93], v[142:145], v[246:249], v[90:93]
	v_mfma_i32_16x16x64_i8 v[38:41], v[146:149], v[174:177], v[38:41]
	s_nop 0
	v_mfma_i32_16x16x64_i8 v[38:41], v[150:153], v[178:181], v[38:41]
	v_mfma_i32_16x16x64_i8 v[34:37], v[154:157], v[174:177], v[34:37]
	s_nop 0
	v_mfma_i32_16x16x64_i8 v[34:37], v[158:161], v[178:181], v[34:37]
	v_mfma_i32_16x16x64_i8 v[58:61], v[146:149], v[182:185], v[58:61]
	s_nop 0
	v_mfma_i32_16x16x64_i8 v[58:61], v[150:153], v[186:189], v[58:61]
	v_mfma_i32_16x16x64_i8 v[54:57], v[154:157], v[182:185], v[54:57]
	s_nop 0
	v_mfma_i32_16x16x64_i8 v[54:57], v[158:161], v[186:189], v[54:57]
	v_mfma_i32_16x16x64_i8 v[86:89], v[146:149], v[190:193], v[86:89]
	s_nop 0
	v_mfma_i32_16x16x64_i8 v[86:89], v[150:153], v[238:241], v[86:89]
	v_mfma_i32_16x16x64_i8 v[82:85], v[154:157], v[190:193], v[82:85]
	s_nop 0
	v_mfma_i32_16x16x64_i8 v[82:85], v[158:161], v[238:241], v[82:85]
	v_mfma_i32_16x16x64_i8 v[102:105], v[146:149], v[242:245], v[102:105]
	s_nop 0
	v_mfma_i32_16x16x64_i8 v[102:105], v[150:153], v[246:249], v[102:105]
	v_mfma_i32_16x16x64_i8 v[98:101], v[154:157], v[242:245], v[98:101]
	s_nop 0
	v_mfma_i32_16x16x64_i8 v[98:101], v[158:161], v[246:249], v[98:101]
	s_barrier
	s_mov_b32 m0, s72
	v_lshl_add_u64 v[166:167], v[166:167], 0, s[6:7]
	s_add_u32 s38, s38, 0x80080
	ds_read_b128 v[174:177], v226 offset:49152
	ds_read_b128 v[178:181], v226 offset:50176
	ds_read_b128 v[182:185], v226 offset:51200
	ds_read_b128 v[186:189], v226 offset:52224
	ds_read_b128 v[190:193], v226 offset:53248
	ds_read_b128 v[238:241], v226 offset:54272
	ds_read_b128 v[242:245], v226 offset:55296
	ds_read_b128 v[246:249], v226 offset:56320
	global_load_lds_dwordx4 v[166:167], off
	v_lshl_add_u64 v[166:167], v[168:169], 0, s[6:7]
	s_mov_b32 m0, s73
	s_addc_u32 s39, s39, 0
	global_load_lds_dwordx4 v[166:167], off
	v_lshl_add_u64 v[166:167], s[38:39], 0, v[202:203]
	s_mov_b32 m0, s74
	s_nop 0
	global_load_lds_dwordx4 v[166:167], off
	v_lshl_add_u64 v[166:167], s[38:39], 0, v[206:207]
	s_mov_b32 m0, s75
	s_nop 0
	global_load_lds_dwordx4 v[166:167], off
	v_lshl_add_u64 v[166:167], v[170:171], 0, s[6:7]
	s_mov_b32 m0, s51
	s_nop 0
	global_load_lds_dwordx4 v[166:167], off
	v_lshl_add_u64 v[166:167], v[172:173], 0, s[6:7]
	s_mov_b32 m0, s53
	s_nop 0
	global_load_lds_dwordx4 v[166:167], off
	s_waitcnt vmcnt(8)
	s_waitcnt lgkmcnt(0)
	s_barrier
	s_waitcnt lgkmcnt(0)
	v_mfma_i32_16x16x64_i8 v[110:113], v[130:133], v[174:177], v[110:113]
	s_nop 0
	v_mfma_i32_16x16x64_i8 v[110:113], v[134:137], v[178:181], v[110:113]
	v_mfma_i32_16x16x64_i8 v[106:109], v[138:141], v[174:177], v[106:109]
	s_nop 0
	v_mfma_i32_16x16x64_i8 v[106:109], v[142:145], v[178:181], v[106:109]
	v_mfma_i32_16x16x64_i8 v[126:129], v[130:133], v[182:185], v[126:129]
	s_nop 0
	v_mfma_i32_16x16x64_i8 v[126:129], v[134:137], v[186:189], v[126:129]
	v_mfma_i32_16x16x64_i8 v[118:121], v[138:141], v[182:185], v[118:121]
	s_nop 0
	v_mfma_i32_16x16x64_i8 v[118:121], v[142:145], v[186:189], v[118:121]
	v_mfma_i32_16x16x64_i8 v[62:65], v[130:133], v[190:193], v[62:65]
	s_nop 0
	v_mfma_i32_16x16x64_i8 v[62:65], v[134:137], v[238:241], v[62:65]
	v_mfma_i32_16x16x64_i8 v[50:53], v[138:141], v[190:193], v[50:53]
	s_nop 0
	v_mfma_i32_16x16x64_i8 v[50:53], v[142:145], v[238:241], v[50:53]
	v_mfma_i32_16x16x64_i8 v[14:17], v[130:133], v[242:245], v[14:17]
	s_nop 0
	v_mfma_i32_16x16x64_i8 v[14:17], v[134:137], v[246:249], v[14:17]
	v_mfma_i32_16x16x64_i8 v[10:13], v[138:141], v[242:245], v[10:13]
	s_nop 0
	v_mfma_i32_16x16x64_i8 v[10:13], v[142:145], v[246:249], v[10:13]
	v_mfma_i32_16x16x64_i8 v[122:125], v[146:149], v[174:177], v[122:125]
	s_nop 0
	v_mfma_i32_16x16x64_i8 v[122:125], v[150:153], v[178:181], v[122:125]
	v_mfma_i32_16x16x64_i8 v[114:117], v[154:157], v[174:177], v[114:117]
	s_nop 0
	v_mfma_i32_16x16x64_i8 v[114:117], v[158:161], v[178:181], v[114:117]
	v_mfma_i32_16x16x64_i8 v[78:81], v[146:149], v[182:185], v[78:81]
	s_nop 0
	v_mfma_i32_16x16x64_i8 v[78:81], v[150:153], v[186:189], v[78:81]
	v_mfma_i32_16x16x64_i8 v[66:69], v[154:157], v[182:185], v[66:69]
	s_nop 0
	v_mfma_i32_16x16x64_i8 v[66:69], v[158:161], v[186:189], v[66:69]
	v_mfma_i32_16x16x64_i8 v[22:25], v[146:149], v[190:193], v[22:25]
	s_nop 0
	v_mfma_i32_16x16x64_i8 v[22:25], v[150:153], v[238:241], v[22:25]
	v_mfma_i32_16x16x64_i8 v[18:21], v[154:157], v[190:193], v[18:21]
	s_nop 0
	v_mfma_i32_16x16x64_i8 v[18:21], v[158:161], v[238:241], v[18:21]
	v_mfma_i32_16x16x64_i8 v[6:9], v[146:149], v[242:245], v[6:9]
	s_nop 0
	v_mfma_i32_16x16x64_i8 v[6:9], v[150:153], v[246:249], v[6:9]
	v_mfma_i32_16x16x64_i8 v[2:5], v[154:157], v[242:245], v[2:5]
	s_nop 0
	v_mfma_i32_16x16x64_i8 v[2:5], v[158:161], v[246:249], v[2:5]
	s_barrier
	s_add_i32 s80, s80, 2
	s_add_u32 s36, s36, 0x100
	s_addc_u32 s37, s37, 0
	s_cmp_gt_u32 s80, 13
	s_cbranch_scc0 .LBB0_746
	s_nop 15
	s_nop 15
	s_and_b64 vcc, exec, s[8:9]
	s_cbranch_vccz .LBB0_749
	s_barrier

.LBB0_752:
	ds_read_b128 v[134:137], v227
	ds_read_b128 v[138:141], v227 offset:1024
	ds_read_b128 v[142:145], v227 offset:2048
	ds_read_b128 v[146:149], v227 offset:3072
	ds_read_b128 v[150:153], v233
	ds_read_b128 v[154:157], v233 offset:1024
	ds_read_b128 v[158:161], v233 offset:2048
	ds_read_b128 v[162:165], v233 offset:3072
	s_add_u32 s30, s29, s2
	s_addc_u32 s31, s33, s3
	s_add_u32 s30, s30, 0x200100
	s_addc_u32 s31, s31, 0
	s_add_u32 s77, s25, s2
	s_addc_u32 s78, s40, s3
	s_cmpk_eq_i32 s2, 0xf00
	s_cselect_b32 s35, s0, s31
	s_cselect_b32 s34, s1, s30
	s_cselect_b32 s31, s14, s78
	s_cselect_b32 s30, s15, s77
	s_mov_b32 m0, s66
	v_lshl_add_u64 v[242:243], v[130:131], 0, s[2:3]
	ds_read_b128 v[166:169], v226
	ds_read_b128 v[170:173], v226 offset:1024
	ds_read_b128 v[174:177], v226 offset:2048
	ds_read_b128 v[178:181], v226 offset:3072
	ds_read_b128 v[182:185], v226 offset:4096
	ds_read_b128 v[186:189], v226 offset:5120
	ds_read_b128 v[190:193], v226 offset:6144
	ds_read_b128 v[238:241], v226 offset:7168
	global_load_lds_dwordx4 v[242:243], off
	v_lshl_add_u64 v[242:243], v[132:133], 0, s[2:3]
	s_mov_b32 m0, s67
	s_nop 0
	global_load_lds_dwordx4 v[242:243], off
	s_waitcnt vmcnt(8)
	s_waitcnt lgkmcnt(0)
	s_barrier
	s_waitcnt lgkmcnt(0)
	v_mfma_f32_16x16x32_bf16 v[26:29], v[134:137], v[166:169], v[26:29]
	v_mfma_f32_16x16x32_bf16 v[30:33], v[142:145], v[166:169], v[30:33]
	v_mfma_f32_16x16x32_bf16 v[42:45], v[134:137], v[174:177], v[42:45]
	v_mfma_f32_16x16x32_bf16 v[46:49], v[142:145], v[174:177], v[46:49]
	v_mfma_f32_16x16x32_bf16 v[70:73], v[134:137], v[182:185], v[70:73]
	v_mfma_f32_16x16x32_bf16 v[74:77], v[142:145], v[182:185], v[74:77]
	v_mfma_f32_16x16x32_bf16 v[90:93], v[134:137], v[190:193], v[90:93]
	v_mfma_f32_16x16x32_bf16 v[94:97], v[142:145], v[190:193], v[94:97]
	v_mfma_f32_16x16x32_bf16 v[26:29], v[138:141], v[170:173], v[26:29]
	v_mfma_f32_16x16x32_bf16 v[30:33], v[146:149], v[170:173], v[30:33]
	v_mfma_f32_16x16x32_bf16 v[42:45], v[138:141], v[178:181], v[42:45]
	v_mfma_f32_16x16x32_bf16 v[46:49], v[146:149], v[178:181], v[46:49]
	v_mfma_f32_16x16x32_bf16 v[70:73], v[138:141], v[186:189], v[70:73]
	v_mfma_f32_16x16x32_bf16 v[74:77], v[146:149], v[186:189], v[74:77]
	v_mfma_f32_16x16x32_bf16 v[90:93], v[138:141], v[238:241], v[90:93]
	v_mfma_f32_16x16x32_bf16 v[94:97], v[146:149], v[238:241], v[94:97]
	v_mfma_f32_16x16x32_bf16 v[34:37], v[150:153], v[166:169], v[34:37]
	v_mfma_f32_16x16x32_bf16 v[38:41], v[158:161], v[166:169], v[38:41]
	v_mfma_f32_16x16x32_bf16 v[54:57], v[150:153], v[174:177], v[54:57]
	v_mfma_f32_16x16x32_bf16 v[58:61], v[158:161], v[174:177], v[58:61]
	v_mfma_f32_16x16x32_bf16 v[82:85], v[150:153], v[182:185], v[82:85]
	v_mfma_f32_16x16x32_bf16 v[86:89], v[158:161], v[182:185], v[86:89]
	v_mfma_f32_16x16x32_bf16 v[98:101], v[150:153], v[190:193], v[98:101]
	v_mfma_f32_16x16x32_bf16 v[102:105], v[158:161], v[190:193], v[102:105]
	v_mfma_f32_16x16x32_bf16 v[34:37], v[154:157], v[170:173], v[34:37]
	v_mfma_f32_16x16x32_bf16 v[38:41], v[162:165], v[170:173], v[38:41]
	v_mfma_f32_16x16x32_bf16 v[54:57], v[154:157], v[178:181], v[54:57]
	v_mfma_f32_16x16x32_bf16 v[58:61], v[162:165], v[178:181], v[58:61]
	v_mfma_f32_16x16x32_bf16 v[82:85], v[154:157], v[186:189], v[82:85]
	v_mfma_f32_16x16x32_bf16 v[86:89], v[162:165], v[186:189], v[86:89]
	v_mfma_f32_16x16x32_bf16 v[98:101], v[154:157], v[238:241], v[98:101]
	v_mfma_f32_16x16x32_bf16 v[102:105], v[162:165], v[238:241], v[102:105]
	s_barrier
	s_mov_b32 m0, s68
	v_lshl_add_u64 v[242:243], s[30:31], 0, v[202:203]
	s_add_u32 s78, s30, 0x80000
	ds_read_b128 v[166:169], v226 offset:16384
	ds_read_b128 v[170:173], v226 offset:17408
	ds_read_b128 v[174:177], v226 offset:18432
	ds_read_b128 v[178:181], v226 offset:19456
	ds_read_b128 v[182:185], v226 offset:20480
	ds_read_b128 v[186:189], v226 offset:21504
	ds_read_b128 v[190:193], v226 offset:22528
	ds_read_b128 v[238:241], v226 offset:23552
	global_load_lds_dwordx4 v[242:243], off
	v_lshl_add_u64 v[244:245], s[30:31], 0, v[206:207]
	s_mov_b32 m0, s69
	s_addc_u32 s79, s31, 0
	global_load_lds_dwordx4 v[244:245], off
	v_lshl_add_u64 v[246:247], s[78:79], 0, v[202:203]
	s_mov_b32 m0, s70
	v_lshl_add_u64 v[248:249], s[34:35], 0, v[204:205]
	global_load_lds_dwordx4 v[246:247], off
	v_lshl_add_u64 v[246:247], s[78:79], 0, v[206:207]
	s_mov_b32 m0, s71
	s_nop 0
	global_load_lds_dwordx4 v[246:247], off
	v_lshl_add_u64 v[246:247], s[34:35], 0, v[194:195]
	s_mov_b32 m0, s23
	s_nop 0
	global_load_lds_dwordx4 v[246:247], off
	s_mov_b32 m0, s42
	s_nop 0
	global_load_lds_dwordx4 v[248:249], off
	s_waitcnt vmcnt(8)
	s_waitcnt lgkmcnt(0)
	s_barrier
	s_waitcnt lgkmcnt(0)
	v_mfma_f32_16x16x32_bf16 v[106:109], v[134:137], v[166:169], v[106:109]
	v_mfma_f32_16x16x32_bf16 v[110:113], v[142:145], v[166:169], v[110:113]
	v_mfma_f32_16x16x32_bf16 v[118:121], v[134:137], v[174:177], v[118:121]
	v_mfma_f32_16x16x32_bf16 v[126:129], v[142:145], v[174:177], v[126:129]
	v_mfma_f32_16x16x32_bf16 v[50:53], v[134:137], v[182:185], v[50:53]
	v_mfma_f32_16x16x32_bf16 v[62:65], v[142:145], v[182:185], v[62:65]
	v_mfma_f32_16x16x32_bf16 v[10:13], v[134:137], v[190:193], v[10:13]
	v_mfma_f32_16x16x32_bf16 v[14:17], v[142:145], v[190:193], v[14:17]
	v_mfma_f32_16x16x32_bf16 v[106:109], v[138:141], v[170:173], v[106:109]
	v_mfma_f32_16x16x32_bf16 v[110:113], v[146:149], v[170:173], v[110:113]
	v_mfma_f32_16x16x32_bf16 v[118:121], v[138:141], v[178:181], v[118:121]
	v_mfma_f32_16x16x32_bf16 v[126:129], v[146:149], v[178:181], v[126:129]
	v_mfma_f32_16x16x32_bf16 v[50:53], v[138:141], v[186:189], v[50:53]
	v_mfma_f32_16x16x32_bf16 v[62:65], v[146:149], v[186:189], v[62:65]
	v_mfma_f32_16x16x32_bf16 v[10:13], v[138:141], v[238:241], v[10:13]
	v_mfma_f32_16x16x32_bf16 v[14:17], v[146:149], v[238:241], v[14:17]
	v_mfma_f32_16x16x32_bf16 v[114:117], v[150:153], v[166:169], v[114:117]
	v_mfma_f32_16x16x32_bf16 v[122:125], v[158:161], v[166:169], v[122:125]
	v_mfma_f32_16x16x32_bf16 v[66:69], v[150:153], v[174:177], v[66:69]
	v_mfma_f32_16x16x32_bf16 v[78:81], v[158:161], v[174:177], v[78:81]
	v_mfma_f32_16x16x32_bf16 v[18:21], v[150:153], v[182:185], v[18:21]
	v_mfma_f32_16x16x32_bf16 v[22:25], v[158:161], v[182:185], v[22:25]
	v_mfma_f32_16x16x32_bf16 v[2:5], v[150:153], v[190:193], v[2:5]
	v_mfma_f32_16x16x32_bf16 v[6:9], v[158:161], v[190:193], v[6:9]
	v_mfma_f32_16x16x32_bf16 v[114:117], v[154:157], v[170:173], v[114:117]
	v_mfma_f32_16x16x32_bf16 v[122:125], v[162:165], v[170:173], v[122:125]
	v_mfma_f32_16x16x32_bf16 v[66:69], v[154:157], v[178:181], v[66:69]
	v_mfma_f32_16x16x32_bf16 v[78:81], v[162:165], v[178:181], v[78:81]
	v_mfma_f32_16x16x32_bf16 v[18:21], v[154:157], v[186:189], v[18:21]
	v_mfma_f32_16x16x32_bf16 v[22:25], v[162:165], v[186:189], v[22:25]
	v_mfma_f32_16x16x32_bf16 v[2:5], v[154:157], v[238:241], v[2:5]
	v_mfma_f32_16x16x32_bf16 v[6:9], v[162:165], v[238:241], v[6:9]
	s_barrier
	ds_read_b128 v[134:137], v235
	ds_read_b128 v[138:141], v235 offset:1024
	ds_read_b128 v[142:145], v235 offset:2048
	ds_read_b128 v[146:149], v235 offset:3072
	ds_read_b128 v[150:153], v236
	ds_read_b128 v[154:157], v236 offset:1024
	ds_read_b128 v[158:161], v236 offset:2048
	ds_read_b128 v[162:165], v236 offset:3072
	s_add_u32 s34, s34, 0x80000
	s_addc_u32 s35, s35, 0
	s_mov_b32 m0, s43
	v_lshl_add_u64 v[250:251], s[34:35], 0, v[194:195]
	ds_read_b128 v[166:169], v226 offset:32768
	ds_read_b128 v[170:173], v226 offset:33792
	ds_read_b128 v[174:177], v226 offset:34816
	ds_read_b128 v[178:181], v226 offset:35840
	ds_read_b128 v[182:185], v226 offset:36864
	ds_read_b128 v[186:189], v226 offset:37888
	ds_read_b128 v[190:193], v226 offset:38912
	ds_read_b128 v[238:241], v226 offset:39936
	global_load_lds_dwordx4 v[250:251], off
	v_lshl_add_u64 v[250:251], s[34:35], 0, v[204:205]
	s_mov_b32 m0, s44
	s_nop 0
	global_load_lds_dwordx4 v[250:251], off
	s_waitcnt vmcnt(8)
	s_waitcnt lgkmcnt(0)
	s_barrier
	s_waitcnt lgkmcnt(0)
	v_mfma_f32_16x16x32_bf16 v[26:29], v[134:137], v[166:169], v[26:29]
	v_mfma_f32_16x16x32_bf16 v[30:33], v[142:145], v[166:169], v[30:33]
	v_mfma_f32_16x16x32_bf16 v[42:45], v[134:137], v[174:177], v[42:45]
	v_mfma_f32_16x16x32_bf16 v[46:49], v[142:145], v[174:177], v[46:49]
	v_mfma_f32_16x16x32_bf16 v[70:73], v[134:137], v[182:185], v[70:73]
	v_mfma_f32_16x16x32_bf16 v[74:77], v[142:145], v[182:185], v[74:77]
	v_mfma_f32_16x16x32_bf16 v[90:93], v[134:137], v[190:193], v[90:93]
	v_mfma_f32_16x16x32_bf16 v[94:97], v[142:145], v[190:193], v[94:97]
	v_mfma_f32_16x16x32_bf16 v[26:29], v[138:141], v[170:173], v[26:29]
	v_mfma_f32_16x16x32_bf16 v[30:33], v[146:149], v[170:173], v[30:33]
	v_mfma_f32_16x16x32_bf16 v[42:45], v[138:141], v[178:181], v[42:45]
	v_mfma_f32_16x16x32_bf16 v[46:49], v[146:149], v[178:181], v[46:49]
	v_mfma_f32_16x16x32_bf16 v[70:73], v[138:141], v[186:189], v[70:73]
	v_mfma_f32_16x16x32_bf16 v[74:77], v[146:149], v[186:189], v[74:77]
	v_mfma_f32_16x16x32_bf16 v[90:93], v[138:141], v[238:241], v[90:93]
	v_mfma_f32_16x16x32_bf16 v[94:97], v[146:149], v[238:241], v[94:97]
	v_mfma_f32_16x16x32_bf16 v[34:37], v[150:153], v[166:169], v[34:37]
	v_mfma_f32_16x16x32_bf16 v[38:41], v[158:161], v[166:169], v[38:41]
	v_mfma_f32_16x16x32_bf16 v[54:57], v[150:153], v[174:177], v[54:57]
	v_mfma_f32_16x16x32_bf16 v[58:61], v[158:161], v[174:177], v[58:61]
	v_mfma_f32_16x16x32_bf16 v[82:85], v[150:153], v[182:185], v[82:85]
	v_mfma_f32_16x16x32_bf16 v[86:89], v[158:161], v[182:185], v[86:89]
	v_mfma_f32_16x16x32_bf16 v[98:101], v[150:153], v[190:193], v[98:101]
	v_mfma_f32_16x16x32_bf16 v[102:105], v[158:161], v[190:193], v[102:105]
	v_mfma_f32_16x16x32_bf16 v[34:37], v[154:157], v[170:173], v[34:37]
	v_mfma_f32_16x16x32_bf16 v[38:41], v[162:165], v[170:173], v[38:41]
	v_mfma_f32_16x16x32_bf16 v[54:57], v[154:157], v[178:181], v[54:57]
	v_mfma_f32_16x16x32_bf16 v[58:61], v[162:165], v[178:181], v[58:61]
	v_mfma_f32_16x16x32_bf16 v[82:85], v[154:157], v[186:189], v[82:85]
	v_mfma_f32_16x16x32_bf16 v[86:89], v[162:165], v[186:189], v[86:89]
	v_mfma_f32_16x16x32_bf16 v[98:101], v[154:157], v[238:241], v[98:101]
	v_mfma_f32_16x16x32_bf16 v[102:105], v[162:165], v[238:241], v[102:105]
	s_barrier
	s_mov_b32 m0, s72
	v_lshl_add_u64 v[242:243], v[242:243], 0, s[6:7]
	s_add_u32 s30, s30, 0x80080
	ds_read_b128 v[166:169], v226 offset:49152
	ds_read_b128 v[170:173], v226 offset:50176
	ds_read_b128 v[174:177], v226 offset:51200
	ds_read_b128 v[178:181], v226 offset:52224
	ds_read_b128 v[182:185], v226 offset:53248
	ds_read_b128 v[186:189], v226 offset:54272
	ds_read_b128 v[190:193], v226 offset:55296
	ds_read_b128 v[238:241], v226 offset:56320
	global_load_lds_dwordx4 v[242:243], off
	v_lshl_add_u64 v[242:243], v[244:245], 0, s[6:7]
	s_mov_b32 m0, s73
	s_addc_u32 s31, s31, 0
	global_load_lds_dwordx4 v[242:243], off
	v_lshl_add_u64 v[242:243], s[30:31], 0, v[202:203]
	s_mov_b32 m0, s74
	s_nop 0
	global_load_lds_dwordx4 v[242:243], off
	v_lshl_add_u64 v[242:243], s[30:31], 0, v[206:207]
	s_mov_b32 m0, s75
	s_nop 0
	global_load_lds_dwordx4 v[242:243], off
	v_lshl_add_u64 v[242:243], v[246:247], 0, s[6:7]
	s_mov_b32 m0, s51
	s_nop 0
	global_load_lds_dwordx4 v[242:243], off
	v_lshl_add_u64 v[242:243], v[248:249], 0, s[6:7]
	s_mov_b32 m0, s53
	s_nop 0
	global_load_lds_dwordx4 v[242:243], off
	s_waitcnt vmcnt(8)
	s_waitcnt lgkmcnt(0)
	s_barrier
	s_waitcnt lgkmcnt(0)
	v_mfma_f32_16x16x32_bf16 v[106:109], v[134:137], v[166:169], v[106:109]
	v_mfma_f32_16x16x32_bf16 v[110:113], v[142:145], v[166:169], v[110:113]
	v_mfma_f32_16x16x32_bf16 v[118:121], v[134:137], v[174:177], v[118:121]
	v_mfma_f32_16x16x32_bf16 v[126:129], v[142:145], v[174:177], v[126:129]
	v_mfma_f32_16x16x32_bf16 v[50:53], v[134:137], v[182:185], v[50:53]
	v_mfma_f32_16x16x32_bf16 v[62:65], v[142:145], v[182:185], v[62:65]
	v_mfma_f32_16x16x32_bf16 v[10:13], v[134:137], v[190:193], v[10:13]
	v_mfma_f32_16x16x32_bf16 v[14:17], v[142:145], v[190:193], v[14:17]
	v_mfma_f32_16x16x32_bf16 v[106:109], v[138:141], v[170:173], v[106:109]
	v_mfma_f32_16x16x32_bf16 v[110:113], v[146:149], v[170:173], v[110:113]
	v_mfma_f32_16x16x32_bf16 v[118:121], v[138:141], v[178:181], v[118:121]
	v_mfma_f32_16x16x32_bf16 v[126:129], v[146:149], v[178:181], v[126:129]
	v_mfma_f32_16x16x32_bf16 v[50:53], v[138:141], v[186:189], v[50:53]
	v_mfma_f32_16x16x32_bf16 v[62:65], v[146:149], v[186:189], v[62:65]
	v_mfma_f32_16x16x32_bf16 v[10:13], v[138:141], v[238:241], v[10:13]
	v_mfma_f32_16x16x32_bf16 v[14:17], v[146:149], v[238:241], v[14:17]
	v_mfma_f32_16x16x32_bf16 v[114:117], v[150:153], v[166:169], v[114:117]
	v_mfma_f32_16x16x32_bf16 v[122:125], v[158:161], v[166:169], v[122:125]
	v_mfma_f32_16x16x32_bf16 v[66:69], v[150:153], v[174:177], v[66:69]
	v_mfma_f32_16x16x32_bf16 v[78:81], v[158:161], v[174:177], v[78:81]
	v_mfma_f32_16x16x32_bf16 v[18:21], v[150:153], v[182:185], v[18:21]
	v_mfma_f32_16x16x32_bf16 v[22:25], v[158:161], v[182:185], v[22:25]
	v_mfma_f32_16x16x32_bf16 v[2:5], v[150:153], v[190:193], v[2:5]
	v_mfma_f32_16x16x32_bf16 v[6:9], v[158:161], v[190:193], v[6:9]
	v_mfma_f32_16x16x32_bf16 v[114:117], v[154:157], v[170:173], v[114:117]
	v_mfma_f32_16x16x32_bf16 v[122:125], v[162:165], v[170:173], v[122:125]
	v_mfma_f32_16x16x32_bf16 v[66:69], v[154:157], v[178:181], v[66:69]
	v_mfma_f32_16x16x32_bf16 v[78:81], v[162:165], v[178:181], v[78:81]
	v_mfma_f32_16x16x32_bf16 v[18:21], v[154:157], v[186:189], v[18:21]
	v_mfma_f32_16x16x32_bf16 v[22:25], v[162:165], v[186:189], v[22:25]
	v_mfma_f32_16x16x32_bf16 v[2:5], v[154:157], v[238:241], v[2:5]
	v_mfma_f32_16x16x32_bf16 v[6:9], v[162:165], v[238:241], v[6:9]
	s_barrier
	s_add_i32 s41, s41, 2
	s_add_u32 s2, s2, 0x100
	s_addc_u32 s3, s3, 0
	s_cmp_gt_u32 s41, 29
	s_cbranch_scc0 .LBB0_752
	s_and_b64 vcc, exec, s[8:9]
	s_cbranch_vccz .LBB0_755
	s_barrier

.LBB0_817:
	ds_read_b128 v[130:133], v223
	ds_read_b128 v[134:137], v223 offset:1024
	ds_read_b128 v[138:141], v223 offset:2048
	ds_read_b128 v[142:145], v223 offset:3072
	ds_read_b128 v[146:149], v224
	ds_read_b128 v[150:153], v224 offset:1024
	ds_read_b128 v[154:157], v224 offset:2048
	ds_read_b128 v[158:161], v224 offset:3072
	s_add_u32 s6, s4, 0xfff00080
	s_addc_u32 s7, s5, -1
	s_cmp_eq_u32 s14, 60
	s_cselect_b32 s9, s19, s7
	s_cselect_b32 s8, s18, s6
	s_cselect_b32 s7, s79, s1
	s_cselect_b32 s6, s78, s0
	v_lshl_add_u64 v[194:195], s[4:5], 0, v[170:171]
	s_add_i32 m0, s35, 0xc000
	ds_read_b128 v[174:177], v225
	ds_read_b128 v[178:181], v225 offset:1024
	ds_read_b128 v[182:185], v225 offset:2048
	ds_read_b128 v[186:189], v225 offset:3072
	ds_read_b128 v[190:193], v225 offset:4096
	ds_read_b128 v[202:205], v225 offset:5120
	ds_read_b128 v[206:209], v225 offset:6144
	ds_read_b128 v[210:213], v225 offset:7168
	global_load_lds_dwordx4 v[194:195], off
	v_lshl_add_u64 v[194:195], s[4:5], 0, v[172:173]
	s_add_i32 m0, s35, 0xe000
	s_nop 0
	global_load_lds_dwordx4 v[194:195], off
	s_waitcnt vmcnt(8)
	s_waitcnt lgkmcnt(0)
	s_barrier
	s_waitcnt lgkmcnt(0)
	v_mfma_f32_16x16x32_bf16 v[14:17], v[130:133], v[174:177], v[14:17]
	v_mfma_f32_16x16x32_bf16 v[10:13], v[138:141], v[174:177], v[10:13]
	v_mfma_f32_16x16x32_bf16 v[34:37], v[130:133], v[182:185], v[34:37]
	v_mfma_f32_16x16x32_bf16 v[26:29], v[138:141], v[182:185], v[26:29]
	v_mfma_f32_16x16x32_bf16 v[46:49], v[130:133], v[190:193], v[46:49]
	v_mfma_f32_16x16x32_bf16 v[42:45], v[138:141], v[190:193], v[42:45]
	v_mfma_f32_16x16x32_bf16 v[62:65], v[130:133], v[206:209], v[62:65]
	v_mfma_f32_16x16x32_bf16 v[58:61], v[138:141], v[206:209], v[58:61]
	v_mfma_f32_16x16x32_bf16 v[14:17], v[134:137], v[178:181], v[14:17]
	v_mfma_f32_16x16x32_bf16 v[10:13], v[142:145], v[178:181], v[10:13]
	v_mfma_f32_16x16x32_bf16 v[34:37], v[134:137], v[186:189], v[34:37]
	v_mfma_f32_16x16x32_bf16 v[26:29], v[142:145], v[186:189], v[26:29]
	v_mfma_f32_16x16x32_bf16 v[46:49], v[134:137], v[202:205], v[46:49]
	v_mfma_f32_16x16x32_bf16 v[42:45], v[142:145], v[202:205], v[42:45]
	v_mfma_f32_16x16x32_bf16 v[62:65], v[134:137], v[210:213], v[62:65]
	v_mfma_f32_16x16x32_bf16 v[58:61], v[142:145], v[210:213], v[58:61]
	v_mfma_f32_16x16x32_bf16 v[6:9], v[146:149], v[174:177], v[6:9]
	v_mfma_f32_16x16x32_bf16 v[2:5], v[154:157], v[174:177], v[2:5]
	v_mfma_f32_16x16x32_bf16 v[22:25], v[146:149], v[182:185], v[22:25]
	v_mfma_f32_16x16x32_bf16 v[18:21], v[154:157], v[182:185], v[18:21]
	v_mfma_f32_16x16x32_bf16 v[38:41], v[146:149], v[190:193], v[38:41]
	v_mfma_f32_16x16x32_bf16 v[30:33], v[154:157], v[190:193], v[30:33]
	v_mfma_f32_16x16x32_bf16 v[54:57], v[146:149], v[206:209], v[54:57]
	v_mfma_f32_16x16x32_bf16 v[50:53], v[154:157], v[206:209], v[50:53]
	v_mfma_f32_16x16x32_bf16 v[6:9], v[150:153], v[178:181], v[6:9]
	v_mfma_f32_16x16x32_bf16 v[2:5], v[158:161], v[178:181], v[2:5]
	v_mfma_f32_16x16x32_bf16 v[22:25], v[150:153], v[186:189], v[22:25]
	v_mfma_f32_16x16x32_bf16 v[18:21], v[158:161], v[186:189], v[18:21]
	v_mfma_f32_16x16x32_bf16 v[38:41], v[150:153], v[202:205], v[38:41]
	v_mfma_f32_16x16x32_bf16 v[30:33], v[158:161], v[202:205], v[30:33]
	v_mfma_f32_16x16x32_bf16 v[54:57], v[150:153], v[210:213], v[54:57]
	v_mfma_f32_16x16x32_bf16 v[50:53], v[158:161], v[210:213], v[50:53]
	s_barrier
	s_add_i32 s15, s17, s33
	v_lshl_add_u64 v[194:195], s[6:7], 0, v[164:165]
	s_mov_b32 m0, s15
	ds_read_b128 v[174:177], v225 offset:16384
	ds_read_b128 v[178:181], v225 offset:17408
	ds_read_b128 v[182:185], v225 offset:18432
	ds_read_b128 v[186:189], v225 offset:19456
	ds_read_b128 v[190:193], v225 offset:20480
	ds_read_b128 v[202:205], v225 offset:21504
	ds_read_b128 v[206:209], v225 offset:22528
	ds_read_b128 v[210:213], v225 offset:23552
	global_load_lds_dwordx4 v[194:195], off
	s_add_i32 m0, s15, 0x2000
	s_add_u32 s44, s6, 0x100000
	v_lshl_add_u64 v[214:215], s[6:7], 0, v[168:169]
	s_addc_u32 s45, s7, 0
	s_add_i32 s15, s55, s33
	global_load_lds_dwordx4 v[214:215], off
	v_lshl_add_u64 v[216:217], s[44:45], 0, v[164:165]
	s_mov_b32 m0, s15
	v_lshl_add_u64 v[218:219], s[8:9], 0, v[166:167]
	global_load_lds_dwordx4 v[216:217], off
	v_lshl_add_u64 v[216:217], s[44:45], 0, v[168:169]
	s_add_i32 m0, s15, 0x2000
	s_nop 0
	global_load_lds_dwordx4 v[216:217], off
	v_lshl_add_u64 v[216:217], s[8:9], 0, v[162:163]
	s_mov_b32 m0, s35
	s_nop 0
	global_load_lds_dwordx4 v[216:217], off
	s_mov_b32 m0, s80
	s_nop 0
	global_load_lds_dwordx4 v[218:219], off
	s_waitcnt vmcnt(8)
	s_waitcnt lgkmcnt(0)
	s_barrier
	s_waitcnt lgkmcnt(0)
	v_mfma_f32_16x16x32_bf16 v[78:81], v[130:133], v[174:177], v[78:81]
	v_mfma_f32_16x16x32_bf16 v[74:77], v[138:141], v[174:177], v[74:77]
	v_mfma_f32_16x16x32_bf16 v[94:97], v[130:133], v[182:185], v[94:97]
	v_mfma_f32_16x16x32_bf16 v[90:93], v[138:141], v[182:185], v[90:93]
	v_mfma_f32_16x16x32_bf16 v[110:113], v[130:133], v[190:193], v[110:113]
	v_mfma_f32_16x16x32_bf16 v[106:109], v[138:141], v[190:193], v[106:109]
	v_mfma_f32_16x16x32_bf16 v[118:121], v[130:133], v[206:209], v[118:121]
	v_mfma_f32_16x16x32_bf16 v[114:117], v[138:141], v[206:209], v[114:117]
	v_mfma_f32_16x16x32_bf16 v[78:81], v[134:137], v[178:181], v[78:81]
	v_mfma_f32_16x16x32_bf16 v[74:77], v[142:145], v[178:181], v[74:77]
	v_mfma_f32_16x16x32_bf16 v[94:97], v[134:137], v[186:189], v[94:97]
	v_mfma_f32_16x16x32_bf16 v[90:93], v[142:145], v[186:189], v[90:93]
	v_mfma_f32_16x16x32_bf16 v[110:113], v[134:137], v[202:205], v[110:113]
	v_mfma_f32_16x16x32_bf16 v[106:109], v[142:145], v[202:205], v[106:109]
	v_mfma_f32_16x16x32_bf16 v[118:121], v[134:137], v[210:213], v[118:121]
	v_mfma_f32_16x16x32_bf16 v[114:117], v[142:145], v[210:213], v[114:117]
	v_mfma_f32_16x16x32_bf16 v[70:73], v[146:149], v[174:177], v[70:73]
	v_mfma_f32_16x16x32_bf16 v[66:69], v[154:157], v[174:177], v[66:69]
	v_mfma_f32_16x16x32_bf16 v[86:89], v[146:149], v[182:185], v[86:89]
	v_mfma_f32_16x16x32_bf16 v[82:85], v[154:157], v[182:185], v[82:85]
	v_mfma_f32_16x16x32_bf16 v[102:105], v[146:149], v[190:193], v[102:105]
	v_mfma_f32_16x16x32_bf16 v[98:101], v[154:157], v[190:193], v[98:101]
	v_mfma_f32_16x16x32_bf16 v[122:125], v[146:149], v[206:209], v[122:125]
	v_mfma_f32_16x16x32_bf16 v[126:129], v[154:157], v[206:209], v[126:129]
	v_mfma_f32_16x16x32_bf16 v[70:73], v[150:153], v[178:181], v[70:73]
	v_mfma_f32_16x16x32_bf16 v[66:69], v[158:161], v[178:181], v[66:69]
	v_mfma_f32_16x16x32_bf16 v[86:89], v[150:153], v[186:189], v[86:89]
	v_mfma_f32_16x16x32_bf16 v[82:85], v[158:161], v[186:189], v[82:85]
	v_mfma_f32_16x16x32_bf16 v[102:105], v[150:153], v[202:205], v[102:105]
	v_mfma_f32_16x16x32_bf16 v[98:101], v[158:161], v[202:205], v[98:101]
	v_mfma_f32_16x16x32_bf16 v[122:125], v[150:153], v[210:213], v[122:125]
	v_mfma_f32_16x16x32_bf16 v[126:129], v[158:161], v[210:213], v[126:129]
	s_barrier
	s_add_i32 s56, 0, 0x18000
	s_add_i32 s57, 0, 0x1c000
	v_add_u32_e32 v142, s56, v222
	v_add_u32_e32 v158, s57, v222
	ds_read_b128 v[130:133], v142
	ds_read_b128 v[134:137], v142 offset:1024
	ds_read_b128 v[138:141], v142 offset:2048
	ds_read_b128 v[142:145], v142 offset:3072
	ds_read_b128 v[146:149], v158
	ds_read_b128 v[150:153], v158 offset:1024
	ds_read_b128 v[154:157], v158 offset:2048
	ds_read_b128 v[158:161], v158 offset:3072
	s_add_u32 s8, s8, 0x100000
	s_addc_u32 s9, s9, 0
	s_mov_b32 m0, s59
	v_lshl_add_u64 v[238:239], s[8:9], 0, v[162:163]
	ds_read_b128 v[174:177], v225 offset:32768
	ds_read_b128 v[178:181], v225 offset:33792
	ds_read_b128 v[182:185], v225 offset:34816
	ds_read_b128 v[186:189], v225 offset:35840
	ds_read_b128 v[190:193], v225 offset:36864
	ds_read_b128 v[202:205], v225 offset:37888
	ds_read_b128 v[206:209], v225 offset:38912
	ds_read_b128 v[210:213], v225 offset:39936
	global_load_lds_dwordx4 v[238:239], off
	v_lshl_add_u64 v[238:239], s[8:9], 0, v[166:167]
	s_mov_b32 m0, s60
	s_nop 0
	global_load_lds_dwordx4 v[238:239], off
	s_waitcnt vmcnt(8)
	s_waitcnt lgkmcnt(0)
	s_barrier
	s_waitcnt lgkmcnt(0)
	v_mfma_f32_16x16x32_bf16 v[14:17], v[130:133], v[174:177], v[14:17]
	v_mfma_f32_16x16x32_bf16 v[10:13], v[138:141], v[174:177], v[10:13]
	v_mfma_f32_16x16x32_bf16 v[34:37], v[130:133], v[182:185], v[34:37]
	v_mfma_f32_16x16x32_bf16 v[26:29], v[138:141], v[182:185], v[26:29]
	v_mfma_f32_16x16x32_bf16 v[46:49], v[130:133], v[190:193], v[46:49]
	v_mfma_f32_16x16x32_bf16 v[42:45], v[138:141], v[190:193], v[42:45]
	v_mfma_f32_16x16x32_bf16 v[62:65], v[130:133], v[206:209], v[62:65]
	v_mfma_f32_16x16x32_bf16 v[58:61], v[138:141], v[206:209], v[58:61]
	v_mfma_f32_16x16x32_bf16 v[14:17], v[134:137], v[178:181], v[14:17]
	v_mfma_f32_16x16x32_bf16 v[10:13], v[142:145], v[178:181], v[10:13]
	v_mfma_f32_16x16x32_bf16 v[34:37], v[134:137], v[186:189], v[34:37]
	v_mfma_f32_16x16x32_bf16 v[26:29], v[142:145], v[186:189], v[26:29]
	v_mfma_f32_16x16x32_bf16 v[46:49], v[134:137], v[202:205], v[46:49]
	v_mfma_f32_16x16x32_bf16 v[42:45], v[142:145], v[202:205], v[42:45]
	v_mfma_f32_16x16x32_bf16 v[62:65], v[134:137], v[210:213], v[62:65]
	v_mfma_f32_16x16x32_bf16 v[58:61], v[142:145], v[210:213], v[58:61]
	v_mfma_f32_16x16x32_bf16 v[6:9], v[146:149], v[174:177], v[6:9]
	v_mfma_f32_16x16x32_bf16 v[2:5], v[154:157], v[174:177], v[2:5]
	v_mfma_f32_16x16x32_bf16 v[22:25], v[146:149], v[182:185], v[22:25]
	v_mfma_f32_16x16x32_bf16 v[18:21], v[154:157], v[182:185], v[18:21]
	v_mfma_f32_16x16x32_bf16 v[38:41], v[146:149], v[190:193], v[38:41]
	v_mfma_f32_16x16x32_bf16 v[30:33], v[154:157], v[190:193], v[30:33]
	v_mfma_f32_16x16x32_bf16 v[54:57], v[146:149], v[206:209], v[54:57]
	v_mfma_f32_16x16x32_bf16 v[50:53], v[154:157], v[206:209], v[50:53]
	v_mfma_f32_16x16x32_bf16 v[6:9], v[150:153], v[178:181], v[6:9]
	v_mfma_f32_16x16x32_bf16 v[2:5], v[158:161], v[178:181], v[2:5]
	v_mfma_f32_16x16x32_bf16 v[22:25], v[150:153], v[186:189], v[22:25]
	v_mfma_f32_16x16x32_bf16 v[18:21], v[158:161], v[186:189], v[18:21]
	v_mfma_f32_16x16x32_bf16 v[38:41], v[150:153], v[202:205], v[38:41]
	v_mfma_f32_16x16x32_bf16 v[30:33], v[158:161], v[202:205], v[30:33]
	v_mfma_f32_16x16x32_bf16 v[54:57], v[150:153], v[210:213], v[54:57]
	v_mfma_f32_16x16x32_bf16 v[50:53], v[158:161], v[210:213], v[50:53]
	s_barrier
	s_add_i32 s8, s56, s33
	v_lshl_add_u64 v[194:195], v[194:195], 0, s[26:27]
	s_mov_b32 m0, s8
	ds_read_b128 v[174:177], v225 offset:49152
	ds_read_b128 v[178:181], v225 offset:50176
	ds_read_b128 v[182:185], v225 offset:51200
	ds_read_b128 v[186:189], v225 offset:52224
	ds_read_b128 v[190:193], v225 offset:53248
	ds_read_b128 v[202:205], v225 offset:54272
	ds_read_b128 v[206:209], v225 offset:55296
	ds_read_b128 v[210:213], v225 offset:56320
	global_load_lds_dwordx4 v[194:195], off
	s_add_i32 m0, s8, 0x2000
	s_add_u32 s6, s6, 0x100080
	v_lshl_add_u64 v[194:195], v[214:215], 0, s[26:27]
	s_addc_u32 s7, s7, 0
	s_add_i32 s8, s57, s33
	global_load_lds_dwordx4 v[194:195], off
	v_lshl_add_u64 v[194:195], s[6:7], 0, v[164:165]
	s_mov_b32 m0, s8
	s_nop 0
	global_load_lds_dwordx4 v[194:195], off
	v_lshl_add_u64 v[194:195], s[6:7], 0, v[168:169]
	s_add_i32 m0, s8, 0x2000
	s_nop 0
	global_load_lds_dwordx4 v[194:195], off
	v_lshl_add_u64 v[194:195], v[216:217], 0, s[26:27]
	s_mov_b32 m0, s65
	s_nop 0
	global_load_lds_dwordx4 v[194:195], off
	v_lshl_add_u64 v[194:195], v[218:219], 0, s[26:27]
	s_mov_b32 m0, s66
	s_nop 0
	global_load_lds_dwordx4 v[194:195], off
	s_waitcnt vmcnt(8)
	s_waitcnt lgkmcnt(0)
	s_barrier
	s_waitcnt lgkmcnt(0)
	v_mfma_f32_16x16x32_bf16 v[78:81], v[130:133], v[174:177], v[78:81]
	v_mfma_f32_16x16x32_bf16 v[74:77], v[138:141], v[174:177], v[74:77]
	v_mfma_f32_16x16x32_bf16 v[94:97], v[130:133], v[182:185], v[94:97]
	v_mfma_f32_16x16x32_bf16 v[90:93], v[138:141], v[182:185], v[90:93]
	v_mfma_f32_16x16x32_bf16 v[110:113], v[130:133], v[190:193], v[110:113]
	v_mfma_f32_16x16x32_bf16 v[106:109], v[138:141], v[190:193], v[106:109]
	v_mfma_f32_16x16x32_bf16 v[118:121], v[130:133], v[206:209], v[118:121]
	v_mfma_f32_16x16x32_bf16 v[114:117], v[138:141], v[206:209], v[114:117]
	v_mfma_f32_16x16x32_bf16 v[78:81], v[134:137], v[178:181], v[78:81]
	v_mfma_f32_16x16x32_bf16 v[74:77], v[142:145], v[178:181], v[74:77]
	v_mfma_f32_16x16x32_bf16 v[94:97], v[134:137], v[186:189], v[94:97]
	v_mfma_f32_16x16x32_bf16 v[90:93], v[142:145], v[186:189], v[90:93]
	v_mfma_f32_16x16x32_bf16 v[110:113], v[134:137], v[202:205], v[110:113]
	v_mfma_f32_16x16x32_bf16 v[106:109], v[142:145], v[202:205], v[106:109]
	v_mfma_f32_16x16x32_bf16 v[118:121], v[134:137], v[210:213], v[118:121]
	v_mfma_f32_16x16x32_bf16 v[114:117], v[142:145], v[210:213], v[114:117]
	v_mfma_f32_16x16x32_bf16 v[70:73], v[146:149], v[174:177], v[70:73]
	v_mfma_f32_16x16x32_bf16 v[66:69], v[154:157], v[174:177], v[66:69]
	v_mfma_f32_16x16x32_bf16 v[86:89], v[146:149], v[182:185], v[86:89]
	v_mfma_f32_16x16x32_bf16 v[82:85], v[154:157], v[182:185], v[82:85]
	v_mfma_f32_16x16x32_bf16 v[102:105], v[146:149], v[190:193], v[102:105]
	v_mfma_f32_16x16x32_bf16 v[98:101], v[154:157], v[190:193], v[98:101]
	v_mfma_f32_16x16x32_bf16 v[122:125], v[146:149], v[206:209], v[122:125]
	v_mfma_f32_16x16x32_bf16 v[126:129], v[154:157], v[206:209], v[126:129]
	v_mfma_f32_16x16x32_bf16 v[70:73], v[150:153], v[178:181], v[70:73]
	v_mfma_f32_16x16x32_bf16 v[66:69], v[158:161], v[178:181], v[66:69]
	v_mfma_f32_16x16x32_bf16 v[86:89], v[150:153], v[186:189], v[86:89]
	v_mfma_f32_16x16x32_bf16 v[82:85], v[158:161], v[186:189], v[82:85]
	v_mfma_f32_16x16x32_bf16 v[102:105], v[150:153], v[202:205], v[102:105]
	v_mfma_f32_16x16x32_bf16 v[98:101], v[158:161], v[202:205], v[98:101]
	v_mfma_f32_16x16x32_bf16 v[122:125], v[150:153], v[210:213], v[122:125]
	v_mfma_f32_16x16x32_bf16 v[126:129], v[158:161], v[210:213], v[126:129]
	s_barrier
	s_add_i32 s14, s14, 2
	s_add_u32 s4, s4, 0x100
	s_addc_u32 s5, s5, 0
	s_add_u32 s0, s0, 0x100
	s_addc_u32 s1, s1, 0
	s_cmp_gt_u32 s14, 61
	s_cbranch_scc0 .LBB0_817
	s_and_b64 vcc, exec, s[28:29]
	s_cbranch_vccz .LBB0_820
	s_barrier

.LBB0_961:
	ds_read_b128 v[158:161], v185
	ds_read_b128 v[154:157], v185 offset:1024
	ds_read_b128 v[150:153], v185 offset:2048
	ds_read_b128 v[146:149], v185 offset:3072
	ds_read_b128 v[142:145], v186
	ds_read_b128 v[138:141], v186 offset:1024
	ds_read_b128 v[134:137], v186 offset:2048
	ds_read_b128 v[130:133], v186 offset:3072
	s_add_u32 s30, s28, 0xfff80080
	s_addc_u32 s31, s29, -1
	s_cmp_eq_u32 s45, 28
	s_cselect_b32 s35, s1, s31
	s_cselect_b32 s34, s15, s30
	s_cselect_b32 s31, s19, s44
	s_cselect_b32 s30, s42, s43
	v_lshl_add_u64 v[220:221], s[28:29], 0, v[170:171]
	s_add_i32 m0, s27, 0xc000
	ds_read_b128 v[174:177], v187
	ds_read_b128 v[178:181], v187 offset:1024
	ds_read_b128 v[188:191], v187 offset:2048
	ds_read_b128 v[192:195], v187 offset:3072
	ds_read_b128 v[202:205], v187 offset:4096
	ds_read_b128 v[206:209], v187 offset:5120
	ds_read_b128 v[210:213], v187 offset:6144
	ds_read_b128 v[214:217], v187 offset:7168
	global_load_lds_dwordx4 v[220:221], off
	v_lshl_add_u64 v[220:221], s[28:29], 0, v[172:173]
	s_add_i32 m0, s27, 0xe000
	s_nop 0
	global_load_lds_dwordx4 v[220:221], off
	s_waitcnt vmcnt(8)
	s_waitcnt lgkmcnt(0)
	s_barrier
	s_waitcnt lgkmcnt(0)
	v_mfma_i32_16x16x64_i8 v[126:129], v[158:161], v[174:177], v[126:129]
	s_nop 0
	v_mfma_i32_16x16x64_i8 v[126:129], v[154:157], v[178:181], v[126:129]
	v_mfma_i32_16x16x64_i8 v[122:125], v[150:153], v[174:177], v[122:125]
	s_nop 0
	v_mfma_i32_16x16x64_i8 v[122:125], v[146:149], v[178:181], v[122:125]
	v_mfma_i32_16x16x64_i8 v[110:113], v[158:161], v[188:191], v[110:113]
	s_nop 0
	v_mfma_i32_16x16x64_i8 v[110:113], v[154:157], v[192:195], v[110:113]
	v_mfma_i32_16x16x64_i8 v[106:109], v[150:153], v[188:191], v[106:109]
	s_nop 0
	v_mfma_i32_16x16x64_i8 v[106:109], v[146:149], v[192:195], v[106:109]
	v_mfma_i32_16x16x64_i8 v[94:97], v[158:161], v[202:205], v[94:97]
	s_nop 0
	v_mfma_i32_16x16x64_i8 v[94:97], v[154:157], v[206:209], v[94:97]
	v_mfma_i32_16x16x64_i8 v[90:93], v[150:153], v[202:205], v[90:93]
	s_nop 0
	v_mfma_i32_16x16x64_i8 v[90:93], v[146:149], v[206:209], v[90:93]
	v_mfma_i32_16x16x64_i8 v[78:81], v[158:161], v[210:213], v[78:81]
	s_nop 0
	v_mfma_i32_16x16x64_i8 v[78:81], v[154:157], v[214:217], v[78:81]
	v_mfma_i32_16x16x64_i8 v[74:77], v[150:153], v[210:213], v[74:77]
	s_nop 0
	v_mfma_i32_16x16x64_i8 v[74:77], v[146:149], v[214:217], v[74:77]
	v_mfma_i32_16x16x64_i8 v[118:121], v[142:145], v[174:177], v[118:121]
	s_nop 0
	v_mfma_i32_16x16x64_i8 v[118:121], v[138:141], v[178:181], v[118:121]
	v_mfma_i32_16x16x64_i8 v[114:117], v[134:137], v[174:177], v[114:117]
	s_nop 0
	v_mfma_i32_16x16x64_i8 v[114:117], v[130:133], v[178:181], v[114:117]
	v_mfma_i32_16x16x64_i8 v[102:105], v[142:145], v[188:191], v[102:105]
	s_nop 0
	v_mfma_i32_16x16x64_i8 v[102:105], v[138:141], v[192:195], v[102:105]
	v_mfma_i32_16x16x64_i8 v[98:101], v[134:137], v[188:191], v[98:101]
	s_nop 0
	v_mfma_i32_16x16x64_i8 v[98:101], v[130:133], v[192:195], v[98:101]
	v_mfma_i32_16x16x64_i8 v[86:89], v[142:145], v[202:205], v[86:89]
	s_nop 0
	v_mfma_i32_16x16x64_i8 v[86:89], v[138:141], v[206:209], v[86:89]
	v_mfma_i32_16x16x64_i8 v[82:85], v[134:137], v[202:205], v[82:85]
	s_nop 0
	v_mfma_i32_16x16x64_i8 v[82:85], v[130:133], v[206:209], v[82:85]
	v_mfma_i32_16x16x64_i8 v[70:73], v[142:145], v[210:213], v[70:73]
	s_nop 0
	v_mfma_i32_16x16x64_i8 v[70:73], v[138:141], v[214:217], v[70:73]
	v_mfma_i32_16x16x64_i8 v[66:69], v[134:137], v[210:213], v[66:69]
	s_nop 0
	v_mfma_i32_16x16x64_i8 v[66:69], v[130:133], v[214:217], v[66:69]
	s_barrier
	s_add_i32 s46, s17, s9
	v_lshl_add_u64 v[174:175], s[30:31], 0, v[166:167]
	s_mov_b32 m0, s46
	ds_read_b128 v[188:191], v187 offset:16384
	ds_read_b128 v[192:195], v187 offset:17408
	ds_read_b128 v[202:205], v187 offset:18432
	ds_read_b128 v[206:209], v187 offset:19456
	ds_read_b128 v[210:213], v187 offset:20480
	ds_read_b128 v[214:217], v187 offset:21504
	ds_read_b128 v[220:223], v187 offset:22528
	ds_read_b128 v[224:227], v187 offset:23552
	global_load_lds_dwordx4 v[174:175], off
	s_add_i32 m0, s46, 0x2000
	s_add_u32 s46, s30, 0x80000
	v_lshl_add_u64 v[176:177], s[30:31], 0, v[162:163]
	s_addc_u32 s47, s31, 0
	s_add_i32 s48, s55, s9
	global_load_lds_dwordx4 v[176:177], off
	v_lshl_add_u64 v[178:179], s[46:47], 0, v[166:167]
	s_mov_b32 m0, s48
	v_lshl_add_u64 v[180:181], s[34:35], 0, v[164:165]
	global_load_lds_dwordx4 v[178:179], off
	v_lshl_add_u64 v[178:179], s[46:47], 0, v[162:163]
	s_add_i32 m0, s48, 0x2000
	s_nop 0
	global_load_lds_dwordx4 v[178:179], off
	v_lshl_add_u64 v[178:179], s[34:35], 0, v[168:169]
	s_mov_b32 m0, s27
	s_nop 0
	global_load_lds_dwordx4 v[178:179], off
	s_mov_b32 m0, s33
	s_nop 0
	global_load_lds_dwordx4 v[180:181], off
	s_waitcnt vmcnt(8)
	s_waitcnt lgkmcnt(0)
	s_barrier
	s_waitcnt lgkmcnt(0)
	v_mfma_i32_16x16x64_i8 v[62:65], v[158:161], v[188:191], v[62:65]
	s_nop 0
	v_mfma_i32_16x16x64_i8 v[62:65], v[154:157], v[192:195], v[62:65]
	v_mfma_i32_16x16x64_i8 v[58:61], v[150:153], v[188:191], v[58:61]
	s_nop 0
	v_mfma_i32_16x16x64_i8 v[58:61], v[146:149], v[192:195], v[58:61]
	v_mfma_i32_16x16x64_i8 v[46:49], v[158:161], v[202:205], v[46:49]
	s_nop 0
	v_mfma_i32_16x16x64_i8 v[46:49], v[154:157], v[206:209], v[46:49]
	v_mfma_i32_16x16x64_i8 v[42:45], v[150:153], v[202:205], v[42:45]
	s_nop 0
	v_mfma_i32_16x16x64_i8 v[42:45], v[146:149], v[206:209], v[42:45]
	v_mfma_i32_16x16x64_i8 v[30:33], v[158:161], v[210:213], v[30:33]
	s_nop 0
	v_mfma_i32_16x16x64_i8 v[30:33], v[154:157], v[214:217], v[30:33]
	v_mfma_i32_16x16x64_i8 v[26:29], v[150:153], v[210:213], v[26:29]
	s_nop 0
	v_mfma_i32_16x16x64_i8 v[26:29], v[146:149], v[214:217], v[26:29]
	v_mfma_i32_16x16x64_i8 v[14:17], v[158:161], v[220:223], v[14:17]
	s_nop 0
	v_mfma_i32_16x16x64_i8 v[14:17], v[154:157], v[224:227], v[14:17]
	v_mfma_i32_16x16x64_i8 v[10:13], v[150:153], v[220:223], v[10:13]
	s_nop 0
	v_mfma_i32_16x16x64_i8 v[10:13], v[146:149], v[224:227], v[10:13]
	v_mfma_i32_16x16x64_i8 v[54:57], v[142:145], v[188:191], v[54:57]
	s_nop 0
	v_mfma_i32_16x16x64_i8 v[54:57], v[138:141], v[192:195], v[54:57]
	v_mfma_i32_16x16x64_i8 v[50:53], v[134:137], v[188:191], v[50:53]
	s_nop 0
	v_mfma_i32_16x16x64_i8 v[50:53], v[130:133], v[192:195], v[50:53]
	v_mfma_i32_16x16x64_i8 v[38:41], v[142:145], v[202:205], v[38:41]
	s_nop 0
	v_mfma_i32_16x16x64_i8 v[38:41], v[138:141], v[206:209], v[38:41]
	v_mfma_i32_16x16x64_i8 v[34:37], v[134:137], v[202:205], v[34:37]
	s_nop 0
	v_mfma_i32_16x16x64_i8 v[34:37], v[130:133], v[206:209], v[34:37]
	v_mfma_i32_16x16x64_i8 v[22:25], v[142:145], v[210:213], v[22:25]
	s_nop 0
	v_mfma_i32_16x16x64_i8 v[22:25], v[138:141], v[214:217], v[22:25]
	v_mfma_i32_16x16x64_i8 v[18:21], v[134:137], v[210:213], v[18:21]
	s_nop 0
	v_mfma_i32_16x16x64_i8 v[18:21], v[130:133], v[214:217], v[18:21]
	v_mfma_i32_16x16x64_i8 v[6:9], v[142:145], v[220:223], v[6:9]
	s_nop 0
	v_mfma_i32_16x16x64_i8 v[6:9], v[138:141], v[224:227], v[6:9]
	v_mfma_i32_16x16x64_i8 v[2:5], v[134:137], v[220:223], v[2:5]
	s_nop 0
	v_mfma_i32_16x16x64_i8 v[2:5], v[130:133], v[224:227], v[2:5]
	s_barrier
	v_add_u32_e32 v142, s56, v183
	v_add_u32_e32 v158, s57, v183
	ds_read_b128 v[130:133], v142
	ds_read_b128 v[134:137], v142 offset:1024
	ds_read_b128 v[138:141], v142 offset:2048
	ds_read_b128 v[142:145], v142 offset:3072
	ds_read_b128 v[146:149], v158
	ds_read_b128 v[150:153], v158 offset:1024
	ds_read_b128 v[154:157], v158 offset:2048
	ds_read_b128 v[158:161], v158 offset:3072
	s_add_u32 s34, s34, 0x80000
	s_addc_u32 s35, s35, 0
	s_mov_b32 m0, s36
	v_lshl_add_u64 v[232:233], s[34:35], 0, v[168:169]
	ds_read_b128 v[188:191], v187 offset:32768
	ds_read_b128 v[192:195], v187 offset:33792
	ds_read_b128 v[202:205], v187 offset:34816
	ds_read_b128 v[206:209], v187 offset:35840
	ds_read_b128 v[210:213], v187 offset:36864
	ds_read_b128 v[214:217], v187 offset:37888
	ds_read_b128 v[220:223], v187 offset:38912
	ds_read_b128 v[224:227], v187 offset:39936
	global_load_lds_dwordx4 v[232:233], off
	v_lshl_add_u64 v[232:233], s[34:35], 0, v[164:165]
	s_mov_b32 m0, s37
	s_nop 0
	global_load_lds_dwordx4 v[232:233], off
	s_waitcnt vmcnt(8)
	s_waitcnt lgkmcnt(0)
	s_barrier
	s_waitcnt lgkmcnt(0)
	v_mfma_i32_16x16x64_i8 v[126:129], v[130:133], v[188:191], v[126:129]
	s_nop 0
	v_mfma_i32_16x16x64_i8 v[126:129], v[134:137], v[192:195], v[126:129]
	v_mfma_i32_16x16x64_i8 v[122:125], v[138:141], v[188:191], v[122:125]
	s_nop 0
	v_mfma_i32_16x16x64_i8 v[122:125], v[142:145], v[192:195], v[122:125]
	v_mfma_i32_16x16x64_i8 v[110:113], v[130:133], v[202:205], v[110:113]
	s_nop 0
	v_mfma_i32_16x16x64_i8 v[110:113], v[134:137], v[206:209], v[110:113]
	v_mfma_i32_16x16x64_i8 v[106:109], v[138:141], v[202:205], v[106:109]
	s_nop 0
	v_mfma_i32_16x16x64_i8 v[106:109], v[142:145], v[206:209], v[106:109]
	v_mfma_i32_16x16x64_i8 v[94:97], v[130:133], v[210:213], v[94:97]
	s_nop 0
	v_mfma_i32_16x16x64_i8 v[94:97], v[134:137], v[214:217], v[94:97]
	v_mfma_i32_16x16x64_i8 v[90:93], v[138:141], v[210:213], v[90:93]
	s_nop 0
	v_mfma_i32_16x16x64_i8 v[90:93], v[142:145], v[214:217], v[90:93]
	v_mfma_i32_16x16x64_i8 v[78:81], v[130:133], v[220:223], v[78:81]
	s_nop 0
	v_mfma_i32_16x16x64_i8 v[78:81], v[134:137], v[224:227], v[78:81]
	v_mfma_i32_16x16x64_i8 v[74:77], v[138:141], v[220:223], v[74:77]
	s_nop 0
	v_mfma_i32_16x16x64_i8 v[74:77], v[142:145], v[224:227], v[74:77]
	v_mfma_i32_16x16x64_i8 v[118:121], v[146:149], v[188:191], v[118:121]
	s_nop 0
	v_mfma_i32_16x16x64_i8 v[118:121], v[150:153], v[192:195], v[118:121]
	v_mfma_i32_16x16x64_i8 v[114:117], v[154:157], v[188:191], v[114:117]
	s_nop 0
	v_mfma_i32_16x16x64_i8 v[114:117], v[158:161], v[192:195], v[114:117]
	v_mfma_i32_16x16x64_i8 v[102:105], v[146:149], v[202:205], v[102:105]
	s_nop 0
	v_mfma_i32_16x16x64_i8 v[102:105], v[150:153], v[206:209], v[102:105]
	v_mfma_i32_16x16x64_i8 v[98:101], v[154:157], v[202:205], v[98:101]
	s_nop 0
	v_mfma_i32_16x16x64_i8 v[98:101], v[158:161], v[206:209], v[98:101]
	v_mfma_i32_16x16x64_i8 v[86:89], v[146:149], v[210:213], v[86:89]
	s_nop 0
	v_mfma_i32_16x16x64_i8 v[86:89], v[150:153], v[214:217], v[86:89]
	v_mfma_i32_16x16x64_i8 v[82:85], v[154:157], v[210:213], v[82:85]
	s_nop 0
	v_mfma_i32_16x16x64_i8 v[82:85], v[158:161], v[214:217], v[82:85]
	v_mfma_i32_16x16x64_i8 v[70:73], v[146:149], v[220:223], v[70:73]
	s_nop 0
	v_mfma_i32_16x16x64_i8 v[70:73], v[150:153], v[224:227], v[70:73]
	v_mfma_i32_16x16x64_i8 v[66:69], v[154:157], v[220:223], v[66:69]
	s_nop 0
	v_mfma_i32_16x16x64_i8 v[66:69], v[158:161], v[224:227], v[66:69]
	s_barrier
	s_add_i32 s34, s56, s9
	v_lshl_add_u64 v[174:175], v[174:175], 0, s[4:5]
	s_mov_b32 m0, s34
	ds_read_b128 v[188:191], v187 offset:49152
	ds_read_b128 v[192:195], v187 offset:50176
	ds_read_b128 v[202:205], v187 offset:51200
	ds_read_b128 v[206:209], v187 offset:52224
	ds_read_b128 v[210:213], v187 offset:53248
	ds_read_b128 v[214:217], v187 offset:54272
	ds_read_b128 v[220:223], v187 offset:55296
	ds_read_b128 v[224:227], v187 offset:56320
	global_load_lds_dwordx4 v[174:175], off
	s_add_i32 m0, s34, 0x2000
	s_add_u32 s30, s30, 0x80080
	v_lshl_add_u64 v[174:175], v[176:177], 0, s[4:5]
	s_addc_u32 s31, s31, 0
	s_add_i32 s34, s57, s9
	global_load_lds_dwordx4 v[174:175], off
	v_lshl_add_u64 v[174:175], s[30:31], 0, v[166:167]
	s_mov_b32 m0, s34
	s_nop 0
	global_load_lds_dwordx4 v[174:175], off
	v_lshl_add_u64 v[174:175], s[30:31], 0, v[162:163]
	s_add_i32 m0, s34, 0x2000
	s_nop 0
	global_load_lds_dwordx4 v[174:175], off
	v_lshl_add_u64 v[174:175], v[178:179], 0, s[4:5]
	s_mov_b32 m0, s39
	s_nop 0
	global_load_lds_dwordx4 v[174:175], off
	v_lshl_add_u64 v[174:175], v[180:181], 0, s[4:5]
	s_mov_b32 m0, s40
	s_nop 0
	global_load_lds_dwordx4 v[174:175], off
	s_waitcnt vmcnt(8)
	s_waitcnt lgkmcnt(0)
	s_barrier
	s_waitcnt lgkmcnt(0)
	v_mfma_i32_16x16x64_i8 v[62:65], v[130:133], v[188:191], v[62:65]
	s_nop 0
	v_mfma_i32_16x16x64_i8 v[62:65], v[134:137], v[192:195], v[62:65]
	v_mfma_i32_16x16x64_i8 v[58:61], v[138:141], v[188:191], v[58:61]
	s_nop 0
	v_mfma_i32_16x16x64_i8 v[58:61], v[142:145], v[192:195], v[58:61]
	v_mfma_i32_16x16x64_i8 v[46:49], v[130:133], v[202:205], v[46:49]
	s_nop 0
	v_mfma_i32_16x16x64_i8 v[46:49], v[134:137], v[206:209], v[46:49]
	v_mfma_i32_16x16x64_i8 v[42:45], v[138:141], v[202:205], v[42:45]
	s_nop 0
	v_mfma_i32_16x16x64_i8 v[42:45], v[142:145], v[206:209], v[42:45]
	v_mfma_i32_16x16x64_i8 v[30:33], v[130:133], v[210:213], v[30:33]
	s_nop 0
	v_mfma_i32_16x16x64_i8 v[30:33], v[134:137], v[214:217], v[30:33]
	v_mfma_i32_16x16x64_i8 v[26:29], v[138:141], v[210:213], v[26:29]
	s_nop 0
	v_mfma_i32_16x16x64_i8 v[26:29], v[142:145], v[214:217], v[26:29]
	v_mfma_i32_16x16x64_i8 v[14:17], v[130:133], v[220:223], v[14:17]
	s_nop 0
	v_mfma_i32_16x16x64_i8 v[14:17], v[134:137], v[224:227], v[14:17]
	v_mfma_i32_16x16x64_i8 v[10:13], v[138:141], v[220:223], v[10:13]
	s_nop 0
	v_mfma_i32_16x16x64_i8 v[10:13], v[142:145], v[224:227], v[10:13]
	v_mfma_i32_16x16x64_i8 v[54:57], v[146:149], v[188:191], v[54:57]
	s_nop 0
	v_mfma_i32_16x16x64_i8 v[54:57], v[150:153], v[192:195], v[54:57]
	v_mfma_i32_16x16x64_i8 v[50:53], v[154:157], v[188:191], v[50:53]
	s_nop 0
	v_mfma_i32_16x16x64_i8 v[50:53], v[158:161], v[192:195], v[50:53]
	v_mfma_i32_16x16x64_i8 v[38:41], v[146:149], v[202:205], v[38:41]
	s_nop 0
	v_mfma_i32_16x16x64_i8 v[38:41], v[150:153], v[206:209], v[38:41]
	v_mfma_i32_16x16x64_i8 v[34:37], v[154:157], v[202:205], v[34:37]
	s_nop 0
	v_mfma_i32_16x16x64_i8 v[34:37], v[158:161], v[206:209], v[34:37]
	v_mfma_i32_16x16x64_i8 v[22:25], v[146:149], v[210:213], v[22:25]
	s_nop 0
	v_mfma_i32_16x16x64_i8 v[22:25], v[150:153], v[214:217], v[22:25]
	v_mfma_i32_16x16x64_i8 v[18:21], v[154:157], v[210:213], v[18:21]
	s_nop 0
	v_mfma_i32_16x16x64_i8 v[18:21], v[158:161], v[214:217], v[18:21]
	v_mfma_i32_16x16x64_i8 v[6:9], v[146:149], v[220:223], v[6:9]
	s_nop 0
	v_mfma_i32_16x16x64_i8 v[6:9], v[150:153], v[224:227], v[6:9]
	v_mfma_i32_16x16x64_i8 v[2:5], v[154:157], v[220:223], v[2:5]
	s_nop 0
	v_mfma_i32_16x16x64_i8 v[2:5], v[158:161], v[224:227], v[2:5]
	s_barrier
	s_add_i32 s45, s45, 2
	s_add_u32 s28, s28, 0x100
	s_addc_u32 s29, s29, 0
	s_add_u32 s43, s43, 0x100
	s_addc_u32 s44, s44, 0
	s_cmp_gt_u32 s45, 29
	s_cbranch_scc0 .LBB0_961
	s_nop 15
	s_nop 15
	s_and_b64 vcc, exec, s[6:7]
	s_cbranch_vccz .LBB0_964
	s_barrier

.LBB0_1058:
	ds_read_b128 v[128:131], v194
	ds_read_b128 v[132:135], v194 offset:1024
	ds_read_b128 v[136:139], v194 offset:2048
	ds_read_b128 v[140:143], v194 offset:3072
	ds_read_b128 v[144:147], v195
	ds_read_b128 v[148:151], v195 offset:1024
	ds_read_b128 v[152:155], v195 offset:2048
	ds_read_b128 v[156:159], v195 offset:3072
	s_add_u32 s2, s0, 0x100
	s_addc_u32 s3, s1, 0
	s_cmpk_eq_i32 s39, 0xa8
	s_cselect_b32 s37, s31, s3
	s_cselect_b32 s36, s30, s2
	s_cselect_b32 s5, s7, s38
	s_cselect_b32 s4, s6, s29
	v_lshl_add_u64 v[188:189], s[0:1], 0, v[168:169]
	s_add_i32 m0, s27, 0xc000
	ds_read_b128 v[172:175], v196
	ds_read_b128 v[176:179], v196 offset:1024
	ds_read_b128 v[180:183], v196 offset:2048
	ds_read_b128 v[184:187], v196 offset:3072
	ds_read_b128 v[200:203], v196 offset:4096
	ds_read_b128 v[204:207], v196 offset:5120
	ds_read_b128 v[208:211], v196 offset:6144
	ds_read_b128 v[212:215], v196 offset:7168
	global_load_lds_dwordx4 v[188:189], off
	v_lshl_add_u64 v[188:189], s[0:1], 0, v[170:171]
	s_add_i32 m0, s27, 0xe000
	s_nop 0
	global_load_lds_dwordx4 v[188:189], off
	s_waitcnt vmcnt(8)
	s_waitcnt lgkmcnt(0)
	s_barrier
	s_waitcnt lgkmcnt(0)
	v_mfma_f32_16x16x32_bf16 v[12:15], v[128:131], v[172:175], v[12:15]
	v_mfma_f32_16x16x32_bf16 v[8:11], v[136:139], v[172:175], v[8:11]
	v_mfma_f32_16x16x32_bf16 v[36:39], v[128:131], v[180:183], v[36:39]
	v_mfma_f32_16x16x32_bf16 v[32:35], v[136:139], v[180:183], v[32:35]
	v_mfma_f32_16x16x32_bf16 v[44:47], v[128:131], v[200:203], v[44:47]
	v_mfma_f32_16x16x32_bf16 v[40:43], v[136:139], v[200:203], v[40:43]
	v_mfma_f32_16x16x32_bf16 v[64:67], v[128:131], v[208:211], v[64:67]
	v_mfma_f32_16x16x32_bf16 v[56:59], v[136:139], v[208:211], v[56:59]
	v_mfma_f32_16x16x32_bf16 v[12:15], v[132:135], v[176:179], v[12:15]
	v_mfma_f32_16x16x32_bf16 v[8:11], v[140:143], v[176:179], v[8:11]
	v_mfma_f32_16x16x32_bf16 v[36:39], v[132:135], v[184:187], v[36:39]
	v_mfma_f32_16x16x32_bf16 v[32:35], v[140:143], v[184:187], v[32:35]
	v_mfma_f32_16x16x32_bf16 v[44:47], v[132:135], v[204:207], v[44:47]
	v_mfma_f32_16x16x32_bf16 v[40:43], v[140:143], v[204:207], v[40:43]
	v_mfma_f32_16x16x32_bf16 v[64:67], v[132:135], v[212:215], v[64:67]
	v_mfma_f32_16x16x32_bf16 v[56:59], v[140:143], v[212:215], v[56:59]
	v_mfma_f32_16x16x32_bf16 v[4:7], v[144:147], v[172:175], v[4:7]
	v_mfma_f32_16x16x32_bf16 v[0:3], v[152:155], v[172:175], v[0:3]
	v_mfma_f32_16x16x32_bf16 v[24:27], v[144:147], v[180:183], v[24:27]
	v_mfma_f32_16x16x32_bf16 v[16:19], v[152:155], v[180:183], v[16:19]
	v_mfma_f32_16x16x32_bf16 v[28:31], v[144:147], v[200:203], v[28:31]
	v_mfma_f32_16x16x32_bf16 v[20:23], v[152:155], v[200:203], v[20:23]
	v_mfma_f32_16x16x32_bf16 v[52:55], v[144:147], v[208:211], v[52:55]
	v_mfma_f32_16x16x32_bf16 v[48:51], v[152:155], v[208:211], v[48:51]
	v_mfma_f32_16x16x32_bf16 v[4:7], v[148:151], v[176:179], v[4:7]
	v_mfma_f32_16x16x32_bf16 v[0:3], v[156:159], v[176:179], v[0:3]
	v_mfma_f32_16x16x32_bf16 v[24:27], v[148:151], v[184:187], v[24:27]
	v_mfma_f32_16x16x32_bf16 v[16:19], v[156:159], v[184:187], v[16:19]
	v_mfma_f32_16x16x32_bf16 v[28:31], v[148:151], v[204:207], v[28:31]
	v_mfma_f32_16x16x32_bf16 v[20:23], v[156:159], v[204:207], v[20:23]
	v_mfma_f32_16x16x32_bf16 v[52:55], v[148:151], v[212:215], v[52:55]
	v_mfma_f32_16x16x32_bf16 v[48:51], v[156:159], v[212:215], v[48:51]
	s_barrier
	s_add_i32 s0, s17, s25
	v_lshl_add_u64 v[188:189], s[4:5], 0, v[162:163]
	s_mov_b32 m0, s0
	ds_read_b128 v[172:175], v196 offset:16384
	ds_read_b128 v[176:179], v196 offset:17408
	ds_read_b128 v[180:183], v196 offset:18432
	ds_read_b128 v[184:187], v196 offset:19456
	ds_read_b128 v[200:203], v196 offset:20480
	ds_read_b128 v[204:207], v196 offset:21504
	ds_read_b128 v[208:211], v196 offset:22528
	ds_read_b128 v[212:215], v196 offset:23552
	global_load_lds_dwordx4 v[188:189], off
	s_add_i32 m0, s0, 0x2000
	s_add_u32 s0, s4, 0x2b0000
	v_lshl_add_u64 v[216:217], s[4:5], 0, v[166:167]
	s_addc_u32 s1, s5, 0
	s_add_i32 s40, s55, s25
	global_load_lds_dwordx4 v[216:217], off
	v_lshl_add_u64 v[220:221], s[0:1], 0, v[162:163]
	s_mov_b32 m0, s40
	v_lshl_add_u64 v[222:223], s[36:37], 0, v[164:165]
	global_load_lds_dwordx4 v[220:221], off
	v_lshl_add_u64 v[220:221], s[0:1], 0, v[166:167]
	s_add_i32 m0, s40, 0x2000
	s_nop 0
	global_load_lds_dwordx4 v[220:221], off
	v_lshl_add_u64 v[220:221], s[36:37], 0, v[160:161]
	s_mov_b32 m0, s27
	s_nop 0
	global_load_lds_dwordx4 v[220:221], off
	s_mov_b32 m0, s33
	s_nop 0
	global_load_lds_dwordx4 v[222:223], off
	s_waitcnt vmcnt(8)
	s_waitcnt lgkmcnt(0)
	s_barrier
	s_waitcnt lgkmcnt(0)
	v_mfma_f32_16x16x32_bf16 v[76:79], v[128:131], v[172:175], v[76:79]
	v_mfma_f32_16x16x32_bf16 v[72:75], v[136:139], v[172:175], v[72:75]
	v_mfma_f32_16x16x32_bf16 v[92:95], v[128:131], v[180:183], v[92:95]
	v_mfma_f32_16x16x32_bf16 v[88:91], v[136:139], v[180:183], v[88:91]
	v_mfma_f32_16x16x32_bf16 v[108:111], v[128:131], v[200:203], v[108:111]
	v_mfma_f32_16x16x32_bf16 v[104:107], v[136:139], v[200:203], v[104:107]
	v_mfma_f32_16x16x32_bf16 v[124:127], v[128:131], v[208:211], v[124:127]
	v_mfma_f32_16x16x32_bf16 v[120:123], v[136:139], v[208:211], v[120:123]
	v_mfma_f32_16x16x32_bf16 v[76:79], v[132:135], v[176:179], v[76:79]
	v_mfma_f32_16x16x32_bf16 v[72:75], v[140:143], v[176:179], v[72:75]
	v_mfma_f32_16x16x32_bf16 v[92:95], v[132:135], v[184:187], v[92:95]
	v_mfma_f32_16x16x32_bf16 v[88:91], v[140:143], v[184:187], v[88:91]
	v_mfma_f32_16x16x32_bf16 v[108:111], v[132:135], v[204:207], v[108:111]
	v_mfma_f32_16x16x32_bf16 v[104:107], v[140:143], v[204:207], v[104:107]
	v_mfma_f32_16x16x32_bf16 v[124:127], v[132:135], v[212:215], v[124:127]
	v_mfma_f32_16x16x32_bf16 v[120:123], v[140:143], v[212:215], v[120:123]
	v_mfma_f32_16x16x32_bf16 v[68:71], v[144:147], v[172:175], v[68:71]
	v_mfma_f32_16x16x32_bf16 v[60:63], v[152:155], v[172:175], v[60:63]
	v_mfma_f32_16x16x32_bf16 v[84:87], v[144:147], v[180:183], v[84:87]
	v_mfma_f32_16x16x32_bf16 v[80:83], v[152:155], v[180:183], v[80:83]
	v_mfma_f32_16x16x32_bf16 v[100:103], v[144:147], v[200:203], v[100:103]
	v_mfma_f32_16x16x32_bf16 v[96:99], v[152:155], v[200:203], v[96:99]
	v_mfma_f32_16x16x32_bf16 v[116:119], v[144:147], v[208:211], v[116:119]
	v_mfma_f32_16x16x32_bf16 v[112:115], v[152:155], v[208:211], v[112:115]
	v_mfma_f32_16x16x32_bf16 v[68:71], v[148:151], v[176:179], v[68:71]
	v_mfma_f32_16x16x32_bf16 v[60:63], v[156:159], v[176:179], v[60:63]
	v_mfma_f32_16x16x32_bf16 v[84:87], v[148:151], v[184:187], v[84:87]
	v_mfma_f32_16x16x32_bf16 v[80:83], v[156:159], v[184:187], v[80:83]
	v_mfma_f32_16x16x32_bf16 v[100:103], v[148:151], v[204:207], v[100:103]
	v_mfma_f32_16x16x32_bf16 v[96:99], v[156:159], v[204:207], v[96:99]
	v_mfma_f32_16x16x32_bf16 v[116:119], v[148:151], v[212:215], v[116:119]
	v_mfma_f32_16x16x32_bf16 v[112:115], v[156:159], v[212:215], v[112:115]
	s_barrier
	v_add_u32_e32 v140, s56, v193
	v_add_u32_e32 v156, s57, v193
	ds_read_b128 v[128:131], v140
	ds_read_b128 v[132:135], v140 offset:1024
	ds_read_b128 v[136:139], v140 offset:2048
	ds_read_b128 v[140:143], v140 offset:3072
	ds_read_b128 v[144:147], v156
	ds_read_b128 v[148:151], v156 offset:1024
	ds_read_b128 v[152:155], v156 offset:2048
	ds_read_b128 v[156:159], v156 offset:3072
	s_add_u32 s0, s36, 0x2b0000
	s_addc_u32 s1, s37, 0
	s_mov_b32 m0, s46
	v_lshl_add_u64 v[224:225], s[0:1], 0, v[160:161]
	ds_read_b128 v[172:175], v196 offset:32768
	ds_read_b128 v[176:179], v196 offset:33792
	ds_read_b128 v[180:183], v196 offset:34816
	ds_read_b128 v[184:187], v196 offset:35840
	ds_read_b128 v[200:203], v196 offset:36864
	ds_read_b128 v[204:207], v196 offset:37888
	ds_read_b128 v[208:211], v196 offset:38912
	ds_read_b128 v[212:215], v196 offset:39936
	global_load_lds_dwordx4 v[224:225], off
	v_lshl_add_u64 v[224:225], s[0:1], 0, v[164:165]
	s_mov_b32 m0, s47
	s_nop 0
	global_load_lds_dwordx4 v[224:225], off
	s_waitcnt vmcnt(8)
	s_waitcnt lgkmcnt(0)
	s_barrier
	s_waitcnt lgkmcnt(0)
	v_mfma_f32_16x16x32_bf16 v[12:15], v[128:131], v[172:175], v[12:15]
	v_mfma_f32_16x16x32_bf16 v[8:11], v[136:139], v[172:175], v[8:11]
	v_mfma_f32_16x16x32_bf16 v[36:39], v[128:131], v[180:183], v[36:39]
	v_mfma_f32_16x16x32_bf16 v[32:35], v[136:139], v[180:183], v[32:35]
	v_mfma_f32_16x16x32_bf16 v[44:47], v[128:131], v[200:203], v[44:47]
	v_mfma_f32_16x16x32_bf16 v[40:43], v[136:139], v[200:203], v[40:43]
	v_mfma_f32_16x16x32_bf16 v[64:67], v[128:131], v[208:211], v[64:67]
	v_mfma_f32_16x16x32_bf16 v[56:59], v[136:139], v[208:211], v[56:59]
	v_mfma_f32_16x16x32_bf16 v[12:15], v[132:135], v[176:179], v[12:15]
	v_mfma_f32_16x16x32_bf16 v[8:11], v[140:143], v[176:179], v[8:11]
	v_mfma_f32_16x16x32_bf16 v[36:39], v[132:135], v[184:187], v[36:39]
	v_mfma_f32_16x16x32_bf16 v[32:35], v[140:143], v[184:187], v[32:35]
	v_mfma_f32_16x16x32_bf16 v[44:47], v[132:135], v[204:207], v[44:47]
	v_mfma_f32_16x16x32_bf16 v[40:43], v[140:143], v[204:207], v[40:43]
	v_mfma_f32_16x16x32_bf16 v[64:67], v[132:135], v[212:215], v[64:67]
	v_mfma_f32_16x16x32_bf16 v[56:59], v[140:143], v[212:215], v[56:59]
	v_mfma_f32_16x16x32_bf16 v[4:7], v[144:147], v[172:175], v[4:7]
	v_mfma_f32_16x16x32_bf16 v[0:3], v[152:155], v[172:175], v[0:3]
	v_mfma_f32_16x16x32_bf16 v[24:27], v[144:147], v[180:183], v[24:27]
	v_mfma_f32_16x16x32_bf16 v[16:19], v[152:155], v[180:183], v[16:19]
	v_mfma_f32_16x16x32_bf16 v[28:31], v[144:147], v[200:203], v[28:31]
	v_mfma_f32_16x16x32_bf16 v[20:23], v[152:155], v[200:203], v[20:23]
	v_mfma_f32_16x16x32_bf16 v[52:55], v[144:147], v[208:211], v[52:55]
	v_mfma_f32_16x16x32_bf16 v[48:51], v[152:155], v[208:211], v[48:51]
	v_mfma_f32_16x16x32_bf16 v[4:7], v[148:151], v[176:179], v[4:7]
	v_mfma_f32_16x16x32_bf16 v[0:3], v[156:159], v[176:179], v[0:3]
	v_mfma_f32_16x16x32_bf16 v[24:27], v[148:151], v[184:187], v[24:27]
	v_mfma_f32_16x16x32_bf16 v[16:19], v[156:159], v[184:187], v[16:19]
	v_mfma_f32_16x16x32_bf16 v[28:31], v[148:151], v[204:207], v[28:31]
	v_mfma_f32_16x16x32_bf16 v[20:23], v[156:159], v[204:207], v[20:23]
	v_mfma_f32_16x16x32_bf16 v[52:55], v[148:151], v[212:215], v[52:55]
	v_mfma_f32_16x16x32_bf16 v[48:51], v[156:159], v[212:215], v[48:51]
	s_barrier
	s_add_i32 s0, s56, s25
	v_lshl_add_u64 v[188:189], v[188:189], 0, s[18:19]
	s_mov_b32 m0, s0
	ds_read_b128 v[172:175], v196 offset:49152
	ds_read_b128 v[176:179], v196 offset:50176
	ds_read_b128 v[180:183], v196 offset:51200
	ds_read_b128 v[184:187], v196 offset:52224
	ds_read_b128 v[200:203], v196 offset:53248
	ds_read_b128 v[204:207], v196 offset:54272
	ds_read_b128 v[208:211], v196 offset:55296
	ds_read_b128 v[212:215], v196 offset:56320
	global_load_lds_dwordx4 v[188:189], off
	s_add_i32 m0, s0, 0x2000
	s_add_u32 s0, s4, 0x2b0080
	v_lshl_add_u64 v[188:189], v[216:217], 0, s[18:19]
	s_addc_u32 s1, s5, 0
	s_add_i32 s4, s57, s25
	global_load_lds_dwordx4 v[188:189], off
	v_lshl_add_u64 v[188:189], s[0:1], 0, v[162:163]
	s_mov_b32 m0, s4
	s_nop 0
	global_load_lds_dwordx4 v[188:189], off
	v_lshl_add_u64 v[188:189], s[0:1], 0, v[166:167]
	s_add_i32 m0, s4, 0x2000
	s_nop 0
	global_load_lds_dwordx4 v[188:189], off
	v_lshl_add_u64 v[188:189], v[220:221], 0, s[18:19]
	s_mov_b32 m0, s52
	s_nop 0
	global_load_lds_dwordx4 v[188:189], off
	v_lshl_add_u64 v[188:189], v[222:223], 0, s[18:19]
	s_mov_b32 m0, s53
	s_nop 0
	global_load_lds_dwordx4 v[188:189], off
	s_waitcnt vmcnt(8)
	s_waitcnt lgkmcnt(0)
	s_barrier
	s_waitcnt lgkmcnt(0)
	v_mfma_f32_16x16x32_bf16 v[76:79], v[128:131], v[172:175], v[76:79]
	v_mfma_f32_16x16x32_bf16 v[72:75], v[136:139], v[172:175], v[72:75]
	v_mfma_f32_16x16x32_bf16 v[92:95], v[128:131], v[180:183], v[92:95]
	v_mfma_f32_16x16x32_bf16 v[88:91], v[136:139], v[180:183], v[88:91]
	v_mfma_f32_16x16x32_bf16 v[108:111], v[128:131], v[200:203], v[108:111]
	v_mfma_f32_16x16x32_bf16 v[104:107], v[136:139], v[200:203], v[104:107]
	v_mfma_f32_16x16x32_bf16 v[124:127], v[128:131], v[208:211], v[124:127]
	v_mfma_f32_16x16x32_bf16 v[120:123], v[136:139], v[208:211], v[120:123]
	v_mfma_f32_16x16x32_bf16 v[76:79], v[132:135], v[176:179], v[76:79]
	v_mfma_f32_16x16x32_bf16 v[72:75], v[140:143], v[176:179], v[72:75]
	v_mfma_f32_16x16x32_bf16 v[92:95], v[132:135], v[184:187], v[92:95]
	v_mfma_f32_16x16x32_bf16 v[88:91], v[140:143], v[184:187], v[88:91]
	v_mfma_f32_16x16x32_bf16 v[108:111], v[132:135], v[204:207], v[108:111]
	v_mfma_f32_16x16x32_bf16 v[104:107], v[140:143], v[204:207], v[104:107]
	v_mfma_f32_16x16x32_bf16 v[124:127], v[132:135], v[212:215], v[124:127]
	v_mfma_f32_16x16x32_bf16 v[120:123], v[140:143], v[212:215], v[120:123]
	v_mfma_f32_16x16x32_bf16 v[68:71], v[144:147], v[172:175], v[68:71]
	v_mfma_f32_16x16x32_bf16 v[60:63], v[152:155], v[172:175], v[60:63]
	v_mfma_f32_16x16x32_bf16 v[84:87], v[144:147], v[180:183], v[84:87]
	v_mfma_f32_16x16x32_bf16 v[80:83], v[152:155], v[180:183], v[80:83]
	v_mfma_f32_16x16x32_bf16 v[100:103], v[144:147], v[200:203], v[100:103]
	v_mfma_f32_16x16x32_bf16 v[96:99], v[152:155], v[200:203], v[96:99]
	v_mfma_f32_16x16x32_bf16 v[116:119], v[144:147], v[208:211], v[116:119]
	v_mfma_f32_16x16x32_bf16 v[112:115], v[152:155], v[208:211], v[112:115]
	v_mfma_f32_16x16x32_bf16 v[68:71], v[148:151], v[176:179], v[68:71]
	v_mfma_f32_16x16x32_bf16 v[60:63], v[156:159], v[176:179], v[60:63]
	v_mfma_f32_16x16x32_bf16 v[84:87], v[148:151], v[184:187], v[84:87]
	v_mfma_f32_16x16x32_bf16 v[80:83], v[156:159], v[184:187], v[80:83]
	v_mfma_f32_16x16x32_bf16 v[100:103], v[148:151], v[204:207], v[100:103]
	v_mfma_f32_16x16x32_bf16 v[96:99], v[156:159], v[204:207], v[96:99]
	v_mfma_f32_16x16x32_bf16 v[116:119], v[148:151], v[212:215], v[116:119]
	v_mfma_f32_16x16x32_bf16 v[112:115], v[156:159], v[212:215], v[112:115]
	s_barrier
	s_add_i32 s39, s39, 2
	s_add_u32 s29, s29, 0x100
	s_addc_u32 s38, s38, 0
	s_cmpk_gt_u32 s39, 0xa9
	s_mov_b64 s[0:1], s[2:3]
	s_cbranch_scc0 .LBB0_1058
	s_and_b64 vcc, exec, s[20:21]
	s_cbranch_vccz .LBB0_1061
	s_barrier
